# sc1 write-through on gate/up epilogue stores and on the fp16 residual-stream stores of the norm passes
# baseline (speedup 1.0000x reference)
.LBB0_309:
	v_lshlrev_b32_e32 v134, 16, v126
	v_and_b32_e32 v135, 0xffff0000, v126
	v_lshlrev_b32_e32 v126, 16, v127
	v_and_b32_e32 v127, 0xffff0000, v127
	v_pk_mul_f32 v[136:137], v[126:127], v[126:127]
	v_lshlrev_b32_e32 v138, 16, v128
	v_pk_fma_f32 v[136:137], v[134:135], v[134:135], v[136:137]
	v_and_b32_e32 v139, 0xffff0000, v128
	v_pk_fma_f32 v[136:137], v[138:139], v[138:139], v[136:137]
	v_lshlrev_b32_e32 v128, 16, v129
	v_and_b32_e32 v129, 0xffff0000, v129
	v_pk_fma_f32 v[136:137], v[128:129], v[128:129], v[136:137]
	v_lshlrev_b32_e32 v140, 16, v122
	v_and_b32_e32 v141, 0xffff0000, v122
	v_pk_fma_f32 v[136:137], v[140:141], v[140:141], v[136:137]
	v_lshlrev_b32_e32 v122, 16, v123
	v_and_b32_e32 v123, 0xffff0000, v123
	v_pk_fma_f32 v[136:137], v[122:123], v[122:123], v[136:137]
	v_lshlrev_b32_e32 v142, 16, v124
	v_and_b32_e32 v143, 0xffff0000, v124
	v_pk_fma_f32 v[136:137], v[142:143], v[142:143], v[136:137]
	v_lshlrev_b32_e32 v124, 16, v125
	v_and_b32_e32 v125, 0xffff0000, v125
	v_pk_fma_f32 v[136:137], v[124:125], v[124:125], v[136:137]
	v_lshlrev_b32_e32 v144, 16, v118
	v_and_b32_e32 v145, 0xffff0000, v118
	v_pk_fma_f32 v[136:137], v[144:145], v[144:145], v[136:137]
	v_lshlrev_b32_e32 v118, 16, v119
	v_and_b32_e32 v119, 0xffff0000, v119
	v_pk_fma_f32 v[136:137], v[118:119], v[118:119], v[136:137]
	v_lshlrev_b32_e32 v146, 16, v120
	v_and_b32_e32 v147, 0xffff0000, v120
	v_pk_fma_f32 v[136:137], v[146:147], v[146:147], v[136:137]
	v_lshlrev_b32_e32 v120, 16, v121
	v_and_b32_e32 v121, 0xffff0000, v121
	v_pk_fma_f32 v[136:137], v[120:121], v[120:121], v[136:137]
	v_lshlrev_b32_e32 v148, 16, v114
	v_and_b32_e32 v149, 0xffff0000, v114
	v_pk_fma_f32 v[136:137], v[148:149], v[148:149], v[136:137]
	v_lshlrev_b32_e32 v114, 16, v115
	v_and_b32_e32 v115, 0xffff0000, v115
	v_pk_fma_f32 v[136:137], v[114:115], v[114:115], v[136:137]
	v_lshlrev_b32_e32 v150, 16, v116
	v_and_b32_e32 v151, 0xffff0000, v116
	v_pk_fma_f32 v[136:137], v[150:151], v[150:151], v[136:137]
	v_lshlrev_b32_e32 v116, 16, v117
	v_and_b32_e32 v117, 0xffff0000, v117
	v_pk_fma_f32 v[136:137], v[116:117], v[116:117], v[136:137]
	v_cvt_f32_f16_sdwa v153, v110 dst_sel:DWORD dst_unused:UNUSED_PAD src0_sel:WORD_1
	v_add_f32_e32 v133, v136, v137
	v_mov_b32_e32 v136, 0
	v_cvt_f32_f16_e32 v152, v110
	v_add_f32_dpp v133, v133, v133 quad_perm:[1,0,3,2] row_mask:0xf bank_mask:0xf bound_ctrl:1
	v_cvt_f32_f16_sdwa v155, v111 dst_sel:DWORD dst_unused:UNUSED_PAD src0_sel:WORD_1
	v_cvt_f32_f16_e32 v154, v111
	v_add_f32_dpp v133, v133, v133 quad_perm:[2,3,0,1] row_mask:0xf bank_mask:0xf bound_ctrl:1
	v_pk_mul_f32 v[110:111], v[6:7], v[134:135]
	v_cvt_f32_f16_sdwa v135, v112 dst_sel:DWORD dst_unused:UNUSED_PAD src0_sel:WORD_1
	v_add_f32_dpp v133, v133, v133 row_half_mirror row_mask:0xf bank_mask:0xf bound_ctrl:1
	v_cvt_f32_f16_e32 v134, v112
	v_pk_mul_f32 v[122:123], v[16:17], v[122:123]
	v_add_f32_dpp v133, v133, v133 row_mirror row_mask:0xf bank_mask:0xf bound_ctrl:1
	v_pk_mul_f32 v[124:125], v[12:13], v[124:125]
	v_pk_mul_f32 v[126:127], v[8:9], v[126:127]
	v_mov_b32_dpp v136, v133 row_bcast:15 row_mask:0xa bank_mask:0xf
	v_add_f32_e32 v133, v133, v136
	v_mov_b32_e32 v136, 0
	v_pk_mul_f32 v[118:119], v[24:25], v[118:119]
	v_pk_mul_f32 v[128:129], v[4:5], v[128:129]
	v_mov_b32_dpp v136, v133 row_bcast:31 row_mask:0xc bank_mask:0xf
	v_add_f32_e32 v133, v133, v136
	v_pk_mul_f32 v[120:121], v[20:21], v[120:121]
	v_readlane_b32 s13, v133, 63
	s_nop 1
	v_fma_f32 v133, s13, v132, v1
	v_rsq_f32_e32 v133, v133
	s_nop 0
	v_mul_f32_e32 v136, 0.5, v133
	v_pk_fma_f32 v[110:111], v[110:111], v[136:137], v[152:153] op_sel_hi:[1,0,1]
	v_cvt_f32_f16_sdwa v153, v113 dst_sel:DWORD dst_unused:UNUSED_PAD src0_sel:WORD_1
	v_cvt_f32_f16_e32 v152, v113
	v_pk_mul_f32 v[112:113], v[2:3], v[138:139]
	v_cvt_f32_f16_sdwa v139, v107 dst_sel:DWORD dst_unused:UNUSED_PAD src0_sel:WORD_1
	v_pk_fma_f32 v[112:113], v[112:113], v[136:137], v[134:135] op_sel_hi:[1,0,1]
	v_cvt_f32_f16_sdwa v135, v106 dst_sel:DWORD dst_unused:UNUSED_PAD src0_sel:WORD_1
	v_cvt_f32_f16_e32 v134, v106
	v_cvt_f32_f16_e32 v138, v107
	v_pk_mul_f32 v[106:107], v[14:15], v[140:141]
	v_pk_fma_f32 v[126:127], v[126:127], v[136:137], v[154:155] op_sel_hi:[1,0,1]
	v_pk_fma_f32 v[106:107], v[106:107], v[136:137], v[134:135] op_sel_hi:[1,0,1]
	v_cvt_f32_f16_sdwa v135, v108 dst_sel:DWORD dst_unused:UNUSED_PAD src0_sel:WORD_1
	v_cvt_f32_f16_e32 v134, v108
	v_pk_fma_f32 v[122:123], v[122:123], v[136:137], v[138:139] op_sel_hi:[1,0,1]
	v_cvt_f32_f16_sdwa v139, v109 dst_sel:DWORD dst_unused:UNUSED_PAD src0_sel:WORD_1
	v_cvt_f32_f16_e32 v138, v109
	v_pk_mul_f32 v[108:109], v[10:11], v[142:143]
	v_pk_mul_f32 v[142:143], v[126:127], v[126:127]
	v_pk_fma_f32 v[108:109], v[108:109], v[136:137], v[134:135] op_sel_hi:[1,0,1]
	v_cvt_f32_f16_sdwa v135, v102 dst_sel:DWORD dst_unused:UNUSED_PAD src0_sel:WORD_1
	v_cvt_f32_f16_e32 v134, v102
	v_pk_fma_f32 v[124:125], v[124:125], v[136:137], v[138:139] op_sel_hi:[1,0,1]
	v_cvt_f32_f16_sdwa v139, v103 dst_sel:DWORD dst_unused:UNUSED_PAD src0_sel:WORD_1
	v_cvt_f32_f16_e32 v138, v103
	v_pk_mul_f32 v[102:103], v[22:23], v[144:145]
	v_pk_fma_f32 v[142:143], v[110:111], v[110:111], v[142:143]
	v_pk_fma_f32 v[102:103], v[102:103], v[136:137], v[134:135] op_sel_hi:[1,0,1]
	v_cvt_f32_f16_sdwa v135, v104 dst_sel:DWORD dst_unused:UNUSED_PAD src0_sel:WORD_1
	v_cvt_f32_f16_e32 v134, v104
	v_pk_fma_f32 v[118:119], v[118:119], v[136:137], v[138:139] op_sel_hi:[1,0,1]
	v_cvt_f32_f16_sdwa v139, v105 dst_sel:DWORD dst_unused:UNUSED_PAD src0_sel:WORD_1
	v_cvt_f32_f16_e32 v138, v105
	v_pk_fma_f32 v[128:129], v[128:129], v[136:137], v[152:153] op_sel_hi:[1,0,1]
	v_pk_fma_f32 v[142:143], v[112:113], v[112:113], v[142:143]
	v_pk_mul_f32 v[104:105], v[18:19], v[146:147]
	v_pk_fma_f32 v[142:143], v[128:129], v[128:129], v[142:143]
	v_pk_fma_f32 v[104:105], v[104:105], v[136:137], v[134:135] op_sel_hi:[1,0,1]
	v_cvt_f32_f16_sdwa v135, v98 dst_sel:DWORD dst_unused:UNUSED_PAD src0_sel:WORD_1
	v_cvt_f32_f16_e32 v134, v98
	v_pk_fma_f32 v[142:143], v[106:107], v[106:107], v[142:143]
	v_pk_fma_f32 v[120:121], v[120:121], v[136:137], v[138:139] op_sel_hi:[1,0,1]
	v_cvt_f32_f16_sdwa v139, v99 dst_sel:DWORD dst_unused:UNUSED_PAD src0_sel:WORD_1
	v_cvt_f32_f16_e32 v138, v99
	v_pk_fma_f32 v[142:143], v[122:123], v[122:123], v[142:143]
	v_pk_mul_f32 v[98:99], v[30:31], v[148:149]
	v_pk_fma_f32 v[142:143], v[108:109], v[108:109], v[142:143]
	v_pk_fma_f32 v[134:135], v[98:99], v[136:137], v[134:135] op_sel_hi:[1,0,1]
	v_pk_fma_f32 v[142:143], v[124:125], v[124:125], v[142:143]
	v_pk_mul_f32 v[98:99], v[32:33], v[114:115]
	v_pk_fma_f32 v[142:143], v[102:103], v[102:103], v[142:143]
	v_pk_fma_f32 v[114:115], v[98:99], v[136:137], v[138:139] op_sel_hi:[1,0,1]
	v_cvt_f32_f16_sdwa v99, v100 dst_sel:DWORD dst_unused:UNUSED_PAD src0_sel:WORD_1
	v_cvt_f32_f16_e32 v98, v100
	v_pk_fma_f32 v[142:143], v[118:119], v[118:119], v[142:143]
	v_cvt_f32_f16_sdwa v139, v101 dst_sel:DWORD dst_unused:UNUSED_PAD src0_sel:WORD_1
	v_cvt_f32_f16_e32 v138, v101
	v_pk_fma_f32 v[142:143], v[104:105], v[104:105], v[142:143]
	v_pk_mul_f32 v[100:101], v[26:27], v[150:151]
	v_pk_fma_f32 v[142:143], v[120:121], v[120:121], v[142:143]
	v_pk_fma_f32 v[140:141], v[100:101], v[136:137], v[98:99] op_sel_hi:[1,0,1]
	v_pk_fma_f32 v[142:143], v[134:135], v[134:135], v[142:143]
	v_pk_mul_f32 v[98:99], v[28:29], v[116:117]
	v_pk_fma_f32 v[142:143], v[114:115], v[114:115], v[142:143]
	v_pk_fma_f32 v[116:117], v[98:99], v[136:137], v[138:139] op_sel_hi:[1,0,1]
	v_pk_fma_f32 v[142:143], v[140:141], v[140:141], v[142:143]
	v_lshl_add_u64 v[136:137], s[14:15], 0, v[130:131]
	v_pk_fma_f32 v[142:143], v[116:117], v[116:117], v[142:143]
	v_add_co_u32_e32 v138, vcc, s11, v136
	v_add_f32_e32 v133, v142, v143
	v_mov_b32_e32 v142, 0
	v_cvt_pk_f16_f32 v98, v110, v111
	v_add_f32_dpp v133, v133, v133 quad_perm:[1,0,3,2] row_mask:0xf bank_mask:0xf bound_ctrl:1
	v_cvt_pk_f16_f32 v99, v126, v127
	v_cvt_pk_f16_f32 v100, v112, v113
	v_add_f32_dpp v133, v133, v133 quad_perm:[2,3,0,1] row_mask:0xf bank_mask:0xf bound_ctrl:1
	v_cvt_pk_f16_f32 v101, v128, v129
	v_addc_co_u32_e32 v139, vcc, 0, v137, vcc
	v_add_f32_dpp v133, v133, v133 row_half_mirror row_mask:0xf bank_mask:0xf bound_ctrl:1
	global_store_dwordx4 v[138:139], v[98:101], off offset:1024 sc1
	s_add_u32 s14, s14, s16
	v_add_f32_dpp v133, v133, v133 row_mirror row_mask:0xf bank_mask:0xf bound_ctrl:1
	v_cvt_pk_f16_f32 v98, v106, v107
	v_cvt_pk_f16_f32 v99, v122, v123
	v_mov_b32_dpp v142, v133 row_bcast:15 row_mask:0xa bank_mask:0xf
	v_add_f32_e32 v133, v133, v142
	v_mov_b32_e32 v142, 0
	v_cvt_pk_f16_f32 v100, v108, v109
	v_cvt_pk_f16_f32 v101, v124, v125
	v_mov_b32_dpp v142, v133 row_bcast:31 row_mask:0xc bank_mask:0xf
	v_add_f32_e32 v133, v133, v142
	global_store_dwordx4 v[138:139], v[98:101], off offset:2048 sc1
	v_readlane_b32 s13, v133, 63
	s_addc_u32 s15, s15, s17
	v_cvt_pk_f16_f32 v98, v102, v103
	v_fma_f32 v133, s13, v132, v1
	v_cvt_pk_f16_f32 v99, v118, v119
	v_cvt_pk_f16_f32 v100, v104, v105
	v_cvt_pk_f16_f32 v101, v120, v121
	v_rsq_f32_e32 v142, v133
	global_store_dwordx4 v[138:139], v[98:101], off offset:3072 sc1
	v_add_co_u32_e32 v138, vcc, s22, v136
	s_nop 0
	v_cvt_pk_f16_f32 v98, v134, v135
	v_cvt_pk_f16_f32 v99, v114, v115
	v_cvt_pk_f16_f32 v100, v140, v141
	v_cvt_pk_f16_f32 v101, v116, v117
	v_addc_co_u32_e32 v139, vcc, 0, v137, vcc
	global_store_dwordx4 v[138:139], v[98:101], off sc1
	s_add_u32 s18, s18, s16
	s_addc_u32 s19, s19, s17
	v_pk_mul_f32 v[98:99], v[40:41], v[126:127]
	s_nop 0
	v_pk_mul_f32 v[100:101], v[98:99], v[142:143] op_sel_hi:[1,0]
	v_pk_mul_f32 v[98:99], v[38:39], v[110:111]
	v_pk_mul_f32 v[110:111], v[36:37], v[128:129]
	v_pk_mul_f32 v[98:99], v[98:99], v[142:143] op_sel_hi:[1,0]
	v_pk_mul_f32 v[110:111], v[110:111], v[142:143] op_sel_hi:[1,0]
	v_cvt_pk_bf16_f32 v98, v98, v99
	v_cvt_pk_bf16_f32 v99, v100, v101
	v_pk_mul_f32 v[100:101], v[34:35], v[112:113]
	s_waitcnt vmcnt(9)
	v_mov_b64_e32 v[128:129], v[76:77]
	v_pk_mul_f32 v[100:101], v[100:101], v[142:143] op_sel_hi:[1,0]
	v_mov_b64_e32 v[126:127], v[74:75]
	v_cvt_pk_bf16_f32 v100, v100, v101
	v_cvt_pk_bf16_f32 v101, v110, v111
	v_add_co_u32_e32 v110, vcc, s23, v136
	s_nop 1
	v_addc_co_u32_e32 v111, vcc, 0, v137, vcc
	global_store_dwordx4 v[110:111], v[98:101], off
	s_andn2_b64 vcc, exec, s[20:21]
	s_nop 0
	v_pk_mul_f32 v[98:99], v[46:47], v[106:107]
	v_pk_mul_f32 v[100:101], v[48:49], v[122:123]
	v_pk_mul_f32 v[98:99], v[98:99], v[142:143] op_sel_hi:[1,0]
	v_pk_mul_f32 v[100:101], v[100:101], v[142:143] op_sel_hi:[1,0]
	v_cvt_pk_bf16_f32 v98, v98, v99
	v_pk_mul_f32 v[106:107], v[44:45], v[124:125]
	v_cvt_pk_bf16_f32 v99, v100, v101
	v_pk_mul_f32 v[100:101], v[42:43], v[108:109]
	v_pk_mul_f32 v[106:107], v[106:107], v[142:143] op_sel_hi:[1,0]
	v_pk_mul_f32 v[100:101], v[100:101], v[142:143] op_sel_hi:[1,0]
	s_waitcnt vmcnt(8)
	v_mov_b64_e32 v[124:125], v[84:85]
	v_cvt_pk_bf16_f32 v100, v100, v101
	v_cvt_pk_bf16_f32 v101, v106, v107
	global_store_dwordx4 v[110:111], v[98:101], off offset:1024
	v_mov_b64_e32 v[108:109], v[72:73]
	v_mov_b64_e32 v[122:123], v[82:83]
	v_pk_mul_f32 v[98:99], v[54:55], v[102:103]
	v_pk_mul_f32 v[100:101], v[56:57], v[118:119]
	v_pk_mul_f32 v[98:99], v[98:99], v[142:143] op_sel_hi:[1,0]
	v_pk_mul_f32 v[100:101], v[100:101], v[142:143] op_sel_hi:[1,0]
	v_cvt_pk_bf16_f32 v98, v98, v99
	v_pk_mul_f32 v[102:103], v[52:53], v[120:121]
	v_cvt_pk_bf16_f32 v99, v100, v101
	v_pk_mul_f32 v[100:101], v[50:51], v[104:105]
	v_pk_mul_f32 v[102:103], v[102:103], v[142:143] op_sel_hi:[1,0]
	v_pk_mul_f32 v[100:101], v[100:101], v[142:143] op_sel_hi:[1,0]
	s_waitcnt vmcnt(8)
	v_mov_b64_e32 v[120:121], v[88:89]
	v_cvt_pk_bf16_f32 v100, v100, v101
	v_cvt_pk_bf16_f32 v101, v102, v103
	global_store_dwordx4 v[110:111], v[98:101], off offset:2048
	s_waitcnt vmcnt(8)
	v_pk_mul_f32 v[102:103], v[60:61], v[116:117]
	v_mov_b64_e32 v[118:119], v[86:87]
	s_waitcnt vmcnt(7)
	v_pk_mul_f32 v[98:99], v[62:63], v[134:135]
	v_pk_mul_f32 v[100:101], v[64:65], v[114:115]
	v_pk_mul_f32 v[98:99], v[98:99], v[142:143] op_sel_hi:[1,0]
	v_pk_mul_f32 v[100:101], v[100:101], v[142:143] op_sel_hi:[1,0]
	v_cvt_pk_bf16_f32 v98, v98, v99
	v_pk_mul_f32 v[102:103], v[102:103], v[142:143] op_sel_hi:[1,0]
	v_cvt_pk_bf16_f32 v99, v100, v101
	v_pk_mul_f32 v[100:101], v[58:59], v[140:141]
	v_mov_b64_e32 v[116:117], v[92:93]
	v_pk_mul_f32 v[100:101], v[100:101], v[142:143] op_sel_hi:[1,0]
	v_mov_b64_e32 v[114:115], v[90:91]
	v_cvt_pk_bf16_f32 v100, v100, v101
	v_cvt_pk_bf16_f32 v101, v102, v103
	global_store_dwordx4 v[110:111], v[98:101], off offset:3072
	v_mov_b64_e32 v[112:113], v[68:69]
	v_mov_b64_e32 v[104:105], v[80:81]
	v_mov_b64_e32 v[100:101], v[96:97]
	v_mov_b64_e32 v[110:111], v[66:67]
	v_mov_b64_e32 v[106:107], v[70:71]
	v_mov_b64_e32 v[102:103], v[78:79]
	v_mov_b64_e32 v[98:99], v[94:95]
	s_cbranch_vccz .LBB0_312

.LBB0_641:
	v_lshlrev_b32_e32 v140, 16, v126
	v_and_b32_e32 v141, 0xffff0000, v126
	v_lshlrev_b32_e32 v126, 16, v127
	v_and_b32_e32 v127, 0xffff0000, v127
	v_pk_mul_f32 v[142:143], v[126:127], v[126:127]
	v_lshlrev_b32_e32 v144, 16, v128
	v_pk_fma_f32 v[142:143], v[140:141], v[140:141], v[142:143]
	v_and_b32_e32 v145, 0xffff0000, v128
	v_pk_fma_f32 v[142:143], v[144:145], v[144:145], v[142:143]
	v_lshlrev_b32_e32 v128, 16, v129
	v_and_b32_e32 v129, 0xffff0000, v129
	v_pk_fma_f32 v[142:143], v[128:129], v[128:129], v[142:143]
	v_lshlrev_b32_e32 v146, 16, v122
	v_and_b32_e32 v147, 0xffff0000, v122
	v_pk_fma_f32 v[142:143], v[146:147], v[146:147], v[142:143]
	v_lshlrev_b32_e32 v122, 16, v123
	v_and_b32_e32 v123, 0xffff0000, v123
	v_pk_fma_f32 v[142:143], v[122:123], v[122:123], v[142:143]
	v_lshlrev_b32_e32 v148, 16, v124
	v_and_b32_e32 v149, 0xffff0000, v124
	v_pk_fma_f32 v[142:143], v[148:149], v[148:149], v[142:143]
	v_lshlrev_b32_e32 v124, 16, v125
	v_and_b32_e32 v125, 0xffff0000, v125
	v_pk_fma_f32 v[142:143], v[124:125], v[124:125], v[142:143]
	v_lshlrev_b32_e32 v150, 16, v118
	v_and_b32_e32 v151, 0xffff0000, v118
	v_pk_fma_f32 v[142:143], v[150:151], v[150:151], v[142:143]
	v_lshlrev_b32_e32 v118, 16, v119
	v_and_b32_e32 v119, 0xffff0000, v119
	v_pk_fma_f32 v[142:143], v[118:119], v[118:119], v[142:143]
	v_lshlrev_b32_e32 v152, 16, v120
	v_and_b32_e32 v153, 0xffff0000, v120
	v_pk_fma_f32 v[142:143], v[152:153], v[152:153], v[142:143]
	v_lshlrev_b32_e32 v120, 16, v121
	v_and_b32_e32 v121, 0xffff0000, v121
	v_pk_fma_f32 v[142:143], v[120:121], v[120:121], v[142:143]
	v_lshlrev_b32_e32 v154, 16, v114
	v_and_b32_e32 v155, 0xffff0000, v114
	v_pk_fma_f32 v[142:143], v[154:155], v[154:155], v[142:143]
	v_lshlrev_b32_e32 v114, 16, v115
	v_and_b32_e32 v115, 0xffff0000, v115
	v_pk_fma_f32 v[142:143], v[114:115], v[114:115], v[142:143]
	v_lshlrev_b32_e32 v156, 16, v116
	v_and_b32_e32 v157, 0xffff0000, v116
	v_pk_fma_f32 v[142:143], v[156:157], v[156:157], v[142:143]
	v_lshlrev_b32_e32 v116, 16, v117
	v_and_b32_e32 v117, 0xffff0000, v117
	v_pk_fma_f32 v[142:143], v[116:117], v[116:117], v[142:143]
	v_cvt_f32_f16_sdwa v159, v110 dst_sel:DWORD dst_unused:UNUSED_PAD src0_sel:WORD_1
	v_add_f32_e32 v142, v142, v143
	v_mov_b32_e32 v143, 0
	v_cvt_f32_f16_e32 v158, v110
	v_add_f32_dpp v142, v142, v142 quad_perm:[1,0,3,2] row_mask:0xf bank_mask:0xf bound_ctrl:1
	v_cvt_f32_f16_sdwa v161, v111 dst_sel:DWORD dst_unused:UNUSED_PAD src0_sel:WORD_1
	v_cvt_f32_f16_e32 v160, v111
	v_add_f32_dpp v142, v142, v142 quad_perm:[2,3,0,1] row_mask:0xf bank_mask:0xf bound_ctrl:1
	v_pk_mul_f32 v[110:111], v[6:7], v[140:141]
	v_cvt_f32_f16_sdwa v141, v112 dst_sel:DWORD dst_unused:UNUSED_PAD src0_sel:WORD_1
	v_add_f32_dpp v142, v142, v142 row_half_mirror row_mask:0xf bank_mask:0xf bound_ctrl:1
	v_cvt_f32_f16_e32 v140, v112
	v_pk_mul_f32 v[128:129], v[4:5], v[128:129]
	v_add_f32_dpp v142, v142, v142 row_mirror row_mask:0xf bank_mask:0xf bound_ctrl:1
	v_pk_mul_f32 v[122:123], v[16:17], v[122:123]
	v_pk_mul_f32 v[118:119], v[24:25], v[118:119]
	v_mov_b32_dpp v143, v142 row_bcast:15 row_mask:0xa bank_mask:0xf
	v_add_f32_e32 v142, v142, v143
	v_mov_b32_e32 v143, 0
	v_pk_mul_f32 v[126:127], v[8:9], v[126:127]
	s_nop 0
	v_mov_b32_dpp v143, v142 row_bcast:31 row_mask:0xc bank_mask:0xf
	v_add_f32_e32 v142, v142, v143
	s_nop 0
	v_readlane_b32 s6, v142, 63
	s_nop 1
	v_fma_f32 v142, s6, v137, v136
	v_rsq_f32_e32 v142, v142
	s_nop 0
	v_pk_fma_f32 v[110:111], v[110:111], v[142:143], v[158:159] op_sel_hi:[1,0,1]
	v_cvt_f32_f16_sdwa v159, v113 dst_sel:DWORD dst_unused:UNUSED_PAD src0_sel:WORD_1
	v_cvt_f32_f16_e32 v158, v113
	v_pk_mul_f32 v[112:113], v[2:3], v[144:145]
	v_cvt_f32_f16_sdwa v145, v107 dst_sel:DWORD dst_unused:UNUSED_PAD src0_sel:WORD_1
	v_cvt_f32_f16_e32 v144, v107
	v_pk_fma_f32 v[112:113], v[112:113], v[142:143], v[140:141] op_sel_hi:[1,0,1]
	v_pk_fma_f32 v[140:141], v[128:129], v[142:143], v[158:159] op_sel_hi:[1,0,1]
	v_cvt_f32_f16_sdwa v129, v106 dst_sel:DWORD dst_unused:UNUSED_PAD src0_sel:WORD_1
	v_cvt_f32_f16_e32 v128, v106
	v_pk_mul_f32 v[106:107], v[14:15], v[146:147]
	v_pk_fma_f32 v[144:145], v[122:123], v[142:143], v[144:145] op_sel_hi:[1,0,1]
	v_cvt_f32_f16_sdwa v123, v108 dst_sel:DWORD dst_unused:UNUSED_PAD src0_sel:WORD_1
	v_cvt_f32_f16_e32 v122, v108
	v_pk_fma_f32 v[106:107], v[106:107], v[142:143], v[128:129] op_sel_hi:[1,0,1]
	v_cvt_f32_f16_sdwa v129, v109 dst_sel:DWORD dst_unused:UNUSED_PAD src0_sel:WORD_1
	v_cvt_f32_f16_e32 v128, v109
	v_pk_mul_f32 v[108:109], v[10:11], v[148:149]
	v_pk_fma_f32 v[126:127], v[126:127], v[142:143], v[160:161] op_sel_hi:[1,0,1]
	v_pk_fma_f32 v[108:109], v[108:109], v[142:143], v[122:123] op_sel_hi:[1,0,1]
	v_pk_mul_f32 v[122:123], v[12:13], v[124:125]
	v_cvt_f32_f16_sdwa v125, v103 dst_sel:DWORD dst_unused:UNUSED_PAD src0_sel:WORD_1
	v_cvt_f32_f16_e32 v124, v103
	v_pk_fma_f32 v[146:147], v[122:123], v[142:143], v[128:129] op_sel_hi:[1,0,1]
	v_cvt_f32_f16_sdwa v123, v102 dst_sel:DWORD dst_unused:UNUSED_PAD src0_sel:WORD_1
	v_cvt_f32_f16_e32 v122, v102
	v_pk_mul_f32 v[102:103], v[22:23], v[150:151]
	v_pk_fma_f32 v[148:149], v[118:119], v[142:143], v[124:125] op_sel_hi:[1,0,1]
	v_cvt_f32_f16_sdwa v119, v104 dst_sel:DWORD dst_unused:UNUSED_PAD src0_sel:WORD_1
	v_cvt_f32_f16_e32 v118, v104
	v_pk_fma_f32 v[102:103], v[102:103], v[142:143], v[122:123] op_sel_hi:[1,0,1]
	v_cvt_f32_f16_sdwa v123, v105 dst_sel:DWORD dst_unused:UNUSED_PAD src0_sel:WORD_1
	v_cvt_f32_f16_e32 v122, v105
	v_pk_mul_f32 v[104:105], v[18:19], v[152:153]
	s_nop 0
	v_pk_fma_f32 v[104:105], v[104:105], v[142:143], v[118:119] op_sel_hi:[1,0,1]
	v_pk_mul_f32 v[118:119], v[20:21], v[120:121]
	v_cvt_f32_f16_sdwa v121, v99 dst_sel:DWORD dst_unused:UNUSED_PAD src0_sel:WORD_1
	v_pk_fma_f32 v[150:151], v[118:119], v[142:143], v[122:123] op_sel_hi:[1,0,1]
	v_cvt_f32_f16_sdwa v119, v98 dst_sel:DWORD dst_unused:UNUSED_PAD src0_sel:WORD_1
	v_cvt_f32_f16_e32 v118, v98
	v_cvt_f32_f16_e32 v120, v99
	v_pk_mul_f32 v[98:99], v[30:31], v[154:155]
	s_nop 0
	v_pk_fma_f32 v[152:153], v[98:99], v[142:143], v[118:119] op_sel_hi:[1,0,1]
	v_pk_mul_f32 v[98:99], v[32:33], v[114:115]
	v_cvt_f32_f16_sdwa v115, v101 dst_sel:DWORD dst_unused:UNUSED_PAD src0_sel:WORD_1
	v_pk_fma_f32 v[154:155], v[98:99], v[142:143], v[120:121] op_sel_hi:[1,0,1]
	v_cvt_f32_f16_sdwa v99, v100 dst_sel:DWORD dst_unused:UNUSED_PAD src0_sel:WORD_1
	v_cvt_f32_f16_e32 v98, v100
	v_cvt_f32_f16_e32 v114, v101
	v_pk_mul_f32 v[100:101], v[26:27], v[156:157]
	s_nop 0
	v_pk_fma_f32 v[156:157], v[100:101], v[142:143], v[98:99] op_sel_hi:[1,0,1]
	v_pk_mul_f32 v[98:99], v[28:29], v[116:117]
	v_cvt_pk_f16_f32 v100, v112, v113
	v_pk_fma_f32 v[142:143], v[98:99], v[142:143], v[114:115] op_sel_hi:[1,0,1]
	v_lshl_add_u64 v[114:115], s[94:95], 0, v[132:133]
	v_add_co_u32_e32 v116, vcc, s28, v114
	v_cvt_pk_f16_f32 v98, v110, v111
	v_cvt_pk_f16_f32 v99, v126, v127
	v_cvt_pk_f16_f32 v101, v140, v141
	v_addc_co_u32_e32 v117, vcc, 0, v115, vcc
	global_store_dwordx4 v[116:117], v[98:101], off offset:1024 sc1
	v_add_co_u32_e32 v114, vcc, s29, v114
	s_nop 0
	v_cvt_pk_f16_f32 v98, v106, v107
	v_cvt_pk_f16_f32 v99, v144, v145
	v_cvt_pk_f16_f32 v100, v108, v109
	v_cvt_pk_f16_f32 v101, v146, v147
	global_store_dwordx4 v[116:117], v[98:101], off offset:2048 sc1
	v_addc_co_u32_e32 v115, vcc, 0, v115, vcc
	s_nop 0
	v_cvt_pk_f16_f32 v98, v102, v103
	v_cvt_pk_f16_f32 v99, v148, v149
	v_cvt_pk_f16_f32 v100, v104, v105
	v_cvt_pk_f16_f32 v101, v150, v151
	global_store_dwordx4 v[116:117], v[98:101], off offset:3072 sc1
	v_pk_mul_f32 v[116:117], v[126:127], v[126:127]
	s_nop 0
	v_pk_fma_f32 v[116:117], v[110:111], v[110:111], v[116:117]
	v_cvt_pk_f16_f32 v98, v152, v153
	v_pk_fma_f32 v[116:117], v[112:113], v[112:113], v[116:117]
	v_cvt_pk_f16_f32 v99, v154, v155
	v_pk_fma_f32 v[116:117], v[140:141], v[140:141], v[116:117]
	v_cvt_pk_f16_f32 v100, v156, v157
	v_pk_fma_f32 v[116:117], v[106:107], v[106:107], v[116:117]
	v_cvt_pk_f16_f32 v101, v142, v143
	v_pk_fma_f32 v[116:117], v[144:145], v[144:145], v[116:117]
	global_store_dwordx4 v[114:115], v[98:101], off sc1
	v_pk_fma_f32 v[116:117], v[108:109], v[108:109], v[116:117]
	s_nop 0
	v_pk_fma_f32 v[116:117], v[146:147], v[146:147], v[116:117]
	v_pk_mul_f32 v[98:99], v[40:41], v[126:127]
	v_pk_fma_f32 v[116:117], v[102:103], v[102:103], v[116:117]
	s_nop 0
	v_pk_fma_f32 v[116:117], v[148:149], v[148:149], v[116:117]
	s_nop 0
	v_pk_fma_f32 v[116:117], v[104:105], v[104:105], v[116:117]
	s_nop 0
	v_pk_fma_f32 v[116:117], v[150:151], v[150:151], v[116:117]
	s_nop 0
	v_pk_fma_f32 v[116:117], v[152:153], v[152:153], v[116:117]
	s_nop 0
	v_pk_fma_f32 v[116:117], v[154:155], v[154:155], v[116:117]
	s_nop 0
	v_pk_fma_f32 v[116:117], v[156:157], v[156:157], v[116:117]
	s_nop 0
	v_pk_fma_f32 v[116:117], v[142:143], v[142:143], v[116:117]
	s_nop 0
	v_add_f32_e32 v116, v116, v117
	v_mov_b32_e32 v117, 0
	s_nop 0
	v_add_f32_dpp v116, v116, v116 quad_perm:[1,0,3,2] row_mask:0xf bank_mask:0xf bound_ctrl:1
	s_nop 1
	v_add_f32_dpp v116, v116, v116 quad_perm:[2,3,0,1] row_mask:0xf bank_mask:0xf bound_ctrl:1
	s_nop 1
	v_add_f32_dpp v116, v116, v116 row_half_mirror row_mask:0xf bank_mask:0xf bound_ctrl:1
	s_nop 1
	v_add_f32_dpp v116, v116, v116 row_mirror row_mask:0xf bank_mask:0xf bound_ctrl:1
	s_nop 1
	v_mov_b32_dpp v117, v116 row_bcast:15 row_mask:0xa bank_mask:0xf
	v_add_f32_e32 v116, v116, v117
	v_mov_b32_e32 v117, 0
	s_nop 1
	v_mov_b32_dpp v117, v116 row_bcast:31 row_mask:0xc bank_mask:0xf
	v_add_f32_e32 v116, v116, v117
	s_nop 0
	v_readlane_b32 s6, v116, 63
	s_nop 1
	v_fma_f32 v116, s6, v137, v136
	v_rsq_f32_e32 v158, v116
	s_nop 0
	v_pk_mul_f32 v[122:123], v[98:99], v[158:159] op_sel_hi:[1,0]
	v_pk_mul_f32 v[98:99], v[38:39], v[110:111]
	s_nop 0
	v_pk_mul_f32 v[128:129], v[98:99], v[158:159] op_sel_hi:[1,0]
	v_max_f32_e64 v99, |v122|, |v123|
	v_max_f32_e64 v98, |v128|, |v129|
	v_max3_f32 v100, v98, 0, v99
	v_pk_mul_f32 v[98:99], v[34:35], v[112:113]
	s_nop 0
	v_pk_mul_f32 v[124:125], v[98:99], v[158:159] op_sel_hi:[1,0]
	v_pk_mul_f32 v[98:99], v[36:37], v[140:141]
	v_max_f32_e64 v101, |v124|, |v125|
	v_pk_mul_f32 v[126:127], v[98:99], v[158:159] op_sel_hi:[1,0]
	s_nop 0
	v_max_f32_e64 v98, |v126|, |v127|
	v_max3_f32 v100, v100, v101, v98
	v_pk_mul_f32 v[98:99], v[46:47], v[106:107]
	s_nop 0
	v_pk_mul_f32 v[114:115], v[98:99], v[158:159] op_sel_hi:[1,0]
	v_pk_mul_f32 v[98:99], v[48:49], v[144:145]
	v_max_f32_e64 v101, |v114|, |v115|
	v_pk_mul_f32 v[118:119], v[98:99], v[158:159] op_sel_hi:[1,0]
	s_nop 0
	v_max_f32_e64 v98, |v118|, |v119|
	v_max3_f32 v100, v100, v101, v98
	v_pk_mul_f32 v[98:99], v[42:43], v[108:109]
	s_nop 0
	v_pk_mul_f32 v[116:117], v[98:99], v[158:159] op_sel_hi:[1,0]
	v_pk_mul_f32 v[98:99], v[44:45], v[146:147]
	v_max_f32_e64 v101, |v116|, |v117|
	v_pk_mul_f32 v[120:121], v[98:99], v[158:159] op_sel_hi:[1,0]
	s_nop 0
	v_max_f32_e64 v98, |v120|, |v121|
	v_max3_f32 v100, v100, v101, v98
	v_pk_mul_f32 v[98:99], v[54:55], v[102:103]
	s_nop 0
	v_pk_mul_f32 v[106:107], v[98:99], v[158:159] op_sel_hi:[1,0]
	v_pk_mul_f32 v[98:99], v[56:57], v[148:149]
	v_max_f32_e64 v101, |v106|, |v107|
	v_pk_mul_f32 v[110:111], v[98:99], v[158:159] op_sel_hi:[1,0]
	s_nop 0
	v_max_f32_e64 v98, |v110|, |v111|
	v_max3_f32 v100, v100, v101, v98
	v_pk_mul_f32 v[98:99], v[50:51], v[104:105]
	s_nop 0
	v_pk_mul_f32 v[108:109], v[98:99], v[158:159] op_sel_hi:[1,0]
	v_pk_mul_f32 v[98:99], v[52:53], v[150:151]
	v_max_f32_e64 v101, |v108|, |v109|
	v_pk_mul_f32 v[112:113], v[98:99], v[158:159] op_sel_hi:[1,0]
	s_nop 0
	v_max_f32_e64 v98, |v112|, |v113|
	v_max3_f32 v104, v100, v101, v98
	s_waitcnt vmcnt(4)
	v_pk_mul_f32 v[98:99], v[62:63], v[152:153]
	v_pk_mul_f32 v[100:101], v[64:65], v[154:155]
	v_pk_mul_f32 v[98:99], v[98:99], v[158:159] op_sel_hi:[1,0]
	v_pk_mul_f32 v[102:103], v[100:101], v[158:159] op_sel_hi:[1,0]
	v_max_f32_e64 v105, |v98|, |v99|
	v_max_f32_e64 v100, |v102|, |v103|
	v_max3_f32 v140, v104, v105, v100
	v_pk_mul_f32 v[100:101], v[58:59], v[156:157]
	v_pk_mul_f32 v[104:105], v[60:61], v[142:143]
	v_pk_mul_f32 v[100:101], v[100:101], v[158:159] op_sel_hi:[1,0]
	v_pk_mul_f32 v[104:105], v[104:105], v[158:159] op_sel_hi:[1,0]
	v_max_f32_e64 v141, |v100|, |v101|
	v_max_f32_e64 v142, |v104|, |v105|
	v_max3_f32 v140, v140, v141, v142
	v_mov_b32_e32 v141, 0
	s_nop 1
	v_mov_b32_dpp v141, v140 quad_perm:[1,0,3,2] row_mask:0xf bank_mask:0xf
	v_max_f32_e32 v141, v141, v141
	v_max_f32_e32 v140, v140, v141
	v_mov_b32_e32 v141, 0
	s_nop 1
	v_mov_b32_dpp v141, v140 quad_perm:[2,3,0,1] row_mask:0xf bank_mask:0xf
	v_max_f32_e32 v141, v141, v141
	v_max_f32_e32 v140, v140, v141
	v_mov_b32_e32 v141, 0
	s_nop 1
	v_mov_b32_dpp v141, v140 row_half_mirror row_mask:0xf bank_mask:0xf
	v_max_f32_e32 v141, v141, v141
	v_max_f32_e32 v140, v140, v141
	v_mov_b32_e32 v141, 0
	s_nop 1
	v_mov_b32_dpp v141, v140 row_mirror row_mask:0xf bank_mask:0xf
	v_max_f32_e32 v141, v141, v141
	v_max_f32_e32 v140, v140, v141
	v_mov_b32_e32 v141, 0
	s_nop 1
	v_mov_b32_dpp v141, v140 row_bcast:15 row_mask:0xa bank_mask:0xf
	v_max_f32_e32 v141, v141, v141
	v_max_f32_e32 v140, v140, v141
	v_mov_b32_e32 v141, 0
	s_nop 1
	v_mov_b32_dpp v141, v140 row_bcast:31 row_mask:0xc bank_mask:0xf
	v_max_f32_e32 v141, v141, v141
	v_max_f32_e32 v140, v140, v141
	s_nop 0
	v_readlane_b32 s17, v140, 63
	s_nop 1
	v_cmp_gt_f32_e64 s[6:7], s17, 0
	s_and_saveexec_b64 s[26:27], s[4:5]
	s_cbranch_execz .LBB0_638
	v_mul_f32_e32 v140, s17, v138
	s_add_u32 s38, s94, s15
	v_cndmask_b32_e64 v140, 1.0, v140, s[6:7]
	s_addc_u32 s39, s95, s37
	global_store_dword v1, v140, s[38:39]
	s_branch .LBB0_638

.LBB0_912:
	v_lshlrev_b32_e32 v140, 16, v126
	v_and_b32_e32 v141, 0xffff0000, v126
	v_lshlrev_b32_e32 v126, 16, v127
	v_and_b32_e32 v127, 0xffff0000, v127
	v_pk_mul_f32 v[142:143], v[126:127], v[126:127]
	v_lshlrev_b32_e32 v144, 16, v128
	v_pk_fma_f32 v[142:143], v[140:141], v[140:141], v[142:143]
	v_and_b32_e32 v145, 0xffff0000, v128
	v_pk_fma_f32 v[142:143], v[144:145], v[144:145], v[142:143]
	v_lshlrev_b32_e32 v128, 16, v129
	v_and_b32_e32 v129, 0xffff0000, v129
	v_pk_fma_f32 v[142:143], v[128:129], v[128:129], v[142:143]
	v_lshlrev_b32_e32 v146, 16, v122
	v_and_b32_e32 v147, 0xffff0000, v122
	v_pk_fma_f32 v[142:143], v[146:147], v[146:147], v[142:143]
	v_lshlrev_b32_e32 v122, 16, v123
	v_and_b32_e32 v123, 0xffff0000, v123
	v_pk_fma_f32 v[142:143], v[122:123], v[122:123], v[142:143]
	v_lshlrev_b32_e32 v148, 16, v124
	v_and_b32_e32 v149, 0xffff0000, v124
	v_pk_fma_f32 v[142:143], v[148:149], v[148:149], v[142:143]
	v_lshlrev_b32_e32 v124, 16, v125
	v_and_b32_e32 v125, 0xffff0000, v125
	v_pk_fma_f32 v[142:143], v[124:125], v[124:125], v[142:143]
	v_lshlrev_b32_e32 v150, 16, v118
	v_and_b32_e32 v151, 0xffff0000, v118
	v_pk_fma_f32 v[142:143], v[150:151], v[150:151], v[142:143]
	v_lshlrev_b32_e32 v118, 16, v119
	v_and_b32_e32 v119, 0xffff0000, v119
	v_pk_fma_f32 v[142:143], v[118:119], v[118:119], v[142:143]
	v_lshlrev_b32_e32 v152, 16, v120
	v_and_b32_e32 v153, 0xffff0000, v120
	v_pk_fma_f32 v[142:143], v[152:153], v[152:153], v[142:143]
	v_lshlrev_b32_e32 v120, 16, v121
	v_and_b32_e32 v121, 0xffff0000, v121
	v_pk_fma_f32 v[142:143], v[120:121], v[120:121], v[142:143]
	v_lshlrev_b32_e32 v154, 16, v114
	v_and_b32_e32 v155, 0xffff0000, v114
	v_pk_fma_f32 v[142:143], v[154:155], v[154:155], v[142:143]
	v_lshlrev_b32_e32 v114, 16, v115
	v_and_b32_e32 v115, 0xffff0000, v115
	v_pk_fma_f32 v[142:143], v[114:115], v[114:115], v[142:143]
	v_lshlrev_b32_e32 v156, 16, v116
	v_and_b32_e32 v157, 0xffff0000, v116
	v_pk_fma_f32 v[142:143], v[156:157], v[156:157], v[142:143]
	v_lshlrev_b32_e32 v116, 16, v117
	v_and_b32_e32 v117, 0xffff0000, v117
	v_pk_fma_f32 v[142:143], v[116:117], v[116:117], v[142:143]
	v_cvt_f32_f16_sdwa v159, v110 dst_sel:DWORD dst_unused:UNUSED_PAD src0_sel:WORD_1
	v_add_f32_e32 v142, v142, v143
	v_mov_b32_e32 v143, 0
	v_cvt_f32_f16_e32 v158, v110
	v_add_f32_dpp v142, v142, v142 quad_perm:[1,0,3,2] row_mask:0xf bank_mask:0xf bound_ctrl:1
	v_cvt_f32_f16_sdwa v161, v111 dst_sel:DWORD dst_unused:UNUSED_PAD src0_sel:WORD_1
	v_cvt_f32_f16_e32 v160, v111
	v_add_f32_dpp v142, v142, v142 quad_perm:[2,3,0,1] row_mask:0xf bank_mask:0xf bound_ctrl:1
	v_pk_mul_f32 v[110:111], v[6:7], v[140:141]
	v_cvt_f32_f16_sdwa v141, v112 dst_sel:DWORD dst_unused:UNUSED_PAD src0_sel:WORD_1
	v_add_f32_dpp v142, v142, v142 row_half_mirror row_mask:0xf bank_mask:0xf bound_ctrl:1
	v_cvt_f32_f16_e32 v140, v112
	v_pk_mul_f32 v[128:129], v[4:5], v[128:129]
	v_add_f32_dpp v142, v142, v142 row_mirror row_mask:0xf bank_mask:0xf bound_ctrl:1
	v_pk_mul_f32 v[122:123], v[16:17], v[122:123]
	v_pk_mul_f32 v[118:119], v[24:25], v[118:119]
	v_mov_b32_dpp v143, v142 row_bcast:15 row_mask:0xa bank_mask:0xf
	v_add_f32_e32 v142, v142, v143
	v_mov_b32_e32 v143, 0
	v_pk_mul_f32 v[126:127], v[8:9], v[126:127]
	s_nop 0
	v_mov_b32_dpp v143, v142 row_bcast:31 row_mask:0xc bank_mask:0xf
	v_add_f32_e32 v142, v142, v143
	s_nop 0
	v_readlane_b32 s6, v142, 63
	s_nop 1
	v_fma_f32 v142, s6, v137, v136
	v_rsq_f32_e32 v142, v142
	s_nop 0
	v_mul_f32_e32 v142, 0.5, v142
	v_pk_fma_f32 v[110:111], v[110:111], v[142:143], v[158:159] op_sel_hi:[1,0,1]
	v_cvt_f32_f16_sdwa v159, v113 dst_sel:DWORD dst_unused:UNUSED_PAD src0_sel:WORD_1
	v_cvt_f32_f16_e32 v158, v113
	v_pk_mul_f32 v[112:113], v[2:3], v[144:145]
	v_cvt_f32_f16_sdwa v145, v107 dst_sel:DWORD dst_unused:UNUSED_PAD src0_sel:WORD_1
	v_cvt_f32_f16_e32 v144, v107
	v_pk_fma_f32 v[112:113], v[112:113], v[142:143], v[140:141] op_sel_hi:[1,0,1]
	v_pk_fma_f32 v[140:141], v[128:129], v[142:143], v[158:159] op_sel_hi:[1,0,1]
	v_cvt_f32_f16_sdwa v129, v106 dst_sel:DWORD dst_unused:UNUSED_PAD src0_sel:WORD_1
	v_cvt_f32_f16_e32 v128, v106
	v_pk_mul_f32 v[106:107], v[14:15], v[146:147]
	v_pk_fma_f32 v[144:145], v[122:123], v[142:143], v[144:145] op_sel_hi:[1,0,1]
	v_cvt_f32_f16_sdwa v123, v108 dst_sel:DWORD dst_unused:UNUSED_PAD src0_sel:WORD_1
	v_cvt_f32_f16_e32 v122, v108
	v_pk_fma_f32 v[106:107], v[106:107], v[142:143], v[128:129] op_sel_hi:[1,0,1]
	v_cvt_f32_f16_sdwa v129, v109 dst_sel:DWORD dst_unused:UNUSED_PAD src0_sel:WORD_1
	v_cvt_f32_f16_e32 v128, v109
	v_pk_mul_f32 v[108:109], v[10:11], v[148:149]
	v_pk_fma_f32 v[126:127], v[126:127], v[142:143], v[160:161] op_sel_hi:[1,0,1]
	v_pk_fma_f32 v[108:109], v[108:109], v[142:143], v[122:123] op_sel_hi:[1,0,1]
	v_pk_mul_f32 v[122:123], v[12:13], v[124:125]
	v_cvt_f32_f16_sdwa v125, v103 dst_sel:DWORD dst_unused:UNUSED_PAD src0_sel:WORD_1
	v_cvt_f32_f16_e32 v124, v103
	v_pk_fma_f32 v[146:147], v[122:123], v[142:143], v[128:129] op_sel_hi:[1,0,1]
	v_cvt_f32_f16_sdwa v123, v102 dst_sel:DWORD dst_unused:UNUSED_PAD src0_sel:WORD_1
	v_cvt_f32_f16_e32 v122, v102
	v_pk_mul_f32 v[102:103], v[22:23], v[150:151]
	v_pk_fma_f32 v[148:149], v[118:119], v[142:143], v[124:125] op_sel_hi:[1,0,1]
	v_cvt_f32_f16_sdwa v119, v104 dst_sel:DWORD dst_unused:UNUSED_PAD src0_sel:WORD_1
	v_cvt_f32_f16_e32 v118, v104
	v_pk_fma_f32 v[102:103], v[102:103], v[142:143], v[122:123] op_sel_hi:[1,0,1]
	v_cvt_f32_f16_sdwa v123, v105 dst_sel:DWORD dst_unused:UNUSED_PAD src0_sel:WORD_1
	v_cvt_f32_f16_e32 v122, v105
	v_pk_mul_f32 v[104:105], v[18:19], v[152:153]
	s_nop 0
	v_pk_fma_f32 v[104:105], v[104:105], v[142:143], v[118:119] op_sel_hi:[1,0,1]
	v_pk_mul_f32 v[118:119], v[20:21], v[120:121]
	v_cvt_f32_f16_sdwa v121, v99 dst_sel:DWORD dst_unused:UNUSED_PAD src0_sel:WORD_1
	v_pk_fma_f32 v[150:151], v[118:119], v[142:143], v[122:123] op_sel_hi:[1,0,1]
	v_cvt_f32_f16_sdwa v119, v98 dst_sel:DWORD dst_unused:UNUSED_PAD src0_sel:WORD_1
	v_cvt_f32_f16_e32 v118, v98
	v_cvt_f32_f16_e32 v120, v99
	v_pk_mul_f32 v[98:99], v[30:31], v[154:155]
	s_nop 0
	v_pk_fma_f32 v[152:153], v[98:99], v[142:143], v[118:119] op_sel_hi:[1,0,1]
	v_pk_mul_f32 v[98:99], v[32:33], v[114:115]
	v_cvt_f32_f16_sdwa v115, v101 dst_sel:DWORD dst_unused:UNUSED_PAD src0_sel:WORD_1
	v_pk_fma_f32 v[154:155], v[98:99], v[142:143], v[120:121] op_sel_hi:[1,0,1]
	v_cvt_f32_f16_sdwa v99, v100 dst_sel:DWORD dst_unused:UNUSED_PAD src0_sel:WORD_1
	v_cvt_f32_f16_e32 v98, v100
	v_cvt_f32_f16_e32 v114, v101
	v_pk_mul_f32 v[100:101], v[26:27], v[156:157]
	s_nop 0
	v_pk_fma_f32 v[156:157], v[100:101], v[142:143], v[98:99] op_sel_hi:[1,0,1]
	v_pk_mul_f32 v[98:99], v[28:29], v[116:117]
	v_cvt_pk_f16_f32 v100, v112, v113
	v_pk_fma_f32 v[142:143], v[98:99], v[142:143], v[114:115] op_sel_hi:[1,0,1]
	v_lshl_add_u64 v[114:115], s[94:95], 0, v[132:133]
	v_add_co_u32_e32 v116, vcc, s28, v114
	v_cvt_pk_f16_f32 v98, v110, v111
	v_cvt_pk_f16_f32 v99, v126, v127
	v_cvt_pk_f16_f32 v101, v140, v141
	v_addc_co_u32_e32 v117, vcc, 0, v115, vcc
	global_store_dwordx4 v[116:117], v[98:101], off offset:1024 sc1
	v_add_co_u32_e32 v114, vcc, s29, v114
	s_nop 0
	v_cvt_pk_f16_f32 v98, v106, v107
	v_cvt_pk_f16_f32 v99, v144, v145
	v_cvt_pk_f16_f32 v100, v108, v109
	v_cvt_pk_f16_f32 v101, v146, v147
	global_store_dwordx4 v[116:117], v[98:101], off offset:2048 sc1
	v_addc_co_u32_e32 v115, vcc, 0, v115, vcc
	s_nop 0
	v_cvt_pk_f16_f32 v98, v102, v103
	v_cvt_pk_f16_f32 v99, v148, v149
	v_cvt_pk_f16_f32 v100, v104, v105
	v_cvt_pk_f16_f32 v101, v150, v151
	global_store_dwordx4 v[116:117], v[98:101], off offset:3072 sc1
	v_pk_mul_f32 v[116:117], v[126:127], v[126:127]
	s_nop 0
	v_pk_fma_f32 v[116:117], v[110:111], v[110:111], v[116:117]
	v_cvt_pk_f16_f32 v98, v152, v153
	v_pk_fma_f32 v[116:117], v[112:113], v[112:113], v[116:117]
	v_cvt_pk_f16_f32 v99, v154, v155
	v_pk_fma_f32 v[116:117], v[140:141], v[140:141], v[116:117]
	v_cvt_pk_f16_f32 v100, v156, v157
	v_pk_fma_f32 v[116:117], v[106:107], v[106:107], v[116:117]
	v_cvt_pk_f16_f32 v101, v142, v143
	v_pk_fma_f32 v[116:117], v[144:145], v[144:145], v[116:117]
	global_store_dwordx4 v[114:115], v[98:101], off sc1
	v_pk_fma_f32 v[116:117], v[108:109], v[108:109], v[116:117]
	s_nop 0
	v_pk_fma_f32 v[116:117], v[146:147], v[146:147], v[116:117]
	v_pk_mul_f32 v[98:99], v[40:41], v[126:127]
	v_pk_fma_f32 v[116:117], v[102:103], v[102:103], v[116:117]
	s_nop 0
	v_pk_fma_f32 v[116:117], v[148:149], v[148:149], v[116:117]
	s_nop 0
	v_pk_fma_f32 v[116:117], v[104:105], v[104:105], v[116:117]
	s_nop 0
	v_pk_fma_f32 v[116:117], v[150:151], v[150:151], v[116:117]
	s_nop 0
	v_pk_fma_f32 v[116:117], v[152:153], v[152:153], v[116:117]
	s_nop 0
	v_pk_fma_f32 v[116:117], v[154:155], v[154:155], v[116:117]
	s_nop 0
	v_pk_fma_f32 v[116:117], v[156:157], v[156:157], v[116:117]
	s_nop 0
	v_pk_fma_f32 v[116:117], v[142:143], v[142:143], v[116:117]
	s_nop 0
	v_add_f32_e32 v116, v116, v117
	v_mov_b32_e32 v117, 0
	s_nop 0
	v_add_f32_dpp v116, v116, v116 quad_perm:[1,0,3,2] row_mask:0xf bank_mask:0xf bound_ctrl:1
	s_nop 1
	v_add_f32_dpp v116, v116, v116 quad_perm:[2,3,0,1] row_mask:0xf bank_mask:0xf bound_ctrl:1
	s_nop 1
	v_add_f32_dpp v116, v116, v116 row_half_mirror row_mask:0xf bank_mask:0xf bound_ctrl:1
	s_nop 1
	v_add_f32_dpp v116, v116, v116 row_mirror row_mask:0xf bank_mask:0xf bound_ctrl:1
	s_nop 1
	v_mov_b32_dpp v117, v116 row_bcast:15 row_mask:0xa bank_mask:0xf
	v_add_f32_e32 v116, v116, v117
	v_mov_b32_e32 v117, 0
	s_nop 1
	v_mov_b32_dpp v117, v116 row_bcast:31 row_mask:0xc bank_mask:0xf
	v_add_f32_e32 v116, v116, v117
	s_nop 0
	v_readlane_b32 s6, v116, 63
	s_nop 1
	v_fma_f32 v116, s6, v137, v136
	v_rsq_f32_e32 v158, v116
	s_nop 0
	v_pk_mul_f32 v[122:123], v[98:99], v[158:159] op_sel_hi:[1,0]
	v_pk_mul_f32 v[98:99], v[38:39], v[110:111]
	s_nop 0
	v_pk_mul_f32 v[128:129], v[98:99], v[158:159] op_sel_hi:[1,0]
	v_max_f32_e64 v99, |v122|, |v123|
	v_max_f32_e64 v98, |v128|, |v129|
	v_max3_f32 v100, v98, 0, v99
	v_pk_mul_f32 v[98:99], v[34:35], v[112:113]
	s_nop 0
	v_pk_mul_f32 v[124:125], v[98:99], v[158:159] op_sel_hi:[1,0]
	v_pk_mul_f32 v[98:99], v[36:37], v[140:141]
	v_max_f32_e64 v101, |v124|, |v125|
	v_pk_mul_f32 v[126:127], v[98:99], v[158:159] op_sel_hi:[1,0]
	s_nop 0
	v_max_f32_e64 v98, |v126|, |v127|
	v_max3_f32 v100, v100, v101, v98
	v_pk_mul_f32 v[98:99], v[46:47], v[106:107]
	s_nop 0
	v_pk_mul_f32 v[114:115], v[98:99], v[158:159] op_sel_hi:[1,0]
	v_pk_mul_f32 v[98:99], v[48:49], v[144:145]
	v_max_f32_e64 v101, |v114|, |v115|
	v_pk_mul_f32 v[118:119], v[98:99], v[158:159] op_sel_hi:[1,0]
	s_nop 0
	v_max_f32_e64 v98, |v118|, |v119|
	v_max3_f32 v100, v100, v101, v98
	v_pk_mul_f32 v[98:99], v[42:43], v[108:109]
	s_nop 0
	v_pk_mul_f32 v[116:117], v[98:99], v[158:159] op_sel_hi:[1,0]
	v_pk_mul_f32 v[98:99], v[44:45], v[146:147]
	v_max_f32_e64 v101, |v116|, |v117|
	v_pk_mul_f32 v[120:121], v[98:99], v[158:159] op_sel_hi:[1,0]
	s_nop 0
	v_max_f32_e64 v98, |v120|, |v121|
	v_max3_f32 v100, v100, v101, v98
	v_pk_mul_f32 v[98:99], v[54:55], v[102:103]
	s_nop 0
	v_pk_mul_f32 v[106:107], v[98:99], v[158:159] op_sel_hi:[1,0]
	v_pk_mul_f32 v[98:99], v[56:57], v[148:149]
	v_max_f32_e64 v101, |v106|, |v107|
	v_pk_mul_f32 v[110:111], v[98:99], v[158:159] op_sel_hi:[1,0]
	s_nop 0
	v_max_f32_e64 v98, |v110|, |v111|
	v_max3_f32 v100, v100, v101, v98
	v_pk_mul_f32 v[98:99], v[50:51], v[104:105]
	s_nop 0
	v_pk_mul_f32 v[108:109], v[98:99], v[158:159] op_sel_hi:[1,0]
	v_pk_mul_f32 v[98:99], v[52:53], v[150:151]
	v_max_f32_e64 v101, |v108|, |v109|
	v_pk_mul_f32 v[112:113], v[98:99], v[158:159] op_sel_hi:[1,0]
	s_nop 0
	v_max_f32_e64 v98, |v112|, |v113|
	v_max3_f32 v104, v100, v101, v98
	s_waitcnt vmcnt(4)
	v_pk_mul_f32 v[98:99], v[62:63], v[152:153]
	v_pk_mul_f32 v[100:101], v[64:65], v[154:155]
	v_pk_mul_f32 v[98:99], v[98:99], v[158:159] op_sel_hi:[1,0]
	v_pk_mul_f32 v[102:103], v[100:101], v[158:159] op_sel_hi:[1,0]
	v_max_f32_e64 v105, |v98|, |v99|
	v_max_f32_e64 v100, |v102|, |v103|
	v_max3_f32 v140, v104, v105, v100
	v_pk_mul_f32 v[100:101], v[58:59], v[156:157]
	v_pk_mul_f32 v[104:105], v[60:61], v[142:143]
	v_pk_mul_f32 v[100:101], v[100:101], v[158:159] op_sel_hi:[1,0]
	v_pk_mul_f32 v[104:105], v[104:105], v[158:159] op_sel_hi:[1,0]
	v_max_f32_e64 v141, |v100|, |v101|
	v_max_f32_e64 v142, |v104|, |v105|
	v_max3_f32 v140, v140, v141, v142
	v_mov_b32_e32 v141, 0
	s_nop 1
	v_mov_b32_dpp v141, v140 quad_perm:[1,0,3,2] row_mask:0xf bank_mask:0xf
	v_max_f32_e32 v141, v141, v141
	v_max_f32_e32 v140, v140, v141
	v_mov_b32_e32 v141, 0
	s_nop 1
	v_mov_b32_dpp v141, v140 quad_perm:[2,3,0,1] row_mask:0xf bank_mask:0xf
	v_max_f32_e32 v141, v141, v141
	v_max_f32_e32 v140, v140, v141
	v_mov_b32_e32 v141, 0
	s_nop 1
	v_mov_b32_dpp v141, v140 row_half_mirror row_mask:0xf bank_mask:0xf
	v_max_f32_e32 v141, v141, v141
	v_max_f32_e32 v140, v140, v141
	v_mov_b32_e32 v141, 0
	s_nop 1
	v_mov_b32_dpp v141, v140 row_mirror row_mask:0xf bank_mask:0xf
	v_max_f32_e32 v141, v141, v141
	v_max_f32_e32 v140, v140, v141
	v_mov_b32_e32 v141, 0
	s_nop 1
	v_mov_b32_dpp v141, v140 row_bcast:15 row_mask:0xa bank_mask:0xf
	v_max_f32_e32 v141, v141, v141
	v_max_f32_e32 v140, v140, v141
	v_mov_b32_e32 v141, 0
	s_nop 1
	v_mov_b32_dpp v141, v140 row_bcast:31 row_mask:0xc bank_mask:0xf
	v_max_f32_e32 v141, v141, v141
	v_max_f32_e32 v140, v140, v141
	s_nop 0
	v_readlane_b32 s17, v140, 63
	s_nop 1
	v_cmp_gt_f32_e64 s[6:7], s17, 0
	s_and_saveexec_b64 s[26:27], s[4:5]
	s_cbranch_execz .LBB0_909
	v_mul_f32_e32 v140, s17, v138
	s_add_u32 s38, s94, s15
	v_cndmask_b32_e64 v140, 1.0, v140, s[6:7]
	s_addc_u32 s39, s95, s37
	global_store_dword v1, v140, s[38:39]
	s_branch .LBB0_909

.LBB0_1499:
	v_lshlrev_b32_e32 v140, 16, v126
	v_and_b32_e32 v141, 0xffff0000, v126
	v_lshlrev_b32_e32 v126, 16, v127
	v_and_b32_e32 v127, 0xffff0000, v127
	v_pk_mul_f32 v[142:143], v[126:127], v[126:127]
	v_lshlrev_b32_e32 v144, 16, v128
	v_pk_fma_f32 v[142:143], v[140:141], v[140:141], v[142:143]
	v_and_b32_e32 v145, 0xffff0000, v128
	v_pk_fma_f32 v[142:143], v[144:145], v[144:145], v[142:143]
	v_lshlrev_b32_e32 v128, 16, v129
	v_and_b32_e32 v129, 0xffff0000, v129
	v_pk_fma_f32 v[142:143], v[128:129], v[128:129], v[142:143]
	v_lshlrev_b32_e32 v146, 16, v122
	v_and_b32_e32 v147, 0xffff0000, v122
	v_pk_fma_f32 v[142:143], v[146:147], v[146:147], v[142:143]
	v_lshlrev_b32_e32 v122, 16, v123
	v_and_b32_e32 v123, 0xffff0000, v123
	v_pk_fma_f32 v[142:143], v[122:123], v[122:123], v[142:143]
	v_lshlrev_b32_e32 v148, 16, v124
	v_and_b32_e32 v149, 0xffff0000, v124
	v_pk_fma_f32 v[142:143], v[148:149], v[148:149], v[142:143]
	v_lshlrev_b32_e32 v124, 16, v125
	v_and_b32_e32 v125, 0xffff0000, v125
	v_pk_fma_f32 v[142:143], v[124:125], v[124:125], v[142:143]
	v_lshlrev_b32_e32 v150, 16, v118
	v_and_b32_e32 v151, 0xffff0000, v118
	v_pk_fma_f32 v[142:143], v[150:151], v[150:151], v[142:143]
	v_lshlrev_b32_e32 v118, 16, v119
	v_and_b32_e32 v119, 0xffff0000, v119
	v_pk_fma_f32 v[142:143], v[118:119], v[118:119], v[142:143]
	v_lshlrev_b32_e32 v152, 16, v120
	v_and_b32_e32 v153, 0xffff0000, v120
	v_pk_fma_f32 v[142:143], v[152:153], v[152:153], v[142:143]
	v_lshlrev_b32_e32 v120, 16, v121
	v_and_b32_e32 v121, 0xffff0000, v121
	v_pk_fma_f32 v[142:143], v[120:121], v[120:121], v[142:143]
	v_lshlrev_b32_e32 v154, 16, v114
	v_and_b32_e32 v155, 0xffff0000, v114
	v_pk_fma_f32 v[142:143], v[154:155], v[154:155], v[142:143]
	v_lshlrev_b32_e32 v114, 16, v115
	v_and_b32_e32 v115, 0xffff0000, v115
	v_pk_fma_f32 v[142:143], v[114:115], v[114:115], v[142:143]
	v_lshlrev_b32_e32 v156, 16, v116
	v_and_b32_e32 v157, 0xffff0000, v116
	v_pk_fma_f32 v[142:143], v[156:157], v[156:157], v[142:143]
	v_lshlrev_b32_e32 v116, 16, v117
	v_and_b32_e32 v117, 0xffff0000, v117
	v_pk_fma_f32 v[142:143], v[116:117], v[116:117], v[142:143]
	v_cvt_f32_f16_sdwa v159, v110 dst_sel:DWORD dst_unused:UNUSED_PAD src0_sel:WORD_1
	v_add_f32_e32 v142, v142, v143
	v_mov_b32_e32 v143, 0
	v_cvt_f32_f16_e32 v158, v110
	v_add_f32_dpp v142, v142, v142 quad_perm:[1,0,3,2] row_mask:0xf bank_mask:0xf bound_ctrl:1
	v_cvt_f32_f16_sdwa v161, v111 dst_sel:DWORD dst_unused:UNUSED_PAD src0_sel:WORD_1
	v_cvt_f32_f16_e32 v160, v111
	v_add_f32_dpp v142, v142, v142 quad_perm:[2,3,0,1] row_mask:0xf bank_mask:0xf bound_ctrl:1
	v_pk_mul_f32 v[110:111], v[6:7], v[140:141]
	v_cvt_f32_f16_sdwa v141, v112 dst_sel:DWORD dst_unused:UNUSED_PAD src0_sel:WORD_1
	v_add_f32_dpp v142, v142, v142 row_half_mirror row_mask:0xf bank_mask:0xf bound_ctrl:1
	v_cvt_f32_f16_e32 v140, v112
	v_pk_mul_f32 v[128:129], v[4:5], v[128:129]
	v_add_f32_dpp v142, v142, v142 row_mirror row_mask:0xf bank_mask:0xf bound_ctrl:1
	v_pk_mul_f32 v[122:123], v[16:17], v[122:123]
	v_pk_mul_f32 v[118:119], v[24:25], v[118:119]
	v_mov_b32_dpp v143, v142 row_bcast:15 row_mask:0xa bank_mask:0xf
	v_add_f32_e32 v142, v142, v143
	v_mov_b32_e32 v143, 0
	v_pk_mul_f32 v[126:127], v[8:9], v[126:127]
	s_nop 0
	v_mov_b32_dpp v143, v142 row_bcast:31 row_mask:0xc bank_mask:0xf
	v_add_f32_e32 v142, v142, v143
	s_nop 0
	v_readlane_b32 s6, v142, 63
	s_nop 1
	v_fma_f32 v142, s6, v137, v136
	v_rsq_f32_e32 v142, v142
	s_nop 0
	v_pk_fma_f32 v[110:111], v[110:111], v[142:143], v[158:159] op_sel_hi:[1,0,1]
	v_cvt_f32_f16_sdwa v159, v113 dst_sel:DWORD dst_unused:UNUSED_PAD src0_sel:WORD_1
	v_cvt_f32_f16_e32 v158, v113
	v_pk_mul_f32 v[112:113], v[2:3], v[144:145]
	v_cvt_f32_f16_sdwa v145, v107 dst_sel:DWORD dst_unused:UNUSED_PAD src0_sel:WORD_1
	v_cvt_f32_f16_e32 v144, v107
	v_pk_fma_f32 v[112:113], v[112:113], v[142:143], v[140:141] op_sel_hi:[1,0,1]
	v_pk_fma_f32 v[140:141], v[128:129], v[142:143], v[158:159] op_sel_hi:[1,0,1]
	v_cvt_f32_f16_sdwa v129, v106 dst_sel:DWORD dst_unused:UNUSED_PAD src0_sel:WORD_1
	v_cvt_f32_f16_e32 v128, v106
	v_pk_mul_f32 v[106:107], v[14:15], v[146:147]
	v_pk_fma_f32 v[144:145], v[122:123], v[142:143], v[144:145] op_sel_hi:[1,0,1]
	v_cvt_f32_f16_sdwa v123, v108 dst_sel:DWORD dst_unused:UNUSED_PAD src0_sel:WORD_1
	v_cvt_f32_f16_e32 v122, v108
	v_pk_fma_f32 v[106:107], v[106:107], v[142:143], v[128:129] op_sel_hi:[1,0,1]
	v_cvt_f32_f16_sdwa v129, v109 dst_sel:DWORD dst_unused:UNUSED_PAD src0_sel:WORD_1
	v_cvt_f32_f16_e32 v128, v109
	v_pk_mul_f32 v[108:109], v[10:11], v[148:149]
	v_pk_fma_f32 v[126:127], v[126:127], v[142:143], v[160:161] op_sel_hi:[1,0,1]
	v_pk_fma_f32 v[108:109], v[108:109], v[142:143], v[122:123] op_sel_hi:[1,0,1]
	v_pk_mul_f32 v[122:123], v[12:13], v[124:125]
	v_cvt_f32_f16_sdwa v125, v103 dst_sel:DWORD dst_unused:UNUSED_PAD src0_sel:WORD_1
	v_cvt_f32_f16_e32 v124, v103
	v_pk_fma_f32 v[146:147], v[122:123], v[142:143], v[128:129] op_sel_hi:[1,0,1]
	v_cvt_f32_f16_sdwa v123, v102 dst_sel:DWORD dst_unused:UNUSED_PAD src0_sel:WORD_1
	v_cvt_f32_f16_e32 v122, v102
	v_pk_mul_f32 v[102:103], v[22:23], v[150:151]
	v_pk_fma_f32 v[148:149], v[118:119], v[142:143], v[124:125] op_sel_hi:[1,0,1]
	v_cvt_f32_f16_sdwa v119, v104 dst_sel:DWORD dst_unused:UNUSED_PAD src0_sel:WORD_1
	v_cvt_f32_f16_e32 v118, v104
	v_pk_fma_f32 v[102:103], v[102:103], v[142:143], v[122:123] op_sel_hi:[1,0,1]
	v_cvt_f32_f16_sdwa v123, v105 dst_sel:DWORD dst_unused:UNUSED_PAD src0_sel:WORD_1
	v_cvt_f32_f16_e32 v122, v105
	v_pk_mul_f32 v[104:105], v[18:19], v[152:153]
	s_nop 0
	v_pk_fma_f32 v[104:105], v[104:105], v[142:143], v[118:119] op_sel_hi:[1,0,1]
	v_pk_mul_f32 v[118:119], v[20:21], v[120:121]
	v_cvt_f32_f16_sdwa v121, v99 dst_sel:DWORD dst_unused:UNUSED_PAD src0_sel:WORD_1
	v_pk_fma_f32 v[150:151], v[118:119], v[142:143], v[122:123] op_sel_hi:[1,0,1]
	v_cvt_f32_f16_sdwa v119, v98 dst_sel:DWORD dst_unused:UNUSED_PAD src0_sel:WORD_1
	v_cvt_f32_f16_e32 v118, v98
	v_cvt_f32_f16_e32 v120, v99
	v_pk_mul_f32 v[98:99], v[30:31], v[154:155]
	s_nop 0
	v_pk_fma_f32 v[152:153], v[98:99], v[142:143], v[118:119] op_sel_hi:[1,0,1]
	v_pk_mul_f32 v[98:99], v[32:33], v[114:115]
	v_cvt_f32_f16_sdwa v115, v101 dst_sel:DWORD dst_unused:UNUSED_PAD src0_sel:WORD_1
	v_pk_fma_f32 v[154:155], v[98:99], v[142:143], v[120:121] op_sel_hi:[1,0,1]
	v_cvt_f32_f16_sdwa v99, v100 dst_sel:DWORD dst_unused:UNUSED_PAD src0_sel:WORD_1
	v_cvt_f32_f16_e32 v98, v100
	v_cvt_f32_f16_e32 v114, v101
	v_pk_mul_f32 v[100:101], v[26:27], v[156:157]
	s_nop 0
	v_pk_fma_f32 v[156:157], v[100:101], v[142:143], v[98:99] op_sel_hi:[1,0,1]
	v_pk_mul_f32 v[98:99], v[28:29], v[116:117]
	v_cvt_pk_f16_f32 v100, v112, v113
	v_pk_fma_f32 v[142:143], v[98:99], v[142:143], v[114:115] op_sel_hi:[1,0,1]
	v_lshl_add_u64 v[114:115], s[94:95], 0, v[132:133]
	v_add_co_u32_e32 v116, vcc, s30, v114
	v_cvt_pk_f16_f32 v98, v110, v111
	v_cvt_pk_f16_f32 v99, v126, v127
	v_cvt_pk_f16_f32 v101, v140, v141
	v_addc_co_u32_e32 v117, vcc, 0, v115, vcc
	global_store_dwordx4 v[116:117], v[98:101], off offset:1024 sc1
	v_add_co_u32_e32 v114, vcc, s31, v114
	s_nop 0
	v_cvt_pk_f16_f32 v98, v106, v107
	v_cvt_pk_f16_f32 v99, v144, v145
	v_cvt_pk_f16_f32 v100, v108, v109
	v_cvt_pk_f16_f32 v101, v146, v147
	global_store_dwordx4 v[116:117], v[98:101], off offset:2048 sc1
	v_addc_co_u32_e32 v115, vcc, 0, v115, vcc
	s_nop 0
	v_cvt_pk_f16_f32 v98, v102, v103
	v_cvt_pk_f16_f32 v99, v148, v149
	v_cvt_pk_f16_f32 v100, v104, v105
	v_cvt_pk_f16_f32 v101, v150, v151
	global_store_dwordx4 v[116:117], v[98:101], off offset:3072 sc1
	v_pk_mul_f32 v[116:117], v[126:127], v[126:127]
	s_nop 0
	v_pk_fma_f32 v[116:117], v[110:111], v[110:111], v[116:117]
	v_cvt_pk_f16_f32 v98, v152, v153
	v_pk_fma_f32 v[116:117], v[112:113], v[112:113], v[116:117]
	v_cvt_pk_f16_f32 v99, v154, v155
	v_pk_fma_f32 v[116:117], v[140:141], v[140:141], v[116:117]
	v_cvt_pk_f16_f32 v100, v156, v157
	v_pk_fma_f32 v[116:117], v[106:107], v[106:107], v[116:117]
	v_cvt_pk_f16_f32 v101, v142, v143
	v_pk_fma_f32 v[116:117], v[144:145], v[144:145], v[116:117]
	global_store_dwordx4 v[114:115], v[98:101], off sc1
	v_pk_fma_f32 v[116:117], v[108:109], v[108:109], v[116:117]
	s_nop 0
	v_pk_fma_f32 v[116:117], v[146:147], v[146:147], v[116:117]
	v_pk_mul_f32 v[98:99], v[40:41], v[126:127]
	v_pk_fma_f32 v[116:117], v[102:103], v[102:103], v[116:117]
	s_nop 0
	v_pk_fma_f32 v[116:117], v[148:149], v[148:149], v[116:117]
	s_nop 0
	v_pk_fma_f32 v[116:117], v[104:105], v[104:105], v[116:117]
	s_nop 0
	v_pk_fma_f32 v[116:117], v[150:151], v[150:151], v[116:117]
	s_nop 0
	v_pk_fma_f32 v[116:117], v[152:153], v[152:153], v[116:117]
	s_nop 0
	v_pk_fma_f32 v[116:117], v[154:155], v[154:155], v[116:117]
	s_nop 0
	v_pk_fma_f32 v[116:117], v[156:157], v[156:157], v[116:117]
	s_nop 0
	v_pk_fma_f32 v[116:117], v[142:143], v[142:143], v[116:117]
	s_nop 0
	v_add_f32_e32 v116, v116, v117
	v_mov_b32_e32 v117, 0
	s_nop 0
	v_add_f32_dpp v116, v116, v116 quad_perm:[1,0,3,2] row_mask:0xf bank_mask:0xf bound_ctrl:1
	s_nop 1
	v_add_f32_dpp v116, v116, v116 quad_perm:[2,3,0,1] row_mask:0xf bank_mask:0xf bound_ctrl:1
	s_nop 1
	v_add_f32_dpp v116, v116, v116 row_half_mirror row_mask:0xf bank_mask:0xf bound_ctrl:1
	s_nop 1
	v_add_f32_dpp v116, v116, v116 row_mirror row_mask:0xf bank_mask:0xf bound_ctrl:1
	s_nop 1
	v_mov_b32_dpp v117, v116 row_bcast:15 row_mask:0xa bank_mask:0xf
	v_add_f32_e32 v116, v116, v117
	v_mov_b32_e32 v117, 0
	s_nop 1
	v_mov_b32_dpp v117, v116 row_bcast:31 row_mask:0xc bank_mask:0xf
	v_add_f32_e32 v116, v116, v117
	s_nop 0
	v_readlane_b32 s6, v116, 63
	s_nop 1
	v_fma_f32 v116, s6, v137, v136
	v_rsq_f32_e32 v158, v116
	s_nop 0
	v_pk_mul_f32 v[122:123], v[98:99], v[158:159] op_sel_hi:[1,0]
	v_pk_mul_f32 v[98:99], v[38:39], v[110:111]
	s_nop 0
	v_pk_mul_f32 v[128:129], v[98:99], v[158:159] op_sel_hi:[1,0]
	v_max_f32_e64 v99, |v122|, |v123|
	v_max_f32_e64 v98, |v128|, |v129|
	v_max3_f32 v100, v98, 0, v99
	v_pk_mul_f32 v[98:99], v[34:35], v[112:113]
	s_nop 0
	v_pk_mul_f32 v[124:125], v[98:99], v[158:159] op_sel_hi:[1,0]
	v_pk_mul_f32 v[98:99], v[36:37], v[140:141]
	v_max_f32_e64 v101, |v124|, |v125|
	v_pk_mul_f32 v[126:127], v[98:99], v[158:159] op_sel_hi:[1,0]
	s_nop 0
	v_max_f32_e64 v98, |v126|, |v127|
	v_max3_f32 v100, v100, v101, v98
	v_pk_mul_f32 v[98:99], v[46:47], v[106:107]
	s_nop 0
	v_pk_mul_f32 v[114:115], v[98:99], v[158:159] op_sel_hi:[1,0]
	v_pk_mul_f32 v[98:99], v[48:49], v[144:145]
	v_max_f32_e64 v101, |v114|, |v115|
	v_pk_mul_f32 v[118:119], v[98:99], v[158:159] op_sel_hi:[1,0]
	s_nop 0
	v_max_f32_e64 v98, |v118|, |v119|
	v_max3_f32 v100, v100, v101, v98
	v_pk_mul_f32 v[98:99], v[42:43], v[108:109]
	s_nop 0
	v_pk_mul_f32 v[116:117], v[98:99], v[158:159] op_sel_hi:[1,0]
	v_pk_mul_f32 v[98:99], v[44:45], v[146:147]
	v_max_f32_e64 v101, |v116|, |v117|
	v_pk_mul_f32 v[120:121], v[98:99], v[158:159] op_sel_hi:[1,0]
	s_nop 0
	v_max_f32_e64 v98, |v120|, |v121|
	v_max3_f32 v100, v100, v101, v98
	v_pk_mul_f32 v[98:99], v[54:55], v[102:103]
	s_nop 0
	v_pk_mul_f32 v[106:107], v[98:99], v[158:159] op_sel_hi:[1,0]
	v_pk_mul_f32 v[98:99], v[56:57], v[148:149]
	v_max_f32_e64 v101, |v106|, |v107|
	v_pk_mul_f32 v[110:111], v[98:99], v[158:159] op_sel_hi:[1,0]
	s_nop 0
	v_max_f32_e64 v98, |v110|, |v111|
	v_max3_f32 v100, v100, v101, v98
	v_pk_mul_f32 v[98:99], v[50:51], v[104:105]
	s_nop 0
	v_pk_mul_f32 v[108:109], v[98:99], v[158:159] op_sel_hi:[1,0]
	v_pk_mul_f32 v[98:99], v[52:53], v[150:151]
	v_max_f32_e64 v101, |v108|, |v109|
	v_pk_mul_f32 v[112:113], v[98:99], v[158:159] op_sel_hi:[1,0]
	s_nop 0
	v_max_f32_e64 v98, |v112|, |v113|
	v_max3_f32 v104, v100, v101, v98
	s_waitcnt vmcnt(4)
	v_pk_mul_f32 v[98:99], v[62:63], v[152:153]
	v_pk_mul_f32 v[100:101], v[64:65], v[154:155]
	v_pk_mul_f32 v[98:99], v[98:99], v[158:159] op_sel_hi:[1,0]
	v_pk_mul_f32 v[102:103], v[100:101], v[158:159] op_sel_hi:[1,0]
	v_max_f32_e64 v105, |v98|, |v99|
	v_max_f32_e64 v100, |v102|, |v103|
	v_max3_f32 v140, v104, v105, v100
	v_pk_mul_f32 v[100:101], v[58:59], v[156:157]
	v_pk_mul_f32 v[104:105], v[60:61], v[142:143]
	v_pk_mul_f32 v[100:101], v[100:101], v[158:159] op_sel_hi:[1,0]
	v_pk_mul_f32 v[104:105], v[104:105], v[158:159] op_sel_hi:[1,0]
	v_max_f32_e64 v141, |v100|, |v101|
	v_max_f32_e64 v142, |v104|, |v105|
	v_max3_f32 v140, v140, v141, v142
	v_mov_b32_e32 v141, 0
	s_nop 1
	v_mov_b32_dpp v141, v140 quad_perm:[1,0,3,2] row_mask:0xf bank_mask:0xf
	v_max_f32_e32 v141, v141, v141
	v_max_f32_e32 v140, v140, v141
	v_mov_b32_e32 v141, 0
	s_nop 1
	v_mov_b32_dpp v141, v140 quad_perm:[2,3,0,1] row_mask:0xf bank_mask:0xf
	v_max_f32_e32 v141, v141, v141
	v_max_f32_e32 v140, v140, v141
	v_mov_b32_e32 v141, 0
	s_nop 1
	v_mov_b32_dpp v141, v140 row_half_mirror row_mask:0xf bank_mask:0xf
	v_max_f32_e32 v141, v141, v141
	v_max_f32_e32 v140, v140, v141
	v_mov_b32_e32 v141, 0
	s_nop 1
	v_mov_b32_dpp v141, v140 row_mirror row_mask:0xf bank_mask:0xf
	v_max_f32_e32 v141, v141, v141
	v_max_f32_e32 v140, v140, v141
	v_mov_b32_e32 v141, 0
	s_nop 1
	v_mov_b32_dpp v141, v140 row_bcast:15 row_mask:0xa bank_mask:0xf
	v_max_f32_e32 v141, v141, v141
	v_max_f32_e32 v140, v140, v141
	v_mov_b32_e32 v141, 0
	s_nop 1
	v_mov_b32_dpp v141, v140 row_bcast:31 row_mask:0xc bank_mask:0xf
	v_max_f32_e32 v141, v141, v141
	v_max_f32_e32 v140, v140, v141
	s_nop 0
	v_readlane_b32 s17, v140, 63
	s_nop 1
	v_cmp_gt_f32_e64 s[6:7], s17, 0
	s_and_saveexec_b64 s[28:29], s[4:5]
	s_cbranch_execz .LBB0_1496
	v_mul_f32_e32 v140, s17, v138
	s_add_u32 s40, s94, s15
	v_cndmask_b32_e64 v140, 1.0, v140, s[6:7]
	s_addc_u32 s41, s95, s39
	global_store_dword v1, v140, s[40:41]
	s_branch .LBB0_1496

.LBB0_1770:
	v_lshlrev_b32_e32 v140, 16, v126
	v_and_b32_e32 v141, 0xffff0000, v126
	v_lshlrev_b32_e32 v126, 16, v127
	v_and_b32_e32 v127, 0xffff0000, v127
	v_pk_mul_f32 v[142:143], v[126:127], v[126:127]
	v_lshlrev_b32_e32 v144, 16, v128
	v_pk_fma_f32 v[142:143], v[140:141], v[140:141], v[142:143]
	v_and_b32_e32 v145, 0xffff0000, v128
	v_pk_fma_f32 v[142:143], v[144:145], v[144:145], v[142:143]
	v_lshlrev_b32_e32 v128, 16, v129
	v_and_b32_e32 v129, 0xffff0000, v129
	v_pk_fma_f32 v[142:143], v[128:129], v[128:129], v[142:143]
	v_lshlrev_b32_e32 v146, 16, v122
	v_and_b32_e32 v147, 0xffff0000, v122
	v_pk_fma_f32 v[142:143], v[146:147], v[146:147], v[142:143]
	v_lshlrev_b32_e32 v122, 16, v123
	v_and_b32_e32 v123, 0xffff0000, v123
	v_pk_fma_f32 v[142:143], v[122:123], v[122:123], v[142:143]
	v_lshlrev_b32_e32 v148, 16, v124
	v_and_b32_e32 v149, 0xffff0000, v124
	v_pk_fma_f32 v[142:143], v[148:149], v[148:149], v[142:143]
	v_lshlrev_b32_e32 v124, 16, v125
	v_and_b32_e32 v125, 0xffff0000, v125
	v_pk_fma_f32 v[142:143], v[124:125], v[124:125], v[142:143]
	v_lshlrev_b32_e32 v150, 16, v118
	v_and_b32_e32 v151, 0xffff0000, v118
	v_pk_fma_f32 v[142:143], v[150:151], v[150:151], v[142:143]
	v_lshlrev_b32_e32 v118, 16, v119
	v_and_b32_e32 v119, 0xffff0000, v119
	v_pk_fma_f32 v[142:143], v[118:119], v[118:119], v[142:143]
	v_lshlrev_b32_e32 v152, 16, v120
	v_and_b32_e32 v153, 0xffff0000, v120
	v_pk_fma_f32 v[142:143], v[152:153], v[152:153], v[142:143]
	v_lshlrev_b32_e32 v120, 16, v121
	v_and_b32_e32 v121, 0xffff0000, v121
	v_pk_fma_f32 v[142:143], v[120:121], v[120:121], v[142:143]
	v_lshlrev_b32_e32 v154, 16, v114
	v_and_b32_e32 v155, 0xffff0000, v114
	v_pk_fma_f32 v[142:143], v[154:155], v[154:155], v[142:143]
	v_lshlrev_b32_e32 v114, 16, v115
	v_and_b32_e32 v115, 0xffff0000, v115
	v_pk_fma_f32 v[142:143], v[114:115], v[114:115], v[142:143]
	v_lshlrev_b32_e32 v156, 16, v116
	v_and_b32_e32 v157, 0xffff0000, v116
	v_pk_fma_f32 v[142:143], v[156:157], v[156:157], v[142:143]
	v_lshlrev_b32_e32 v116, 16, v117
	v_and_b32_e32 v117, 0xffff0000, v117
	v_pk_fma_f32 v[142:143], v[116:117], v[116:117], v[142:143]
	v_cvt_f32_f16_sdwa v159, v110 dst_sel:DWORD dst_unused:UNUSED_PAD src0_sel:WORD_1
	v_add_f32_e32 v142, v142, v143
	v_mov_b32_e32 v143, 0
	v_cvt_f32_f16_e32 v158, v110
	v_add_f32_dpp v142, v142, v142 quad_perm:[1,0,3,2] row_mask:0xf bank_mask:0xf bound_ctrl:1
	v_cvt_f32_f16_sdwa v161, v111 dst_sel:DWORD dst_unused:UNUSED_PAD src0_sel:WORD_1
	v_cvt_f32_f16_e32 v160, v111
	v_add_f32_dpp v142, v142, v142 quad_perm:[2,3,0,1] row_mask:0xf bank_mask:0xf bound_ctrl:1
	v_pk_mul_f32 v[110:111], v[6:7], v[140:141]
	v_cvt_f32_f16_sdwa v141, v112 dst_sel:DWORD dst_unused:UNUSED_PAD src0_sel:WORD_1
	v_add_f32_dpp v142, v142, v142 row_half_mirror row_mask:0xf bank_mask:0xf bound_ctrl:1
	v_cvt_f32_f16_e32 v140, v112
	v_pk_mul_f32 v[128:129], v[4:5], v[128:129]
	v_add_f32_dpp v142, v142, v142 row_mirror row_mask:0xf bank_mask:0xf bound_ctrl:1
	v_pk_mul_f32 v[122:123], v[16:17], v[122:123]
	v_pk_mul_f32 v[118:119], v[24:25], v[118:119]
	v_mov_b32_dpp v143, v142 row_bcast:15 row_mask:0xa bank_mask:0xf
	v_add_f32_e32 v142, v142, v143
	v_mov_b32_e32 v143, 0
	v_pk_mul_f32 v[126:127], v[8:9], v[126:127]
	s_nop 0
	v_mov_b32_dpp v143, v142 row_bcast:31 row_mask:0xc bank_mask:0xf
	v_add_f32_e32 v142, v142, v143
	s_nop 0
	v_readlane_b32 s6, v142, 63
	s_nop 1
	v_fma_f32 v142, s6, v137, v136
	v_rsq_f32_e32 v142, v142
	s_nop 0
	v_mul_f32_e32 v142, 0.5, v142
	v_pk_fma_f32 v[110:111], v[110:111], v[142:143], v[158:159] op_sel_hi:[1,0,1]
	v_cvt_f32_f16_sdwa v159, v113 dst_sel:DWORD dst_unused:UNUSED_PAD src0_sel:WORD_1
	v_cvt_f32_f16_e32 v158, v113
	v_pk_mul_f32 v[112:113], v[2:3], v[144:145]
	v_cvt_f32_f16_sdwa v145, v107 dst_sel:DWORD dst_unused:UNUSED_PAD src0_sel:WORD_1
	v_cvt_f32_f16_e32 v144, v107
	v_pk_fma_f32 v[112:113], v[112:113], v[142:143], v[140:141] op_sel_hi:[1,0,1]
	v_pk_fma_f32 v[140:141], v[128:129], v[142:143], v[158:159] op_sel_hi:[1,0,1]
	v_cvt_f32_f16_sdwa v129, v106 dst_sel:DWORD dst_unused:UNUSED_PAD src0_sel:WORD_1
	v_cvt_f32_f16_e32 v128, v106
	v_pk_mul_f32 v[106:107], v[14:15], v[146:147]
	v_pk_fma_f32 v[144:145], v[122:123], v[142:143], v[144:145] op_sel_hi:[1,0,1]
	v_cvt_f32_f16_sdwa v123, v108 dst_sel:DWORD dst_unused:UNUSED_PAD src0_sel:WORD_1
	v_cvt_f32_f16_e32 v122, v108
	v_pk_fma_f32 v[106:107], v[106:107], v[142:143], v[128:129] op_sel_hi:[1,0,1]
	v_cvt_f32_f16_sdwa v129, v109 dst_sel:DWORD dst_unused:UNUSED_PAD src0_sel:WORD_1
	v_cvt_f32_f16_e32 v128, v109
	v_pk_mul_f32 v[108:109], v[10:11], v[148:149]
	v_pk_fma_f32 v[126:127], v[126:127], v[142:143], v[160:161] op_sel_hi:[1,0,1]
	v_pk_fma_f32 v[108:109], v[108:109], v[142:143], v[122:123] op_sel_hi:[1,0,1]
	v_pk_mul_f32 v[122:123], v[12:13], v[124:125]
	v_cvt_f32_f16_sdwa v125, v103 dst_sel:DWORD dst_unused:UNUSED_PAD src0_sel:WORD_1
	v_cvt_f32_f16_e32 v124, v103
	v_pk_fma_f32 v[146:147], v[122:123], v[142:143], v[128:129] op_sel_hi:[1,0,1]
	v_cvt_f32_f16_sdwa v123, v102 dst_sel:DWORD dst_unused:UNUSED_PAD src0_sel:WORD_1
	v_cvt_f32_f16_e32 v122, v102
	v_pk_mul_f32 v[102:103], v[22:23], v[150:151]
	v_pk_fma_f32 v[148:149], v[118:119], v[142:143], v[124:125] op_sel_hi:[1,0,1]
	v_cvt_f32_f16_sdwa v119, v104 dst_sel:DWORD dst_unused:UNUSED_PAD src0_sel:WORD_1
	v_cvt_f32_f16_e32 v118, v104
	v_pk_fma_f32 v[102:103], v[102:103], v[142:143], v[122:123] op_sel_hi:[1,0,1]
	v_cvt_f32_f16_sdwa v123, v105 dst_sel:DWORD dst_unused:UNUSED_PAD src0_sel:WORD_1
	v_cvt_f32_f16_e32 v122, v105
	v_pk_mul_f32 v[104:105], v[18:19], v[152:153]
	s_nop 0
	v_pk_fma_f32 v[104:105], v[104:105], v[142:143], v[118:119] op_sel_hi:[1,0,1]
	v_pk_mul_f32 v[118:119], v[20:21], v[120:121]
	v_cvt_f32_f16_sdwa v121, v99 dst_sel:DWORD dst_unused:UNUSED_PAD src0_sel:WORD_1
	v_pk_fma_f32 v[150:151], v[118:119], v[142:143], v[122:123] op_sel_hi:[1,0,1]
	v_cvt_f32_f16_sdwa v119, v98 dst_sel:DWORD dst_unused:UNUSED_PAD src0_sel:WORD_1
	v_cvt_f32_f16_e32 v118, v98
	v_cvt_f32_f16_e32 v120, v99
	v_pk_mul_f32 v[98:99], v[30:31], v[154:155]
	s_nop 0
	v_pk_fma_f32 v[152:153], v[98:99], v[142:143], v[118:119] op_sel_hi:[1,0,1]
	v_pk_mul_f32 v[98:99], v[32:33], v[114:115]
	v_cvt_f32_f16_sdwa v115, v101 dst_sel:DWORD dst_unused:UNUSED_PAD src0_sel:WORD_1
	v_pk_fma_f32 v[154:155], v[98:99], v[142:143], v[120:121] op_sel_hi:[1,0,1]
	v_cvt_f32_f16_sdwa v99, v100 dst_sel:DWORD dst_unused:UNUSED_PAD src0_sel:WORD_1
	v_cvt_f32_f16_e32 v98, v100
	v_cvt_f32_f16_e32 v114, v101
	v_pk_mul_f32 v[100:101], v[26:27], v[156:157]
	s_nop 0
	v_pk_fma_f32 v[156:157], v[100:101], v[142:143], v[98:99] op_sel_hi:[1,0,1]
	v_pk_mul_f32 v[98:99], v[28:29], v[116:117]
	v_cvt_pk_f16_f32 v100, v112, v113
	v_pk_fma_f32 v[142:143], v[98:99], v[142:143], v[114:115] op_sel_hi:[1,0,1]
	v_lshl_add_u64 v[114:115], s[94:95], 0, v[132:133]
	v_add_co_u32_e32 v116, vcc, s30, v114
	v_cvt_pk_f16_f32 v98, v110, v111
	v_cvt_pk_f16_f32 v99, v126, v127
	v_cvt_pk_f16_f32 v101, v140, v141
	v_addc_co_u32_e32 v117, vcc, 0, v115, vcc
	global_store_dwordx4 v[116:117], v[98:101], off offset:1024 sc1
	v_add_co_u32_e32 v114, vcc, s31, v114
	s_nop 0
	v_cvt_pk_f16_f32 v98, v106, v107
	v_cvt_pk_f16_f32 v99, v144, v145
	v_cvt_pk_f16_f32 v100, v108, v109
	v_cvt_pk_f16_f32 v101, v146, v147
	global_store_dwordx4 v[116:117], v[98:101], off offset:2048 sc1
	v_addc_co_u32_e32 v115, vcc, 0, v115, vcc
	s_nop 0
	v_cvt_pk_f16_f32 v98, v102, v103
	v_cvt_pk_f16_f32 v99, v148, v149
	v_cvt_pk_f16_f32 v100, v104, v105
	v_cvt_pk_f16_f32 v101, v150, v151
	global_store_dwordx4 v[116:117], v[98:101], off offset:3072 sc1
	v_pk_mul_f32 v[116:117], v[126:127], v[126:127]
	s_nop 0
	v_pk_fma_f32 v[116:117], v[110:111], v[110:111], v[116:117]
	v_cvt_pk_f16_f32 v98, v152, v153
	v_pk_fma_f32 v[116:117], v[112:113], v[112:113], v[116:117]
	v_cvt_pk_f16_f32 v99, v154, v155
	v_pk_fma_f32 v[116:117], v[140:141], v[140:141], v[116:117]
	v_cvt_pk_f16_f32 v100, v156, v157
	v_pk_fma_f32 v[116:117], v[106:107], v[106:107], v[116:117]
	v_cvt_pk_f16_f32 v101, v142, v143
	v_pk_fma_f32 v[116:117], v[144:145], v[144:145], v[116:117]
	global_store_dwordx4 v[114:115], v[98:101], off sc1
	v_pk_fma_f32 v[116:117], v[108:109], v[108:109], v[116:117]
	s_nop 0
	v_pk_fma_f32 v[116:117], v[146:147], v[146:147], v[116:117]
	v_pk_mul_f32 v[98:99], v[40:41], v[126:127]
	v_pk_fma_f32 v[116:117], v[102:103], v[102:103], v[116:117]
	s_nop 0
	v_pk_fma_f32 v[116:117], v[148:149], v[148:149], v[116:117]
	s_nop 0
	v_pk_fma_f32 v[116:117], v[104:105], v[104:105], v[116:117]
	s_nop 0
	v_pk_fma_f32 v[116:117], v[150:151], v[150:151], v[116:117]
	s_nop 0
	v_pk_fma_f32 v[116:117], v[152:153], v[152:153], v[116:117]
	s_nop 0
	v_pk_fma_f32 v[116:117], v[154:155], v[154:155], v[116:117]
	s_nop 0
	v_pk_fma_f32 v[116:117], v[156:157], v[156:157], v[116:117]
	s_nop 0
	v_pk_fma_f32 v[116:117], v[142:143], v[142:143], v[116:117]
	s_nop 0
	v_add_f32_e32 v116, v116, v117
	v_mov_b32_e32 v117, 0
	s_nop 0
	v_add_f32_dpp v116, v116, v116 quad_perm:[1,0,3,2] row_mask:0xf bank_mask:0xf bound_ctrl:1
	s_nop 1
	v_add_f32_dpp v116, v116, v116 quad_perm:[2,3,0,1] row_mask:0xf bank_mask:0xf bound_ctrl:1
	s_nop 1
	v_add_f32_dpp v116, v116, v116 row_half_mirror row_mask:0xf bank_mask:0xf bound_ctrl:1
	s_nop 1
	v_add_f32_dpp v116, v116, v116 row_mirror row_mask:0xf bank_mask:0xf bound_ctrl:1
	s_nop 1
	v_mov_b32_dpp v117, v116 row_bcast:15 row_mask:0xa bank_mask:0xf
	v_add_f32_e32 v116, v116, v117
	v_mov_b32_e32 v117, 0
	s_nop 1
	v_mov_b32_dpp v117, v116 row_bcast:31 row_mask:0xc bank_mask:0xf
	v_add_f32_e32 v116, v116, v117
	s_nop 0
	v_readlane_b32 s6, v116, 63
	s_nop 1
	v_fma_f32 v116, s6, v137, v136
	v_rsq_f32_e32 v158, v116
	s_nop 0
	v_pk_mul_f32 v[122:123], v[98:99], v[158:159] op_sel_hi:[1,0]
	v_pk_mul_f32 v[98:99], v[38:39], v[110:111]
	s_nop 0
	v_pk_mul_f32 v[128:129], v[98:99], v[158:159] op_sel_hi:[1,0]
	v_max_f32_e64 v99, |v122|, |v123|
	v_max_f32_e64 v98, |v128|, |v129|
	v_max3_f32 v100, v98, 0, v99
	v_pk_mul_f32 v[98:99], v[34:35], v[112:113]
	s_nop 0
	v_pk_mul_f32 v[124:125], v[98:99], v[158:159] op_sel_hi:[1,0]
	v_pk_mul_f32 v[98:99], v[36:37], v[140:141]
	v_max_f32_e64 v101, |v124|, |v125|
	v_pk_mul_f32 v[126:127], v[98:99], v[158:159] op_sel_hi:[1,0]
	s_nop 0
	v_max_f32_e64 v98, |v126|, |v127|
	v_max3_f32 v100, v100, v101, v98
	v_pk_mul_f32 v[98:99], v[46:47], v[106:107]
	s_nop 0
	v_pk_mul_f32 v[114:115], v[98:99], v[158:159] op_sel_hi:[1,0]
	v_pk_mul_f32 v[98:99], v[48:49], v[144:145]
	v_max_f32_e64 v101, |v114|, |v115|
	v_pk_mul_f32 v[118:119], v[98:99], v[158:159] op_sel_hi:[1,0]
	s_nop 0
	v_max_f32_e64 v98, |v118|, |v119|
	v_max3_f32 v100, v100, v101, v98
	v_pk_mul_f32 v[98:99], v[42:43], v[108:109]
	s_nop 0
	v_pk_mul_f32 v[116:117], v[98:99], v[158:159] op_sel_hi:[1,0]
	v_pk_mul_f32 v[98:99], v[44:45], v[146:147]
	v_max_f32_e64 v101, |v116|, |v117|
	v_pk_mul_f32 v[120:121], v[98:99], v[158:159] op_sel_hi:[1,0]
	s_nop 0
	v_max_f32_e64 v98, |v120|, |v121|
	v_max3_f32 v100, v100, v101, v98
	v_pk_mul_f32 v[98:99], v[54:55], v[102:103]
	s_nop 0
	v_pk_mul_f32 v[106:107], v[98:99], v[158:159] op_sel_hi:[1,0]
	v_pk_mul_f32 v[98:99], v[56:57], v[148:149]
	v_max_f32_e64 v101, |v106|, |v107|
	v_pk_mul_f32 v[110:111], v[98:99], v[158:159] op_sel_hi:[1,0]
	s_nop 0
	v_max_f32_e64 v98, |v110|, |v111|
	v_max3_f32 v100, v100, v101, v98
	v_pk_mul_f32 v[98:99], v[50:51], v[104:105]
	s_nop 0
	v_pk_mul_f32 v[108:109], v[98:99], v[158:159] op_sel_hi:[1,0]
	v_pk_mul_f32 v[98:99], v[52:53], v[150:151]
	v_max_f32_e64 v101, |v108|, |v109|
	v_pk_mul_f32 v[112:113], v[98:99], v[158:159] op_sel_hi:[1,0]
	s_nop 0
	v_max_f32_e64 v98, |v112|, |v113|
	v_max3_f32 v104, v100, v101, v98
	s_waitcnt vmcnt(4)
	v_pk_mul_f32 v[98:99], v[62:63], v[152:153]
	v_pk_mul_f32 v[100:101], v[64:65], v[154:155]
	v_pk_mul_f32 v[98:99], v[98:99], v[158:159] op_sel_hi:[1,0]
	v_pk_mul_f32 v[102:103], v[100:101], v[158:159] op_sel_hi:[1,0]
	v_max_f32_e64 v105, |v98|, |v99|
	v_max_f32_e64 v100, |v102|, |v103|
	v_max3_f32 v140, v104, v105, v100
	v_pk_mul_f32 v[100:101], v[58:59], v[156:157]
	v_pk_mul_f32 v[104:105], v[60:61], v[142:143]
	v_pk_mul_f32 v[100:101], v[100:101], v[158:159] op_sel_hi:[1,0]
	v_pk_mul_f32 v[104:105], v[104:105], v[158:159] op_sel_hi:[1,0]
	v_max_f32_e64 v141, |v100|, |v101|
	v_max_f32_e64 v142, |v104|, |v105|
	v_max3_f32 v140, v140, v141, v142
	v_mov_b32_e32 v141, 0
	s_nop 1
	v_mov_b32_dpp v141, v140 quad_perm:[1,0,3,2] row_mask:0xf bank_mask:0xf
	v_max_f32_e32 v141, v141, v141
	v_max_f32_e32 v140, v140, v141
	v_mov_b32_e32 v141, 0
	s_nop 1
	v_mov_b32_dpp v141, v140 quad_perm:[2,3,0,1] row_mask:0xf bank_mask:0xf
	v_max_f32_e32 v141, v141, v141
	v_max_f32_e32 v140, v140, v141
	v_mov_b32_e32 v141, 0
	s_nop 1
	v_mov_b32_dpp v141, v140 row_half_mirror row_mask:0xf bank_mask:0xf
	v_max_f32_e32 v141, v141, v141
	v_max_f32_e32 v140, v140, v141
	v_mov_b32_e32 v141, 0
	s_nop 1
	v_mov_b32_dpp v141, v140 row_mirror row_mask:0xf bank_mask:0xf
	v_max_f32_e32 v141, v141, v141
	v_max_f32_e32 v140, v140, v141
	v_mov_b32_e32 v141, 0
	s_nop 1
	v_mov_b32_dpp v141, v140 row_bcast:15 row_mask:0xa bank_mask:0xf
	v_max_f32_e32 v141, v141, v141
	v_max_f32_e32 v140, v140, v141
	v_mov_b32_e32 v141, 0
	s_nop 1
	v_mov_b32_dpp v141, v140 row_bcast:31 row_mask:0xc bank_mask:0xf
	v_max_f32_e32 v141, v141, v141
	v_max_f32_e32 v140, v140, v141
	s_nop 0
	v_readlane_b32 s17, v140, 63
	s_nop 1
	v_cmp_gt_f32_e64 s[6:7], s17, 0
	s_and_saveexec_b64 s[28:29], s[4:5]
	s_cbranch_execz .LBB0_1767
	v_mul_f32_e32 v140, s17, v138
	s_add_u32 s40, s94, s15
	v_cndmask_b32_e64 v140, 1.0, v140, s[6:7]
	s_addc_u32 s41, s95, s39
	global_store_dword v1, v140, s[40:41]
	s_branch .LBB0_1767

.LBB0_2038:
	v_lshlrev_b32_e32 v134, 16, v126
	v_and_b32_e32 v135, 0xffff0000, v126
	v_lshlrev_b32_e32 v126, 16, v127
	v_and_b32_e32 v127, 0xffff0000, v127
	v_pk_mul_f32 v[136:137], v[126:127], v[126:127]
	v_lshlrev_b32_e32 v138, 16, v128
	v_pk_fma_f32 v[136:137], v[134:135], v[134:135], v[136:137]
	v_and_b32_e32 v139, 0xffff0000, v128
	v_pk_fma_f32 v[136:137], v[138:139], v[138:139], v[136:137]
	v_lshlrev_b32_e32 v128, 16, v129
	v_and_b32_e32 v129, 0xffff0000, v129
	v_pk_fma_f32 v[136:137], v[128:129], v[128:129], v[136:137]
	v_lshlrev_b32_e32 v140, 16, v122
	v_and_b32_e32 v141, 0xffff0000, v122
	v_pk_fma_f32 v[136:137], v[140:141], v[140:141], v[136:137]
	v_lshlrev_b32_e32 v122, 16, v123
	v_and_b32_e32 v123, 0xffff0000, v123
	v_pk_fma_f32 v[136:137], v[122:123], v[122:123], v[136:137]
	v_lshlrev_b32_e32 v142, 16, v124
	v_and_b32_e32 v143, 0xffff0000, v124
	v_pk_fma_f32 v[136:137], v[142:143], v[142:143], v[136:137]
	v_lshlrev_b32_e32 v124, 16, v125
	v_and_b32_e32 v125, 0xffff0000, v125
	v_pk_fma_f32 v[136:137], v[124:125], v[124:125], v[136:137]
	v_lshlrev_b32_e32 v144, 16, v118
	v_and_b32_e32 v145, 0xffff0000, v118
	v_pk_fma_f32 v[136:137], v[144:145], v[144:145], v[136:137]
	v_lshlrev_b32_e32 v118, 16, v119
	v_and_b32_e32 v119, 0xffff0000, v119
	v_pk_fma_f32 v[136:137], v[118:119], v[118:119], v[136:137]
	v_lshlrev_b32_e32 v146, 16, v120
	v_and_b32_e32 v147, 0xffff0000, v120
	v_pk_fma_f32 v[136:137], v[146:147], v[146:147], v[136:137]
	v_lshlrev_b32_e32 v120, 16, v121
	v_and_b32_e32 v121, 0xffff0000, v121
	v_pk_fma_f32 v[136:137], v[120:121], v[120:121], v[136:137]
	v_lshlrev_b32_e32 v148, 16, v114
	v_and_b32_e32 v149, 0xffff0000, v114
	v_pk_fma_f32 v[136:137], v[148:149], v[148:149], v[136:137]
	v_lshlrev_b32_e32 v114, 16, v115
	v_and_b32_e32 v115, 0xffff0000, v115
	v_pk_fma_f32 v[136:137], v[114:115], v[114:115], v[136:137]
	v_lshlrev_b32_e32 v150, 16, v116
	v_and_b32_e32 v151, 0xffff0000, v116
	v_pk_fma_f32 v[136:137], v[150:151], v[150:151], v[136:137]
	v_lshlrev_b32_e32 v116, 16, v117
	v_and_b32_e32 v117, 0xffff0000, v117
	v_pk_fma_f32 v[136:137], v[116:117], v[116:117], v[136:137]
	v_cvt_f32_f16_sdwa v153, v110 dst_sel:DWORD dst_unused:UNUSED_PAD src0_sel:WORD_1
	v_add_f32_e32 v133, v136, v137
	v_mov_b32_e32 v136, 0
	v_cvt_f32_f16_e32 v152, v110
	v_add_f32_dpp v133, v133, v133 quad_perm:[1,0,3,2] row_mask:0xf bank_mask:0xf bound_ctrl:1
	v_cvt_f32_f16_sdwa v155, v111 dst_sel:DWORD dst_unused:UNUSED_PAD src0_sel:WORD_1
	v_cvt_f32_f16_e32 v154, v111
	v_add_f32_dpp v133, v133, v133 quad_perm:[2,3,0,1] row_mask:0xf bank_mask:0xf bound_ctrl:1
	v_pk_mul_f32 v[110:111], v[6:7], v[134:135]
	v_cvt_f32_f16_sdwa v135, v112 dst_sel:DWORD dst_unused:UNUSED_PAD src0_sel:WORD_1
	v_add_f32_dpp v133, v133, v133 row_half_mirror row_mask:0xf bank_mask:0xf bound_ctrl:1
	v_cvt_f32_f16_e32 v134, v112
	v_pk_mul_f32 v[122:123], v[16:17], v[122:123]
	v_add_f32_dpp v133, v133, v133 row_mirror row_mask:0xf bank_mask:0xf bound_ctrl:1
	v_pk_mul_f32 v[124:125], v[12:13], v[124:125]
	v_pk_mul_f32 v[126:127], v[8:9], v[126:127]
	v_mov_b32_dpp v136, v133 row_bcast:15 row_mask:0xa bank_mask:0xf
	v_add_f32_e32 v133, v133, v136
	v_mov_b32_e32 v136, 0
	v_pk_mul_f32 v[118:119], v[24:25], v[118:119]
	v_pk_mul_f32 v[128:129], v[4:5], v[128:129]
	v_mov_b32_dpp v136, v133 row_bcast:31 row_mask:0xc bank_mask:0xf
	v_add_f32_e32 v133, v133, v136
	v_pk_mul_f32 v[120:121], v[20:21], v[120:121]
	v_readlane_b32 s13, v133, 63
	s_nop 1
	v_fma_f32 v133, s13, v132, v1
	v_rsq_f32_e32 v133, v133
	s_nop 0
	v_mul_f32_e32 v136, 0.5, v133
	v_pk_fma_f32 v[110:111], v[110:111], v[136:137], v[152:153] op_sel_hi:[1,0,1]
	v_cvt_f32_f16_sdwa v153, v113 dst_sel:DWORD dst_unused:UNUSED_PAD src0_sel:WORD_1
	v_cvt_f32_f16_e32 v152, v113
	v_pk_mul_f32 v[112:113], v[2:3], v[138:139]
	v_cvt_f32_f16_sdwa v139, v107 dst_sel:DWORD dst_unused:UNUSED_PAD src0_sel:WORD_1
	v_pk_fma_f32 v[112:113], v[112:113], v[136:137], v[134:135] op_sel_hi:[1,0,1]
	v_cvt_f32_f16_sdwa v135, v106 dst_sel:DWORD dst_unused:UNUSED_PAD src0_sel:WORD_1
	v_cvt_f32_f16_e32 v134, v106
	v_cvt_f32_f16_e32 v138, v107
	v_pk_mul_f32 v[106:107], v[14:15], v[140:141]
	v_pk_fma_f32 v[126:127], v[126:127], v[136:137], v[154:155] op_sel_hi:[1,0,1]
	v_pk_fma_f32 v[106:107], v[106:107], v[136:137], v[134:135] op_sel_hi:[1,0,1]
	v_cvt_f32_f16_sdwa v135, v108 dst_sel:DWORD dst_unused:UNUSED_PAD src0_sel:WORD_1
	v_cvt_f32_f16_e32 v134, v108
	v_pk_fma_f32 v[122:123], v[122:123], v[136:137], v[138:139] op_sel_hi:[1,0,1]
	v_cvt_f32_f16_sdwa v139, v109 dst_sel:DWORD dst_unused:UNUSED_PAD src0_sel:WORD_1
	v_cvt_f32_f16_e32 v138, v109
	v_pk_mul_f32 v[108:109], v[10:11], v[142:143]
	v_pk_mul_f32 v[142:143], v[126:127], v[126:127]
	v_pk_fma_f32 v[108:109], v[108:109], v[136:137], v[134:135] op_sel_hi:[1,0,1]
	v_cvt_f32_f16_sdwa v135, v102 dst_sel:DWORD dst_unused:UNUSED_PAD src0_sel:WORD_1
	v_cvt_f32_f16_e32 v134, v102
	v_pk_fma_f32 v[124:125], v[124:125], v[136:137], v[138:139] op_sel_hi:[1,0,1]
	v_cvt_f32_f16_sdwa v139, v103 dst_sel:DWORD dst_unused:UNUSED_PAD src0_sel:WORD_1
	v_cvt_f32_f16_e32 v138, v103
	v_pk_mul_f32 v[102:103], v[22:23], v[144:145]
	v_pk_fma_f32 v[142:143], v[110:111], v[110:111], v[142:143]
	v_pk_fma_f32 v[102:103], v[102:103], v[136:137], v[134:135] op_sel_hi:[1,0,1]
	v_cvt_f32_f16_sdwa v135, v104 dst_sel:DWORD dst_unused:UNUSED_PAD src0_sel:WORD_1
	v_cvt_f32_f16_e32 v134, v104
	v_pk_fma_f32 v[118:119], v[118:119], v[136:137], v[138:139] op_sel_hi:[1,0,1]
	v_cvt_f32_f16_sdwa v139, v105 dst_sel:DWORD dst_unused:UNUSED_PAD src0_sel:WORD_1
	v_cvt_f32_f16_e32 v138, v105
	v_pk_fma_f32 v[128:129], v[128:129], v[136:137], v[152:153] op_sel_hi:[1,0,1]
	v_pk_fma_f32 v[142:143], v[112:113], v[112:113], v[142:143]
	v_pk_mul_f32 v[104:105], v[18:19], v[146:147]
	v_pk_fma_f32 v[142:143], v[128:129], v[128:129], v[142:143]
	v_pk_fma_f32 v[104:105], v[104:105], v[136:137], v[134:135] op_sel_hi:[1,0,1]
	v_cvt_f32_f16_sdwa v135, v98 dst_sel:DWORD dst_unused:UNUSED_PAD src0_sel:WORD_1
	v_cvt_f32_f16_e32 v134, v98
	v_pk_fma_f32 v[142:143], v[106:107], v[106:107], v[142:143]
	v_pk_fma_f32 v[120:121], v[120:121], v[136:137], v[138:139] op_sel_hi:[1,0,1]
	v_cvt_f32_f16_sdwa v139, v99 dst_sel:DWORD dst_unused:UNUSED_PAD src0_sel:WORD_1
	v_cvt_f32_f16_e32 v138, v99
	v_pk_fma_f32 v[142:143], v[122:123], v[122:123], v[142:143]
	v_pk_mul_f32 v[98:99], v[30:31], v[148:149]
	v_pk_fma_f32 v[142:143], v[108:109], v[108:109], v[142:143]
	v_pk_fma_f32 v[134:135], v[98:99], v[136:137], v[134:135] op_sel_hi:[1,0,1]
	v_pk_fma_f32 v[142:143], v[124:125], v[124:125], v[142:143]
	v_pk_mul_f32 v[98:99], v[32:33], v[114:115]
	v_pk_fma_f32 v[142:143], v[102:103], v[102:103], v[142:143]
	v_pk_fma_f32 v[114:115], v[98:99], v[136:137], v[138:139] op_sel_hi:[1,0,1]
	v_cvt_f32_f16_sdwa v99, v100 dst_sel:DWORD dst_unused:UNUSED_PAD src0_sel:WORD_1
	v_cvt_f32_f16_e32 v98, v100
	v_pk_fma_f32 v[142:143], v[118:119], v[118:119], v[142:143]
	v_cvt_f32_f16_sdwa v139, v101 dst_sel:DWORD dst_unused:UNUSED_PAD src0_sel:WORD_1
	v_cvt_f32_f16_e32 v138, v101
	v_pk_fma_f32 v[142:143], v[104:105], v[104:105], v[142:143]
	v_pk_mul_f32 v[100:101], v[26:27], v[150:151]
	v_pk_fma_f32 v[142:143], v[120:121], v[120:121], v[142:143]
	v_pk_fma_f32 v[140:141], v[100:101], v[136:137], v[98:99] op_sel_hi:[1,0,1]
	v_pk_fma_f32 v[142:143], v[134:135], v[134:135], v[142:143]
	v_pk_mul_f32 v[98:99], v[28:29], v[116:117]
	v_pk_fma_f32 v[142:143], v[114:115], v[114:115], v[142:143]
	v_pk_fma_f32 v[116:117], v[98:99], v[136:137], v[138:139] op_sel_hi:[1,0,1]
	v_pk_fma_f32 v[142:143], v[140:141], v[140:141], v[142:143]
	v_lshl_add_u64 v[136:137], s[14:15], 0, v[130:131]
	v_pk_fma_f32 v[142:143], v[116:117], v[116:117], v[142:143]
	v_add_co_u32_e32 v138, vcc, s11, v136
	v_add_f32_e32 v133, v142, v143
	v_mov_b32_e32 v142, 0
	v_cvt_pk_f16_f32 v98, v110, v111
	v_add_f32_dpp v133, v133, v133 quad_perm:[1,0,3,2] row_mask:0xf bank_mask:0xf bound_ctrl:1
	v_cvt_pk_f16_f32 v99, v126, v127
	v_cvt_pk_f16_f32 v100, v112, v113
	v_add_f32_dpp v133, v133, v133 quad_perm:[2,3,0,1] row_mask:0xf bank_mask:0xf bound_ctrl:1
	v_cvt_pk_f16_f32 v101, v128, v129
	v_addc_co_u32_e32 v139, vcc, 0, v137, vcc
	v_add_f32_dpp v133, v133, v133 row_half_mirror row_mask:0xf bank_mask:0xf bound_ctrl:1
	global_store_dwordx4 v[138:139], v[98:101], off offset:1024 sc1
	s_add_u32 s14, s14, s16
	v_add_f32_dpp v133, v133, v133 row_mirror row_mask:0xf bank_mask:0xf bound_ctrl:1
	v_cvt_pk_f16_f32 v98, v106, v107
	v_cvt_pk_f16_f32 v99, v122, v123
	v_mov_b32_dpp v142, v133 row_bcast:15 row_mask:0xa bank_mask:0xf
	v_add_f32_e32 v133, v133, v142
	v_mov_b32_e32 v142, 0
	v_cvt_pk_f16_f32 v100, v108, v109
	v_cvt_pk_f16_f32 v101, v124, v125
	v_mov_b32_dpp v142, v133 row_bcast:31 row_mask:0xc bank_mask:0xf
	v_add_f32_e32 v133, v133, v142
	global_store_dwordx4 v[138:139], v[98:101], off offset:2048 sc1
	v_readlane_b32 s13, v133, 63
	s_addc_u32 s15, s15, s17
	v_cvt_pk_f16_f32 v98, v102, v103
	v_fma_f32 v133, s13, v132, v1
	v_cvt_pk_f16_f32 v99, v118, v119
	v_cvt_pk_f16_f32 v100, v104, v105
	v_cvt_pk_f16_f32 v101, v120, v121
	v_rsq_f32_e32 v142, v133
	global_store_dwordx4 v[138:139], v[98:101], off offset:3072 sc1
	v_add_co_u32_e32 v138, vcc, s24, v136
	s_nop 0
	v_cvt_pk_f16_f32 v98, v134, v135
	v_cvt_pk_f16_f32 v99, v114, v115
	v_cvt_pk_f16_f32 v100, v140, v141
	v_cvt_pk_f16_f32 v101, v116, v117
	v_addc_co_u32_e32 v139, vcc, 0, v137, vcc
	global_store_dwordx4 v[138:139], v[98:101], off sc1
	s_add_u32 s20, s20, s16
	s_addc_u32 s21, s21, s17
	v_pk_mul_f32 v[98:99], v[40:41], v[126:127]
	s_nop 0
	v_pk_mul_f32 v[100:101], v[98:99], v[142:143] op_sel_hi:[1,0]
	v_pk_mul_f32 v[98:99], v[38:39], v[110:111]
	v_pk_mul_f32 v[110:111], v[36:37], v[128:129]
	v_pk_mul_f32 v[98:99], v[98:99], v[142:143] op_sel_hi:[1,0]
	v_pk_mul_f32 v[110:111], v[110:111], v[142:143] op_sel_hi:[1,0]
	v_cvt_pk_bf16_f32 v98, v98, v99
	v_cvt_pk_bf16_f32 v99, v100, v101
	v_pk_mul_f32 v[100:101], v[34:35], v[112:113]
	s_waitcnt vmcnt(9)
	v_mov_b64_e32 v[128:129], v[76:77]
	v_pk_mul_f32 v[100:101], v[100:101], v[142:143] op_sel_hi:[1,0]
	v_mov_b64_e32 v[126:127], v[74:75]
	v_cvt_pk_bf16_f32 v100, v100, v101
	v_cvt_pk_bf16_f32 v101, v110, v111
	v_add_co_u32_e32 v110, vcc, s25, v136
	s_nop 1
	v_addc_co_u32_e32 v111, vcc, 0, v137, vcc
	global_store_dwordx4 v[110:111], v[98:101], off
	s_andn2_b64 vcc, exec, s[22:23]
	s_nop 0
	v_pk_mul_f32 v[98:99], v[46:47], v[106:107]
	v_pk_mul_f32 v[100:101], v[48:49], v[122:123]
	v_pk_mul_f32 v[98:99], v[98:99], v[142:143] op_sel_hi:[1,0]
	v_pk_mul_f32 v[100:101], v[100:101], v[142:143] op_sel_hi:[1,0]
	v_cvt_pk_bf16_f32 v98, v98, v99
	v_pk_mul_f32 v[106:107], v[44:45], v[124:125]
	v_cvt_pk_bf16_f32 v99, v100, v101
	v_pk_mul_f32 v[100:101], v[42:43], v[108:109]
	v_pk_mul_f32 v[106:107], v[106:107], v[142:143] op_sel_hi:[1,0]
	v_pk_mul_f32 v[100:101], v[100:101], v[142:143] op_sel_hi:[1,0]
	s_waitcnt vmcnt(8)
	v_mov_b64_e32 v[124:125], v[84:85]
	v_cvt_pk_bf16_f32 v100, v100, v101
	v_cvt_pk_bf16_f32 v101, v106, v107
	global_store_dwordx4 v[110:111], v[98:101], off offset:1024
	v_mov_b64_e32 v[108:109], v[72:73]
	v_mov_b64_e32 v[122:123], v[82:83]
	v_pk_mul_f32 v[98:99], v[54:55], v[102:103]
	v_pk_mul_f32 v[100:101], v[56:57], v[118:119]
	v_pk_mul_f32 v[98:99], v[98:99], v[142:143] op_sel_hi:[1,0]
	v_pk_mul_f32 v[100:101], v[100:101], v[142:143] op_sel_hi:[1,0]
	v_cvt_pk_bf16_f32 v98, v98, v99
	v_pk_mul_f32 v[102:103], v[52:53], v[120:121]
	v_cvt_pk_bf16_f32 v99, v100, v101
	v_pk_mul_f32 v[100:101], v[50:51], v[104:105]
	v_pk_mul_f32 v[102:103], v[102:103], v[142:143] op_sel_hi:[1,0]
	v_pk_mul_f32 v[100:101], v[100:101], v[142:143] op_sel_hi:[1,0]
	s_waitcnt vmcnt(8)
	v_mov_b64_e32 v[120:121], v[88:89]
	v_cvt_pk_bf16_f32 v100, v100, v101
	v_cvt_pk_bf16_f32 v101, v102, v103
	global_store_dwordx4 v[110:111], v[98:101], off offset:2048
	s_waitcnt vmcnt(8)
	v_pk_mul_f32 v[102:103], v[60:61], v[116:117]
	v_mov_b64_e32 v[118:119], v[86:87]
	s_waitcnt vmcnt(7)
	v_pk_mul_f32 v[98:99], v[62:63], v[134:135]
	v_pk_mul_f32 v[100:101], v[64:65], v[114:115]
	v_pk_mul_f32 v[98:99], v[98:99], v[142:143] op_sel_hi:[1,0]
	v_pk_mul_f32 v[100:101], v[100:101], v[142:143] op_sel_hi:[1,0]
	v_cvt_pk_bf16_f32 v98, v98, v99
	v_pk_mul_f32 v[102:103], v[102:103], v[142:143] op_sel_hi:[1,0]
	v_cvt_pk_bf16_f32 v99, v100, v101
	v_pk_mul_f32 v[100:101], v[58:59], v[140:141]
	v_mov_b64_e32 v[116:117], v[92:93]
	v_pk_mul_f32 v[100:101], v[100:101], v[142:143] op_sel_hi:[1,0]
	v_mov_b64_e32 v[114:115], v[90:91]
	v_cvt_pk_bf16_f32 v100, v100, v101
	v_cvt_pk_bf16_f32 v101, v102, v103
	global_store_dwordx4 v[110:111], v[98:101], off offset:3072
	v_mov_b64_e32 v[112:113], v[68:69]
	v_mov_b64_e32 v[104:105], v[80:81]
	v_mov_b64_e32 v[100:101], v[96:97]
	v_mov_b64_e32 v[110:111], v[66:67]
	v_mov_b64_e32 v[106:107], v[70:71]
	v_mov_b64_e32 v[102:103], v[78:79]
	v_mov_b64_e32 v[98:99], v[94:95]
	s_cbranch_vccz .LBB0_2041

.LBB0_2374:
	v_lshlrev_b32_e32 v140, 16, v126
	v_and_b32_e32 v141, 0xffff0000, v126
	v_lshlrev_b32_e32 v126, 16, v127
	v_and_b32_e32 v127, 0xffff0000, v127
	v_pk_mul_f32 v[142:143], v[126:127], v[126:127]
	v_lshlrev_b32_e32 v144, 16, v128
	v_pk_fma_f32 v[142:143], v[140:141], v[140:141], v[142:143]
	v_and_b32_e32 v145, 0xffff0000, v128
	v_pk_fma_f32 v[142:143], v[144:145], v[144:145], v[142:143]
	v_lshlrev_b32_e32 v128, 16, v129
	v_and_b32_e32 v129, 0xffff0000, v129
	v_pk_fma_f32 v[142:143], v[128:129], v[128:129], v[142:143]
	v_lshlrev_b32_e32 v146, 16, v122
	v_and_b32_e32 v147, 0xffff0000, v122
	v_pk_fma_f32 v[142:143], v[146:147], v[146:147], v[142:143]
	v_lshlrev_b32_e32 v122, 16, v123
	v_and_b32_e32 v123, 0xffff0000, v123
	v_pk_fma_f32 v[142:143], v[122:123], v[122:123], v[142:143]
	v_lshlrev_b32_e32 v148, 16, v124
	v_and_b32_e32 v149, 0xffff0000, v124
	v_pk_fma_f32 v[142:143], v[148:149], v[148:149], v[142:143]
	v_lshlrev_b32_e32 v124, 16, v125
	v_and_b32_e32 v125, 0xffff0000, v125
	v_pk_fma_f32 v[142:143], v[124:125], v[124:125], v[142:143]
	v_lshlrev_b32_e32 v150, 16, v118
	v_and_b32_e32 v151, 0xffff0000, v118
	v_pk_fma_f32 v[142:143], v[150:151], v[150:151], v[142:143]
	v_lshlrev_b32_e32 v118, 16, v119
	v_and_b32_e32 v119, 0xffff0000, v119
	v_pk_fma_f32 v[142:143], v[118:119], v[118:119], v[142:143]
	v_lshlrev_b32_e32 v152, 16, v120
	v_and_b32_e32 v153, 0xffff0000, v120
	v_pk_fma_f32 v[142:143], v[152:153], v[152:153], v[142:143]
	v_lshlrev_b32_e32 v120, 16, v121
	v_and_b32_e32 v121, 0xffff0000, v121
	v_pk_fma_f32 v[142:143], v[120:121], v[120:121], v[142:143]
	v_lshlrev_b32_e32 v154, 16, v114
	v_and_b32_e32 v155, 0xffff0000, v114
	v_pk_fma_f32 v[142:143], v[154:155], v[154:155], v[142:143]
	v_lshlrev_b32_e32 v114, 16, v115
	v_and_b32_e32 v115, 0xffff0000, v115
	v_pk_fma_f32 v[142:143], v[114:115], v[114:115], v[142:143]
	v_lshlrev_b32_e32 v156, 16, v116
	v_and_b32_e32 v157, 0xffff0000, v116
	v_pk_fma_f32 v[142:143], v[156:157], v[156:157], v[142:143]
	v_lshlrev_b32_e32 v116, 16, v117
	v_and_b32_e32 v117, 0xffff0000, v117
	v_pk_fma_f32 v[142:143], v[116:117], v[116:117], v[142:143]
	v_cvt_f32_f16_sdwa v159, v110 dst_sel:DWORD dst_unused:UNUSED_PAD src0_sel:WORD_1
	v_add_f32_e32 v142, v142, v143
	v_mov_b32_e32 v143, 0
	v_cvt_f32_f16_e32 v158, v110
	v_add_f32_dpp v142, v142, v142 quad_perm:[1,0,3,2] row_mask:0xf bank_mask:0xf bound_ctrl:1
	v_cvt_f32_f16_sdwa v161, v111 dst_sel:DWORD dst_unused:UNUSED_PAD src0_sel:WORD_1
	v_cvt_f32_f16_e32 v160, v111
	v_add_f32_dpp v142, v142, v142 quad_perm:[2,3,0,1] row_mask:0xf bank_mask:0xf bound_ctrl:1
	v_pk_mul_f32 v[110:111], v[6:7], v[140:141]
	v_cvt_f32_f16_sdwa v141, v112 dst_sel:DWORD dst_unused:UNUSED_PAD src0_sel:WORD_1
	v_add_f32_dpp v142, v142, v142 row_half_mirror row_mask:0xf bank_mask:0xf bound_ctrl:1
	v_cvt_f32_f16_e32 v140, v112
	v_pk_mul_f32 v[128:129], v[4:5], v[128:129]
	v_add_f32_dpp v142, v142, v142 row_mirror row_mask:0xf bank_mask:0xf bound_ctrl:1
	v_pk_mul_f32 v[122:123], v[16:17], v[122:123]
	v_pk_mul_f32 v[118:119], v[24:25], v[118:119]
	v_mov_b32_dpp v143, v142 row_bcast:15 row_mask:0xa bank_mask:0xf
	v_add_f32_e32 v142, v142, v143
	v_mov_b32_e32 v143, 0
	v_pk_mul_f32 v[126:127], v[8:9], v[126:127]
	s_nop 0
	v_mov_b32_dpp v143, v142 row_bcast:31 row_mask:0xc bank_mask:0xf
	v_add_f32_e32 v142, v142, v143
	s_nop 0
	v_readlane_b32 s4, v142, 63
	s_nop 1
	v_fma_f32 v142, s4, v137, v136
	v_rsq_f32_e32 v142, v142
	s_nop 0
	v_pk_fma_f32 v[110:111], v[110:111], v[142:143], v[158:159] op_sel_hi:[1,0,1]
	v_cvt_f32_f16_sdwa v159, v113 dst_sel:DWORD dst_unused:UNUSED_PAD src0_sel:WORD_1
	v_cvt_f32_f16_e32 v158, v113
	v_pk_mul_f32 v[112:113], v[2:3], v[144:145]
	v_cvt_f32_f16_sdwa v145, v107 dst_sel:DWORD dst_unused:UNUSED_PAD src0_sel:WORD_1
	v_cvt_f32_f16_e32 v144, v107
	v_pk_fma_f32 v[112:113], v[112:113], v[142:143], v[140:141] op_sel_hi:[1,0,1]
	v_pk_fma_f32 v[140:141], v[128:129], v[142:143], v[158:159] op_sel_hi:[1,0,1]
	v_cvt_f32_f16_sdwa v129, v106 dst_sel:DWORD dst_unused:UNUSED_PAD src0_sel:WORD_1
	v_cvt_f32_f16_e32 v128, v106
	v_pk_mul_f32 v[106:107], v[14:15], v[146:147]
	v_pk_fma_f32 v[144:145], v[122:123], v[142:143], v[144:145] op_sel_hi:[1,0,1]
	v_cvt_f32_f16_sdwa v123, v108 dst_sel:DWORD dst_unused:UNUSED_PAD src0_sel:WORD_1
	v_cvt_f32_f16_e32 v122, v108
	v_pk_fma_f32 v[106:107], v[106:107], v[142:143], v[128:129] op_sel_hi:[1,0,1]
	v_cvt_f32_f16_sdwa v129, v109 dst_sel:DWORD dst_unused:UNUSED_PAD src0_sel:WORD_1
	v_cvt_f32_f16_e32 v128, v109
	v_pk_mul_f32 v[108:109], v[10:11], v[148:149]
	v_pk_fma_f32 v[126:127], v[126:127], v[142:143], v[160:161] op_sel_hi:[1,0,1]
	v_pk_fma_f32 v[108:109], v[108:109], v[142:143], v[122:123] op_sel_hi:[1,0,1]
	v_pk_mul_f32 v[122:123], v[12:13], v[124:125]
	v_cvt_f32_f16_sdwa v125, v103 dst_sel:DWORD dst_unused:UNUSED_PAD src0_sel:WORD_1
	v_cvt_f32_f16_e32 v124, v103
	v_pk_fma_f32 v[146:147], v[122:123], v[142:143], v[128:129] op_sel_hi:[1,0,1]
	v_cvt_f32_f16_sdwa v123, v102 dst_sel:DWORD dst_unused:UNUSED_PAD src0_sel:WORD_1
	v_cvt_f32_f16_e32 v122, v102
	v_pk_mul_f32 v[102:103], v[22:23], v[150:151]
	v_pk_fma_f32 v[148:149], v[118:119], v[142:143], v[124:125] op_sel_hi:[1,0,1]
	v_cvt_f32_f16_sdwa v119, v104 dst_sel:DWORD dst_unused:UNUSED_PAD src0_sel:WORD_1
	v_cvt_f32_f16_e32 v118, v104
	v_pk_fma_f32 v[102:103], v[102:103], v[142:143], v[122:123] op_sel_hi:[1,0,1]
	v_cvt_f32_f16_sdwa v123, v105 dst_sel:DWORD dst_unused:UNUSED_PAD src0_sel:WORD_1
	v_cvt_f32_f16_e32 v122, v105
	v_pk_mul_f32 v[104:105], v[18:19], v[152:153]
	s_nop 0
	v_pk_fma_f32 v[104:105], v[104:105], v[142:143], v[118:119] op_sel_hi:[1,0,1]
	v_pk_mul_f32 v[118:119], v[20:21], v[120:121]
	v_cvt_f32_f16_sdwa v121, v99 dst_sel:DWORD dst_unused:UNUSED_PAD src0_sel:WORD_1
	v_pk_fma_f32 v[150:151], v[118:119], v[142:143], v[122:123] op_sel_hi:[1,0,1]
	v_cvt_f32_f16_sdwa v119, v98 dst_sel:DWORD dst_unused:UNUSED_PAD src0_sel:WORD_1
	v_cvt_f32_f16_e32 v118, v98
	v_cvt_f32_f16_e32 v120, v99
	v_pk_mul_f32 v[98:99], v[30:31], v[154:155]
	s_nop 0
	v_pk_fma_f32 v[152:153], v[98:99], v[142:143], v[118:119] op_sel_hi:[1,0,1]
	v_pk_mul_f32 v[98:99], v[32:33], v[114:115]
	v_cvt_f32_f16_sdwa v115, v101 dst_sel:DWORD dst_unused:UNUSED_PAD src0_sel:WORD_1
	v_pk_fma_f32 v[154:155], v[98:99], v[142:143], v[120:121] op_sel_hi:[1,0,1]
	v_cvt_f32_f16_sdwa v99, v100 dst_sel:DWORD dst_unused:UNUSED_PAD src0_sel:WORD_1
	v_cvt_f32_f16_e32 v98, v100
	v_cvt_f32_f16_e32 v114, v101
	v_pk_mul_f32 v[100:101], v[26:27], v[156:157]
	s_nop 0
	v_pk_fma_f32 v[156:157], v[100:101], v[142:143], v[98:99] op_sel_hi:[1,0,1]
	v_pk_mul_f32 v[98:99], v[28:29], v[116:117]
	v_cvt_pk_f16_f32 v100, v112, v113
	v_pk_fma_f32 v[142:143], v[98:99], v[142:143], v[114:115] op_sel_hi:[1,0,1]
	v_lshl_add_u64 v[114:115], s[94:95], 0, v[132:133]
	v_add_co_u32_e32 v116, vcc, s28, v114
	v_cvt_pk_f16_f32 v98, v110, v111
	v_cvt_pk_f16_f32 v99, v126, v127
	v_cvt_pk_f16_f32 v101, v140, v141
	v_addc_co_u32_e32 v117, vcc, 0, v115, vcc
	global_store_dwordx4 v[116:117], v[98:101], off offset:1024 sc1
	v_add_co_u32_e32 v114, vcc, s29, v114
	s_nop 0
	v_cvt_pk_f16_f32 v98, v106, v107
	v_cvt_pk_f16_f32 v99, v144, v145
	v_cvt_pk_f16_f32 v100, v108, v109
	v_cvt_pk_f16_f32 v101, v146, v147
	global_store_dwordx4 v[116:117], v[98:101], off offset:2048 sc1
	v_addc_co_u32_e32 v115, vcc, 0, v115, vcc
	s_nop 0
	v_cvt_pk_f16_f32 v98, v102, v103
	v_cvt_pk_f16_f32 v99, v148, v149
	v_cvt_pk_f16_f32 v100, v104, v105
	v_cvt_pk_f16_f32 v101, v150, v151
	global_store_dwordx4 v[116:117], v[98:101], off offset:3072 sc1
	v_pk_mul_f32 v[116:117], v[126:127], v[126:127]
	s_nop 0
	v_pk_fma_f32 v[116:117], v[110:111], v[110:111], v[116:117]
	v_cvt_pk_f16_f32 v98, v152, v153
	v_pk_fma_f32 v[116:117], v[112:113], v[112:113], v[116:117]
	v_cvt_pk_f16_f32 v99, v154, v155
	v_pk_fma_f32 v[116:117], v[140:141], v[140:141], v[116:117]
	v_cvt_pk_f16_f32 v100, v156, v157
	v_pk_fma_f32 v[116:117], v[106:107], v[106:107], v[116:117]
	v_cvt_pk_f16_f32 v101, v142, v143
	v_pk_fma_f32 v[116:117], v[144:145], v[144:145], v[116:117]
	global_store_dwordx4 v[114:115], v[98:101], off sc1
	v_pk_fma_f32 v[116:117], v[108:109], v[108:109], v[116:117]
	s_nop 0
	v_pk_fma_f32 v[116:117], v[146:147], v[146:147], v[116:117]
	v_pk_mul_f32 v[98:99], v[40:41], v[126:127]
	v_pk_fma_f32 v[116:117], v[102:103], v[102:103], v[116:117]
	s_nop 0
	v_pk_fma_f32 v[116:117], v[148:149], v[148:149], v[116:117]
	s_nop 0
	v_pk_fma_f32 v[116:117], v[104:105], v[104:105], v[116:117]
	s_nop 0
	v_pk_fma_f32 v[116:117], v[150:151], v[150:151], v[116:117]
	s_nop 0
	v_pk_fma_f32 v[116:117], v[152:153], v[152:153], v[116:117]
	s_nop 0
	v_pk_fma_f32 v[116:117], v[154:155], v[154:155], v[116:117]
	s_nop 0
	v_pk_fma_f32 v[116:117], v[156:157], v[156:157], v[116:117]
	s_nop 0
	v_pk_fma_f32 v[116:117], v[142:143], v[142:143], v[116:117]
	s_nop 0
	v_add_f32_e32 v116, v116, v117
	v_mov_b32_e32 v117, 0
	s_nop 0
	v_add_f32_dpp v116, v116, v116 quad_perm:[1,0,3,2] row_mask:0xf bank_mask:0xf bound_ctrl:1
	s_nop 1
	v_add_f32_dpp v116, v116, v116 quad_perm:[2,3,0,1] row_mask:0xf bank_mask:0xf bound_ctrl:1
	s_nop 1
	v_add_f32_dpp v116, v116, v116 row_half_mirror row_mask:0xf bank_mask:0xf bound_ctrl:1
	s_nop 1
	v_add_f32_dpp v116, v116, v116 row_mirror row_mask:0xf bank_mask:0xf bound_ctrl:1
	s_nop 1
	v_mov_b32_dpp v117, v116 row_bcast:15 row_mask:0xa bank_mask:0xf
	v_add_f32_e32 v116, v116, v117
	v_mov_b32_e32 v117, 0
	s_nop 1
	v_mov_b32_dpp v117, v116 row_bcast:31 row_mask:0xc bank_mask:0xf
	v_add_f32_e32 v116, v116, v117
	s_nop 0
	v_readlane_b32 s4, v116, 63
	s_nop 1
	v_fma_f32 v116, s4, v137, v136
	v_rsq_f32_e32 v158, v116
	s_nop 0
	v_pk_mul_f32 v[122:123], v[98:99], v[158:159] op_sel_hi:[1,0]
	v_pk_mul_f32 v[98:99], v[38:39], v[110:111]
	s_nop 0
	v_pk_mul_f32 v[128:129], v[98:99], v[158:159] op_sel_hi:[1,0]
	v_max_f32_e64 v99, |v122|, |v123|
	v_max_f32_e64 v98, |v128|, |v129|
	v_max3_f32 v100, v98, 0, v99
	v_pk_mul_f32 v[98:99], v[34:35], v[112:113]
	s_nop 0
	v_pk_mul_f32 v[124:125], v[98:99], v[158:159] op_sel_hi:[1,0]
	v_pk_mul_f32 v[98:99], v[36:37], v[140:141]
	v_max_f32_e64 v101, |v124|, |v125|
	v_pk_mul_f32 v[126:127], v[98:99], v[158:159] op_sel_hi:[1,0]
	s_nop 0
	v_max_f32_e64 v98, |v126|, |v127|
	v_max3_f32 v100, v100, v101, v98
	v_pk_mul_f32 v[98:99], v[46:47], v[106:107]
	s_nop 0
	v_pk_mul_f32 v[114:115], v[98:99], v[158:159] op_sel_hi:[1,0]
	v_pk_mul_f32 v[98:99], v[48:49], v[144:145]
	v_max_f32_e64 v101, |v114|, |v115|
	v_pk_mul_f32 v[118:119], v[98:99], v[158:159] op_sel_hi:[1,0]
	s_nop 0
	v_max_f32_e64 v98, |v118|, |v119|
	v_max3_f32 v100, v100, v101, v98
	v_pk_mul_f32 v[98:99], v[42:43], v[108:109]
	s_nop 0
	v_pk_mul_f32 v[116:117], v[98:99], v[158:159] op_sel_hi:[1,0]
	v_pk_mul_f32 v[98:99], v[44:45], v[146:147]
	v_max_f32_e64 v101, |v116|, |v117|
	v_pk_mul_f32 v[120:121], v[98:99], v[158:159] op_sel_hi:[1,0]
	s_nop 0
	v_max_f32_e64 v98, |v120|, |v121|
	v_max3_f32 v100, v100, v101, v98
	v_pk_mul_f32 v[98:99], v[54:55], v[102:103]
	s_nop 0
	v_pk_mul_f32 v[106:107], v[98:99], v[158:159] op_sel_hi:[1,0]
	v_pk_mul_f32 v[98:99], v[56:57], v[148:149]
	v_max_f32_e64 v101, |v106|, |v107|
	v_pk_mul_f32 v[110:111], v[98:99], v[158:159] op_sel_hi:[1,0]
	s_nop 0
	v_max_f32_e64 v98, |v110|, |v111|
	v_max3_f32 v100, v100, v101, v98
	v_pk_mul_f32 v[98:99], v[50:51], v[104:105]
	s_nop 0
	v_pk_mul_f32 v[108:109], v[98:99], v[158:159] op_sel_hi:[1,0]
	v_pk_mul_f32 v[98:99], v[52:53], v[150:151]
	v_max_f32_e64 v101, |v108|, |v109|
	v_pk_mul_f32 v[112:113], v[98:99], v[158:159] op_sel_hi:[1,0]
	s_nop 0
	v_max_f32_e64 v98, |v112|, |v113|
	v_max3_f32 v104, v100, v101, v98
	s_waitcnt vmcnt(4)
	v_pk_mul_f32 v[98:99], v[62:63], v[152:153]
	v_pk_mul_f32 v[100:101], v[64:65], v[154:155]
	v_pk_mul_f32 v[98:99], v[98:99], v[158:159] op_sel_hi:[1,0]
	v_pk_mul_f32 v[102:103], v[100:101], v[158:159] op_sel_hi:[1,0]
	v_max_f32_e64 v105, |v98|, |v99|
	v_max_f32_e64 v100, |v102|, |v103|
	v_max3_f32 v140, v104, v105, v100
	v_pk_mul_f32 v[100:101], v[58:59], v[156:157]
	v_pk_mul_f32 v[104:105], v[60:61], v[142:143]
	v_pk_mul_f32 v[100:101], v[100:101], v[158:159] op_sel_hi:[1,0]
	v_pk_mul_f32 v[104:105], v[104:105], v[158:159] op_sel_hi:[1,0]
	v_max_f32_e64 v141, |v100|, |v101|
	v_max_f32_e64 v142, |v104|, |v105|
	v_max3_f32 v140, v140, v141, v142
	v_mov_b32_e32 v141, 0
	s_nop 1
	v_mov_b32_dpp v141, v140 quad_perm:[1,0,3,2] row_mask:0xf bank_mask:0xf
	v_max_f32_e32 v141, v141, v141
	v_max_f32_e32 v140, v140, v141
	v_mov_b32_e32 v141, 0
	s_nop 1
	v_mov_b32_dpp v141, v140 quad_perm:[2,3,0,1] row_mask:0xf bank_mask:0xf
	v_max_f32_e32 v141, v141, v141
	v_max_f32_e32 v140, v140, v141
	v_mov_b32_e32 v141, 0
	s_nop 1
	v_mov_b32_dpp v141, v140 row_half_mirror row_mask:0xf bank_mask:0xf
	v_max_f32_e32 v141, v141, v141
	v_max_f32_e32 v140, v140, v141
	v_mov_b32_e32 v141, 0
	s_nop 1
	v_mov_b32_dpp v141, v140 row_mirror row_mask:0xf bank_mask:0xf
	v_max_f32_e32 v141, v141, v141
	v_max_f32_e32 v140, v140, v141
	v_mov_b32_e32 v141, 0
	s_nop 1
	v_mov_b32_dpp v141, v140 row_bcast:15 row_mask:0xa bank_mask:0xf
	v_max_f32_e32 v141, v141, v141
	v_max_f32_e32 v140, v140, v141
	v_mov_b32_e32 v141, 0
	s_nop 1
	v_mov_b32_dpp v141, v140 row_bcast:31 row_mask:0xc bank_mask:0xf
	v_max_f32_e32 v141, v141, v141
	v_max_f32_e32 v140, v140, v141
	s_nop 0
	v_readlane_b32 s15, v140, 63
	s_nop 1
	v_cmp_gt_f32_e64 s[4:5], s15, 0
	s_and_saveexec_b64 s[26:27], s[0:1]
	s_cbranch_execz .LBB0_2371
	v_mul_f32_e32 v140, s15, v138
	s_add_u32 s38, s94, s13
	v_cndmask_b32_e64 v140, 1.0, v140, s[4:5]
	s_addc_u32 s39, s95, s37
	global_store_dword v1, v140, s[38:39]
	s_branch .LBB0_2371

.LBB0_2645:
	v_lshlrev_b32_e32 v140, 16, v126
	v_and_b32_e32 v141, 0xffff0000, v126
	v_lshlrev_b32_e32 v126, 16, v127
	v_and_b32_e32 v127, 0xffff0000, v127
	v_pk_mul_f32 v[142:143], v[126:127], v[126:127]
	v_lshlrev_b32_e32 v144, 16, v128
	v_pk_fma_f32 v[142:143], v[140:141], v[140:141], v[142:143]
	v_and_b32_e32 v145, 0xffff0000, v128
	v_pk_fma_f32 v[142:143], v[144:145], v[144:145], v[142:143]
	v_lshlrev_b32_e32 v128, 16, v129
	v_and_b32_e32 v129, 0xffff0000, v129
	v_pk_fma_f32 v[142:143], v[128:129], v[128:129], v[142:143]
	v_lshlrev_b32_e32 v146, 16, v122
	v_and_b32_e32 v147, 0xffff0000, v122
	v_pk_fma_f32 v[142:143], v[146:147], v[146:147], v[142:143]
	v_lshlrev_b32_e32 v122, 16, v123
	v_and_b32_e32 v123, 0xffff0000, v123
	v_pk_fma_f32 v[142:143], v[122:123], v[122:123], v[142:143]
	v_lshlrev_b32_e32 v148, 16, v124
	v_and_b32_e32 v149, 0xffff0000, v124
	v_pk_fma_f32 v[142:143], v[148:149], v[148:149], v[142:143]
	v_lshlrev_b32_e32 v124, 16, v125
	v_and_b32_e32 v125, 0xffff0000, v125
	v_pk_fma_f32 v[142:143], v[124:125], v[124:125], v[142:143]
	v_lshlrev_b32_e32 v150, 16, v118
	v_and_b32_e32 v151, 0xffff0000, v118
	v_pk_fma_f32 v[142:143], v[150:151], v[150:151], v[142:143]
	v_lshlrev_b32_e32 v118, 16, v119
	v_and_b32_e32 v119, 0xffff0000, v119
	v_pk_fma_f32 v[142:143], v[118:119], v[118:119], v[142:143]
	v_lshlrev_b32_e32 v152, 16, v120
	v_and_b32_e32 v153, 0xffff0000, v120
	v_pk_fma_f32 v[142:143], v[152:153], v[152:153], v[142:143]
	v_lshlrev_b32_e32 v120, 16, v121
	v_and_b32_e32 v121, 0xffff0000, v121
	v_pk_fma_f32 v[142:143], v[120:121], v[120:121], v[142:143]
	v_lshlrev_b32_e32 v154, 16, v114
	v_and_b32_e32 v155, 0xffff0000, v114
	v_pk_fma_f32 v[142:143], v[154:155], v[154:155], v[142:143]
	v_lshlrev_b32_e32 v114, 16, v115
	v_and_b32_e32 v115, 0xffff0000, v115
	v_pk_fma_f32 v[142:143], v[114:115], v[114:115], v[142:143]
	v_lshlrev_b32_e32 v156, 16, v116
	v_and_b32_e32 v157, 0xffff0000, v116
	v_pk_fma_f32 v[142:143], v[156:157], v[156:157], v[142:143]
	v_lshlrev_b32_e32 v116, 16, v117
	v_and_b32_e32 v117, 0xffff0000, v117
	v_pk_fma_f32 v[142:143], v[116:117], v[116:117], v[142:143]
	v_cvt_f32_f16_sdwa v159, v110 dst_sel:DWORD dst_unused:UNUSED_PAD src0_sel:WORD_1
	v_add_f32_e32 v142, v142, v143
	v_mov_b32_e32 v143, 0
	v_cvt_f32_f16_e32 v158, v110
	v_add_f32_dpp v142, v142, v142 quad_perm:[1,0,3,2] row_mask:0xf bank_mask:0xf bound_ctrl:1
	v_cvt_f32_f16_sdwa v161, v111 dst_sel:DWORD dst_unused:UNUSED_PAD src0_sel:WORD_1
	v_cvt_f32_f16_e32 v160, v111
	v_add_f32_dpp v142, v142, v142 quad_perm:[2,3,0,1] row_mask:0xf bank_mask:0xf bound_ctrl:1
	v_pk_mul_f32 v[110:111], v[6:7], v[140:141]
	v_cvt_f32_f16_sdwa v141, v112 dst_sel:DWORD dst_unused:UNUSED_PAD src0_sel:WORD_1
	v_add_f32_dpp v142, v142, v142 row_half_mirror row_mask:0xf bank_mask:0xf bound_ctrl:1
	v_cvt_f32_f16_e32 v140, v112
	v_pk_mul_f32 v[128:129], v[4:5], v[128:129]
	v_add_f32_dpp v142, v142, v142 row_mirror row_mask:0xf bank_mask:0xf bound_ctrl:1
	v_pk_mul_f32 v[122:123], v[16:17], v[122:123]
	v_pk_mul_f32 v[118:119], v[24:25], v[118:119]
	v_mov_b32_dpp v143, v142 row_bcast:15 row_mask:0xa bank_mask:0xf
	v_add_f32_e32 v142, v142, v143
	v_mov_b32_e32 v143, 0
	v_pk_mul_f32 v[126:127], v[8:9], v[126:127]
	s_nop 0
	v_mov_b32_dpp v143, v142 row_bcast:31 row_mask:0xc bank_mask:0xf
	v_add_f32_e32 v142, v142, v143
	s_nop 0
	v_readlane_b32 s4, v142, 63
	s_nop 1
	v_fma_f32 v142, s4, v137, v136
	v_rsq_f32_e32 v142, v142
	s_nop 0
	v_mul_f32_e32 v142, 0.5, v142
	v_pk_fma_f32 v[110:111], v[110:111], v[142:143], v[158:159] op_sel_hi:[1,0,1]
	v_cvt_f32_f16_sdwa v159, v113 dst_sel:DWORD dst_unused:UNUSED_PAD src0_sel:WORD_1
	v_cvt_f32_f16_e32 v158, v113
	v_pk_mul_f32 v[112:113], v[2:3], v[144:145]
	v_cvt_f32_f16_sdwa v145, v107 dst_sel:DWORD dst_unused:UNUSED_PAD src0_sel:WORD_1
	v_cvt_f32_f16_e32 v144, v107
	v_pk_fma_f32 v[112:113], v[112:113], v[142:143], v[140:141] op_sel_hi:[1,0,1]
	v_pk_fma_f32 v[140:141], v[128:129], v[142:143], v[158:159] op_sel_hi:[1,0,1]
	v_cvt_f32_f16_sdwa v129, v106 dst_sel:DWORD dst_unused:UNUSED_PAD src0_sel:WORD_1
	v_cvt_f32_f16_e32 v128, v106
	v_pk_mul_f32 v[106:107], v[14:15], v[146:147]
	v_pk_fma_f32 v[144:145], v[122:123], v[142:143], v[144:145] op_sel_hi:[1,0,1]
	v_cvt_f32_f16_sdwa v123, v108 dst_sel:DWORD dst_unused:UNUSED_PAD src0_sel:WORD_1
	v_cvt_f32_f16_e32 v122, v108
	v_pk_fma_f32 v[106:107], v[106:107], v[142:143], v[128:129] op_sel_hi:[1,0,1]
	v_cvt_f32_f16_sdwa v129, v109 dst_sel:DWORD dst_unused:UNUSED_PAD src0_sel:WORD_1
	v_cvt_f32_f16_e32 v128, v109
	v_pk_mul_f32 v[108:109], v[10:11], v[148:149]
	v_pk_fma_f32 v[126:127], v[126:127], v[142:143], v[160:161] op_sel_hi:[1,0,1]
	v_pk_fma_f32 v[108:109], v[108:109], v[142:143], v[122:123] op_sel_hi:[1,0,1]
	v_pk_mul_f32 v[122:123], v[12:13], v[124:125]
	v_cvt_f32_f16_sdwa v125, v103 dst_sel:DWORD dst_unused:UNUSED_PAD src0_sel:WORD_1
	v_cvt_f32_f16_e32 v124, v103
	v_pk_fma_f32 v[146:147], v[122:123], v[142:143], v[128:129] op_sel_hi:[1,0,1]
	v_cvt_f32_f16_sdwa v123, v102 dst_sel:DWORD dst_unused:UNUSED_PAD src0_sel:WORD_1
	v_cvt_f32_f16_e32 v122, v102
	v_pk_mul_f32 v[102:103], v[22:23], v[150:151]
	v_pk_fma_f32 v[148:149], v[118:119], v[142:143], v[124:125] op_sel_hi:[1,0,1]
	v_cvt_f32_f16_sdwa v119, v104 dst_sel:DWORD dst_unused:UNUSED_PAD src0_sel:WORD_1
	v_cvt_f32_f16_e32 v118, v104
	v_pk_fma_f32 v[102:103], v[102:103], v[142:143], v[122:123] op_sel_hi:[1,0,1]
	v_cvt_f32_f16_sdwa v123, v105 dst_sel:DWORD dst_unused:UNUSED_PAD src0_sel:WORD_1
	v_cvt_f32_f16_e32 v122, v105
	v_pk_mul_f32 v[104:105], v[18:19], v[152:153]
	s_nop 0
	v_pk_fma_f32 v[104:105], v[104:105], v[142:143], v[118:119] op_sel_hi:[1,0,1]
	v_pk_mul_f32 v[118:119], v[20:21], v[120:121]
	v_cvt_f32_f16_sdwa v121, v99 dst_sel:DWORD dst_unused:UNUSED_PAD src0_sel:WORD_1
	v_pk_fma_f32 v[150:151], v[118:119], v[142:143], v[122:123] op_sel_hi:[1,0,1]
	v_cvt_f32_f16_sdwa v119, v98 dst_sel:DWORD dst_unused:UNUSED_PAD src0_sel:WORD_1
	v_cvt_f32_f16_e32 v118, v98
	v_cvt_f32_f16_e32 v120, v99
	v_pk_mul_f32 v[98:99], v[30:31], v[154:155]
	s_nop 0
	v_pk_fma_f32 v[152:153], v[98:99], v[142:143], v[118:119] op_sel_hi:[1,0,1]
	v_pk_mul_f32 v[98:99], v[32:33], v[114:115]
	v_cvt_f32_f16_sdwa v115, v101 dst_sel:DWORD dst_unused:UNUSED_PAD src0_sel:WORD_1
	v_pk_fma_f32 v[154:155], v[98:99], v[142:143], v[120:121] op_sel_hi:[1,0,1]
	v_cvt_f32_f16_sdwa v99, v100 dst_sel:DWORD dst_unused:UNUSED_PAD src0_sel:WORD_1
	v_cvt_f32_f16_e32 v98, v100
	v_cvt_f32_f16_e32 v114, v101
	v_pk_mul_f32 v[100:101], v[26:27], v[156:157]
	s_nop 0
	v_pk_fma_f32 v[156:157], v[100:101], v[142:143], v[98:99] op_sel_hi:[1,0,1]
	v_pk_mul_f32 v[98:99], v[28:29], v[116:117]
	v_cvt_pk_f16_f32 v100, v112, v113
	v_pk_fma_f32 v[142:143], v[98:99], v[142:143], v[114:115] op_sel_hi:[1,0,1]
	v_lshl_add_u64 v[114:115], s[94:95], 0, v[132:133]
	v_add_co_u32_e32 v116, vcc, s28, v114
	v_cvt_pk_f16_f32 v98, v110, v111
	v_cvt_pk_f16_f32 v99, v126, v127
	v_cvt_pk_f16_f32 v101, v140, v141
	v_addc_co_u32_e32 v117, vcc, 0, v115, vcc
	global_store_dwordx4 v[116:117], v[98:101], off offset:1024 sc1
	v_add_co_u32_e32 v114, vcc, s29, v114
	s_nop 0
	v_cvt_pk_f16_f32 v98, v106, v107
	v_cvt_pk_f16_f32 v99, v144, v145
	v_cvt_pk_f16_f32 v100, v108, v109
	v_cvt_pk_f16_f32 v101, v146, v147
	global_store_dwordx4 v[116:117], v[98:101], off offset:2048 sc1
	v_addc_co_u32_e32 v115, vcc, 0, v115, vcc
	s_nop 0
	v_cvt_pk_f16_f32 v98, v102, v103
	v_cvt_pk_f16_f32 v99, v148, v149
	v_cvt_pk_f16_f32 v100, v104, v105
	v_cvt_pk_f16_f32 v101, v150, v151
	global_store_dwordx4 v[116:117], v[98:101], off offset:3072 sc1
	v_pk_mul_f32 v[116:117], v[126:127], v[126:127]
	s_nop 0
	v_pk_fma_f32 v[116:117], v[110:111], v[110:111], v[116:117]
	v_cvt_pk_f16_f32 v98, v152, v153
	v_pk_fma_f32 v[116:117], v[112:113], v[112:113], v[116:117]
	v_cvt_pk_f16_f32 v99, v154, v155
	v_pk_fma_f32 v[116:117], v[140:141], v[140:141], v[116:117]
	v_cvt_pk_f16_f32 v100, v156, v157
	v_pk_fma_f32 v[116:117], v[106:107], v[106:107], v[116:117]
	v_cvt_pk_f16_f32 v101, v142, v143
	v_pk_fma_f32 v[116:117], v[144:145], v[144:145], v[116:117]
	global_store_dwordx4 v[114:115], v[98:101], off sc1
	v_pk_fma_f32 v[116:117], v[108:109], v[108:109], v[116:117]
	s_nop 0
	v_pk_fma_f32 v[116:117], v[146:147], v[146:147], v[116:117]
	v_pk_mul_f32 v[98:99], v[40:41], v[126:127]
	v_pk_fma_f32 v[116:117], v[102:103], v[102:103], v[116:117]
	s_nop 0
	v_pk_fma_f32 v[116:117], v[148:149], v[148:149], v[116:117]
	s_nop 0
	v_pk_fma_f32 v[116:117], v[104:105], v[104:105], v[116:117]
	s_nop 0
	v_pk_fma_f32 v[116:117], v[150:151], v[150:151], v[116:117]
	s_nop 0
	v_pk_fma_f32 v[116:117], v[152:153], v[152:153], v[116:117]
	s_nop 0
	v_pk_fma_f32 v[116:117], v[154:155], v[154:155], v[116:117]
	s_nop 0
	v_pk_fma_f32 v[116:117], v[156:157], v[156:157], v[116:117]
	s_nop 0
	v_pk_fma_f32 v[116:117], v[142:143], v[142:143], v[116:117]
	s_nop 0
	v_add_f32_e32 v116, v116, v117
	v_mov_b32_e32 v117, 0
	s_nop 0
	v_add_f32_dpp v116, v116, v116 quad_perm:[1,0,3,2] row_mask:0xf bank_mask:0xf bound_ctrl:1
	s_nop 1
	v_add_f32_dpp v116, v116, v116 quad_perm:[2,3,0,1] row_mask:0xf bank_mask:0xf bound_ctrl:1
	s_nop 1
	v_add_f32_dpp v116, v116, v116 row_half_mirror row_mask:0xf bank_mask:0xf bound_ctrl:1
	s_nop 1
	v_add_f32_dpp v116, v116, v116 row_mirror row_mask:0xf bank_mask:0xf bound_ctrl:1
	s_nop 1
	v_mov_b32_dpp v117, v116 row_bcast:15 row_mask:0xa bank_mask:0xf
	v_add_f32_e32 v116, v116, v117
	v_mov_b32_e32 v117, 0
	s_nop 1
	v_mov_b32_dpp v117, v116 row_bcast:31 row_mask:0xc bank_mask:0xf
	v_add_f32_e32 v116, v116, v117
	s_nop 0
	v_readlane_b32 s4, v116, 63
	s_nop 1
	v_fma_f32 v116, s4, v137, v136
	v_rsq_f32_e32 v158, v116
	s_nop 0
	v_pk_mul_f32 v[122:123], v[98:99], v[158:159] op_sel_hi:[1,0]
	v_pk_mul_f32 v[98:99], v[38:39], v[110:111]
	s_nop 0
	v_pk_mul_f32 v[128:129], v[98:99], v[158:159] op_sel_hi:[1,0]
	v_max_f32_e64 v99, |v122|, |v123|
	v_max_f32_e64 v98, |v128|, |v129|
	v_max3_f32 v100, v98, 0, v99
	v_pk_mul_f32 v[98:99], v[34:35], v[112:113]
	s_nop 0
	v_pk_mul_f32 v[124:125], v[98:99], v[158:159] op_sel_hi:[1,0]
	v_pk_mul_f32 v[98:99], v[36:37], v[140:141]
	v_max_f32_e64 v101, |v124|, |v125|
	v_pk_mul_f32 v[126:127], v[98:99], v[158:159] op_sel_hi:[1,0]
	s_nop 0
	v_max_f32_e64 v98, |v126|, |v127|
	v_max3_f32 v100, v100, v101, v98
	v_pk_mul_f32 v[98:99], v[46:47], v[106:107]
	s_nop 0
	v_pk_mul_f32 v[114:115], v[98:99], v[158:159] op_sel_hi:[1,0]
	v_pk_mul_f32 v[98:99], v[48:49], v[144:145]
	v_max_f32_e64 v101, |v114|, |v115|
	v_pk_mul_f32 v[118:119], v[98:99], v[158:159] op_sel_hi:[1,0]
	s_nop 0
	v_max_f32_e64 v98, |v118|, |v119|
	v_max3_f32 v100, v100, v101, v98
	v_pk_mul_f32 v[98:99], v[42:43], v[108:109]
	s_nop 0
	v_pk_mul_f32 v[116:117], v[98:99], v[158:159] op_sel_hi:[1,0]
	v_pk_mul_f32 v[98:99], v[44:45], v[146:147]
	v_max_f32_e64 v101, |v116|, |v117|
	v_pk_mul_f32 v[120:121], v[98:99], v[158:159] op_sel_hi:[1,0]
	s_nop 0
	v_max_f32_e64 v98, |v120|, |v121|
	v_max3_f32 v100, v100, v101, v98
	v_pk_mul_f32 v[98:99], v[54:55], v[102:103]
	s_nop 0
	v_pk_mul_f32 v[106:107], v[98:99], v[158:159] op_sel_hi:[1,0]
	v_pk_mul_f32 v[98:99], v[56:57], v[148:149]
	v_max_f32_e64 v101, |v106|, |v107|
	v_pk_mul_f32 v[110:111], v[98:99], v[158:159] op_sel_hi:[1,0]
	s_nop 0
	v_max_f32_e64 v98, |v110|, |v111|
	v_max3_f32 v100, v100, v101, v98
	v_pk_mul_f32 v[98:99], v[50:51], v[104:105]
	s_nop 0
	v_pk_mul_f32 v[108:109], v[98:99], v[158:159] op_sel_hi:[1,0]
	v_pk_mul_f32 v[98:99], v[52:53], v[150:151]
	v_max_f32_e64 v101, |v108|, |v109|
	v_pk_mul_f32 v[112:113], v[98:99], v[158:159] op_sel_hi:[1,0]
	s_nop 0
	v_max_f32_e64 v98, |v112|, |v113|
	v_max3_f32 v104, v100, v101, v98
	s_waitcnt vmcnt(4)
	v_pk_mul_f32 v[98:99], v[62:63], v[152:153]
	v_pk_mul_f32 v[100:101], v[64:65], v[154:155]
	v_pk_mul_f32 v[98:99], v[98:99], v[158:159] op_sel_hi:[1,0]
	v_pk_mul_f32 v[102:103], v[100:101], v[158:159] op_sel_hi:[1,0]
	v_max_f32_e64 v105, |v98|, |v99|
	v_max_f32_e64 v100, |v102|, |v103|
	v_max3_f32 v140, v104, v105, v100
	v_pk_mul_f32 v[100:101], v[58:59], v[156:157]
	v_pk_mul_f32 v[104:105], v[60:61], v[142:143]
	v_pk_mul_f32 v[100:101], v[100:101], v[158:159] op_sel_hi:[1,0]
	v_pk_mul_f32 v[104:105], v[104:105], v[158:159] op_sel_hi:[1,0]
	v_max_f32_e64 v141, |v100|, |v101|
	v_max_f32_e64 v142, |v104|, |v105|
	v_max3_f32 v140, v140, v141, v142
	v_mov_b32_e32 v141, 0
	s_nop 1
	v_mov_b32_dpp v141, v140 quad_perm:[1,0,3,2] row_mask:0xf bank_mask:0xf
	v_max_f32_e32 v141, v141, v141
	v_max_f32_e32 v140, v140, v141
	v_mov_b32_e32 v141, 0
	s_nop 1
	v_mov_b32_dpp v141, v140 quad_perm:[2,3,0,1] row_mask:0xf bank_mask:0xf
	v_max_f32_e32 v141, v141, v141
	v_max_f32_e32 v140, v140, v141
	v_mov_b32_e32 v141, 0
	s_nop 1
	v_mov_b32_dpp v141, v140 row_half_mirror row_mask:0xf bank_mask:0xf
	v_max_f32_e32 v141, v141, v141
	v_max_f32_e32 v140, v140, v141
	v_mov_b32_e32 v141, 0
	s_nop 1
	v_mov_b32_dpp v141, v140 row_mirror row_mask:0xf bank_mask:0xf
	v_max_f32_e32 v141, v141, v141
	v_max_f32_e32 v140, v140, v141
	v_mov_b32_e32 v141, 0
	s_nop 1
	v_mov_b32_dpp v141, v140 row_bcast:15 row_mask:0xa bank_mask:0xf
	v_max_f32_e32 v141, v141, v141
	v_max_f32_e32 v140, v140, v141
	v_mov_b32_e32 v141, 0
	s_nop 1
	v_mov_b32_dpp v141, v140 row_bcast:31 row_mask:0xc bank_mask:0xf
	v_max_f32_e32 v141, v141, v141
	v_max_f32_e32 v140, v140, v141
	s_nop 0
	v_readlane_b32 s15, v140, 63
	s_nop 1
	v_cmp_gt_f32_e64 s[4:5], s15, 0
	s_and_saveexec_b64 s[26:27], s[0:1]
	s_cbranch_execz .LBB0_2642
	v_mul_f32_e32 v140, s15, v138
	s_add_u32 s38, s94, s13
	v_cndmask_b32_e64 v140, 1.0, v140, s[4:5]
	s_addc_u32 s39, s95, s37
	global_store_dword v1, v140, s[38:39]
	s_branch .LBB0_2642

.LBB0_2913:
	v_lshlrev_b32_e32 v134, 16, v126
	v_and_b32_e32 v135, 0xffff0000, v126
	v_lshlrev_b32_e32 v126, 16, v127
	v_and_b32_e32 v127, 0xffff0000, v127
	v_pk_mul_f32 v[136:137], v[126:127], v[126:127]
	v_lshlrev_b32_e32 v138, 16, v128
	v_pk_fma_f32 v[136:137], v[134:135], v[134:135], v[136:137]
	v_and_b32_e32 v139, 0xffff0000, v128
	v_pk_fma_f32 v[136:137], v[138:139], v[138:139], v[136:137]
	v_lshlrev_b32_e32 v128, 16, v129
	v_and_b32_e32 v129, 0xffff0000, v129
	v_pk_fma_f32 v[136:137], v[128:129], v[128:129], v[136:137]
	v_lshlrev_b32_e32 v140, 16, v122
	v_and_b32_e32 v141, 0xffff0000, v122
	v_pk_fma_f32 v[136:137], v[140:141], v[140:141], v[136:137]
	v_lshlrev_b32_e32 v122, 16, v123
	v_and_b32_e32 v123, 0xffff0000, v123
	v_pk_fma_f32 v[136:137], v[122:123], v[122:123], v[136:137]
	v_lshlrev_b32_e32 v142, 16, v124
	v_and_b32_e32 v143, 0xffff0000, v124
	v_pk_fma_f32 v[136:137], v[142:143], v[142:143], v[136:137]
	v_lshlrev_b32_e32 v124, 16, v125
	v_and_b32_e32 v125, 0xffff0000, v125
	v_pk_fma_f32 v[136:137], v[124:125], v[124:125], v[136:137]
	v_lshlrev_b32_e32 v144, 16, v118
	v_and_b32_e32 v145, 0xffff0000, v118
	v_pk_fma_f32 v[136:137], v[144:145], v[144:145], v[136:137]
	v_lshlrev_b32_e32 v118, 16, v119
	v_and_b32_e32 v119, 0xffff0000, v119
	v_pk_fma_f32 v[136:137], v[118:119], v[118:119], v[136:137]
	v_lshlrev_b32_e32 v146, 16, v120
	v_and_b32_e32 v147, 0xffff0000, v120
	v_pk_fma_f32 v[136:137], v[146:147], v[146:147], v[136:137]
	v_lshlrev_b32_e32 v120, 16, v121
	v_and_b32_e32 v121, 0xffff0000, v121
	v_pk_fma_f32 v[136:137], v[120:121], v[120:121], v[136:137]
	v_lshlrev_b32_e32 v148, 16, v114
	v_and_b32_e32 v149, 0xffff0000, v114
	v_pk_fma_f32 v[136:137], v[148:149], v[148:149], v[136:137]
	v_lshlrev_b32_e32 v114, 16, v115
	v_and_b32_e32 v115, 0xffff0000, v115
	v_pk_fma_f32 v[136:137], v[114:115], v[114:115], v[136:137]
	v_lshlrev_b32_e32 v150, 16, v116
	v_and_b32_e32 v151, 0xffff0000, v116
	v_pk_fma_f32 v[136:137], v[150:151], v[150:151], v[136:137]
	v_lshlrev_b32_e32 v116, 16, v117
	v_and_b32_e32 v117, 0xffff0000, v117
	v_pk_fma_f32 v[136:137], v[116:117], v[116:117], v[136:137]
	v_cvt_f32_f16_sdwa v153, v110 dst_sel:DWORD dst_unused:UNUSED_PAD src0_sel:WORD_1
	v_add_f32_e32 v133, v136, v137
	v_mov_b32_e32 v136, 0
	v_cvt_f32_f16_e32 v152, v110
	v_add_f32_dpp v133, v133, v133 quad_perm:[1,0,3,2] row_mask:0xf bank_mask:0xf bound_ctrl:1
	v_cvt_f32_f16_sdwa v155, v111 dst_sel:DWORD dst_unused:UNUSED_PAD src0_sel:WORD_1
	v_cvt_f32_f16_e32 v154, v111
	v_add_f32_dpp v133, v133, v133 quad_perm:[2,3,0,1] row_mask:0xf bank_mask:0xf bound_ctrl:1
	v_pk_mul_f32 v[110:111], v[6:7], v[134:135]
	v_cvt_f32_f16_sdwa v135, v112 dst_sel:DWORD dst_unused:UNUSED_PAD src0_sel:WORD_1
	v_add_f32_dpp v133, v133, v133 row_half_mirror row_mask:0xf bank_mask:0xf bound_ctrl:1
	v_cvt_f32_f16_e32 v134, v112
	v_pk_mul_f32 v[122:123], v[16:17], v[122:123]
	v_add_f32_dpp v133, v133, v133 row_mirror row_mask:0xf bank_mask:0xf bound_ctrl:1
	v_pk_mul_f32 v[124:125], v[12:13], v[124:125]
	v_pk_mul_f32 v[126:127], v[8:9], v[126:127]
	v_mov_b32_dpp v136, v133 row_bcast:15 row_mask:0xa bank_mask:0xf
	v_add_f32_e32 v133, v133, v136
	v_mov_b32_e32 v136, 0
	v_pk_mul_f32 v[118:119], v[24:25], v[118:119]
	v_pk_mul_f32 v[128:129], v[4:5], v[128:129]
	v_mov_b32_dpp v136, v133 row_bcast:31 row_mask:0xc bank_mask:0xf
	v_add_f32_e32 v133, v133, v136
	v_pk_mul_f32 v[120:121], v[20:21], v[120:121]
	v_readlane_b32 s11, v133, 63
	s_nop 1
	v_fma_f32 v133, s11, v132, v1
	v_rsq_f32_e32 v133, v133
	s_nop 0
	v_mul_f32_e32 v136, 0.5, v133
	v_pk_fma_f32 v[110:111], v[110:111], v[136:137], v[152:153] op_sel_hi:[1,0,1]
	v_cvt_f32_f16_sdwa v153, v113 dst_sel:DWORD dst_unused:UNUSED_PAD src0_sel:WORD_1
	v_cvt_f32_f16_e32 v152, v113
	v_pk_mul_f32 v[112:113], v[2:3], v[138:139]
	v_cvt_f32_f16_sdwa v139, v107 dst_sel:DWORD dst_unused:UNUSED_PAD src0_sel:WORD_1
	v_pk_fma_f32 v[112:113], v[112:113], v[136:137], v[134:135] op_sel_hi:[1,0,1]
	v_cvt_f32_f16_sdwa v135, v106 dst_sel:DWORD dst_unused:UNUSED_PAD src0_sel:WORD_1
	v_cvt_f32_f16_e32 v134, v106
	v_cvt_f32_f16_e32 v138, v107
	v_pk_mul_f32 v[106:107], v[14:15], v[140:141]
	v_pk_fma_f32 v[126:127], v[126:127], v[136:137], v[154:155] op_sel_hi:[1,0,1]
	v_pk_fma_f32 v[106:107], v[106:107], v[136:137], v[134:135] op_sel_hi:[1,0,1]
	v_cvt_f32_f16_sdwa v135, v108 dst_sel:DWORD dst_unused:UNUSED_PAD src0_sel:WORD_1
	v_cvt_f32_f16_e32 v134, v108
	v_pk_fma_f32 v[122:123], v[122:123], v[136:137], v[138:139] op_sel_hi:[1,0,1]
	v_cvt_f32_f16_sdwa v139, v109 dst_sel:DWORD dst_unused:UNUSED_PAD src0_sel:WORD_1
	v_cvt_f32_f16_e32 v138, v109
	v_pk_mul_f32 v[108:109], v[10:11], v[142:143]
	v_pk_mul_f32 v[142:143], v[126:127], v[126:127]
	v_pk_fma_f32 v[108:109], v[108:109], v[136:137], v[134:135] op_sel_hi:[1,0,1]
	v_cvt_f32_f16_sdwa v135, v102 dst_sel:DWORD dst_unused:UNUSED_PAD src0_sel:WORD_1
	v_cvt_f32_f16_e32 v134, v102
	v_pk_fma_f32 v[124:125], v[124:125], v[136:137], v[138:139] op_sel_hi:[1,0,1]
	v_cvt_f32_f16_sdwa v139, v103 dst_sel:DWORD dst_unused:UNUSED_PAD src0_sel:WORD_1
	v_cvt_f32_f16_e32 v138, v103
	v_pk_mul_f32 v[102:103], v[22:23], v[144:145]
	v_pk_fma_f32 v[142:143], v[110:111], v[110:111], v[142:143]
	v_pk_fma_f32 v[102:103], v[102:103], v[136:137], v[134:135] op_sel_hi:[1,0,1]
	v_cvt_f32_f16_sdwa v135, v104 dst_sel:DWORD dst_unused:UNUSED_PAD src0_sel:WORD_1
	v_cvt_f32_f16_e32 v134, v104
	v_pk_fma_f32 v[118:119], v[118:119], v[136:137], v[138:139] op_sel_hi:[1,0,1]
	v_cvt_f32_f16_sdwa v139, v105 dst_sel:DWORD dst_unused:UNUSED_PAD src0_sel:WORD_1
	v_cvt_f32_f16_e32 v138, v105
	v_pk_fma_f32 v[128:129], v[128:129], v[136:137], v[152:153] op_sel_hi:[1,0,1]
	v_pk_fma_f32 v[142:143], v[112:113], v[112:113], v[142:143]
	v_pk_mul_f32 v[104:105], v[18:19], v[146:147]
	v_pk_fma_f32 v[142:143], v[128:129], v[128:129], v[142:143]
	v_pk_fma_f32 v[104:105], v[104:105], v[136:137], v[134:135] op_sel_hi:[1,0,1]
	v_cvt_f32_f16_sdwa v135, v98 dst_sel:DWORD dst_unused:UNUSED_PAD src0_sel:WORD_1
	v_cvt_f32_f16_e32 v134, v98
	v_pk_fma_f32 v[142:143], v[106:107], v[106:107], v[142:143]
	v_pk_fma_f32 v[120:121], v[120:121], v[136:137], v[138:139] op_sel_hi:[1,0,1]
	v_cvt_f32_f16_sdwa v139, v99 dst_sel:DWORD dst_unused:UNUSED_PAD src0_sel:WORD_1
	v_cvt_f32_f16_e32 v138, v99
	v_pk_fma_f32 v[142:143], v[122:123], v[122:123], v[142:143]
	v_pk_mul_f32 v[98:99], v[30:31], v[148:149]
	v_pk_fma_f32 v[142:143], v[108:109], v[108:109], v[142:143]
	v_pk_fma_f32 v[134:135], v[98:99], v[136:137], v[134:135] op_sel_hi:[1,0,1]
	v_pk_fma_f32 v[142:143], v[124:125], v[124:125], v[142:143]
	v_pk_mul_f32 v[98:99], v[32:33], v[114:115]
	v_pk_fma_f32 v[142:143], v[102:103], v[102:103], v[142:143]
	v_pk_fma_f32 v[114:115], v[98:99], v[136:137], v[138:139] op_sel_hi:[1,0,1]
	v_cvt_f32_f16_sdwa v99, v100 dst_sel:DWORD dst_unused:UNUSED_PAD src0_sel:WORD_1
	v_cvt_f32_f16_e32 v98, v100
	v_pk_fma_f32 v[142:143], v[118:119], v[118:119], v[142:143]
	v_cvt_f32_f16_sdwa v139, v101 dst_sel:DWORD dst_unused:UNUSED_PAD src0_sel:WORD_1
	v_cvt_f32_f16_e32 v138, v101
	v_pk_fma_f32 v[142:143], v[104:105], v[104:105], v[142:143]
	v_pk_mul_f32 v[100:101], v[26:27], v[150:151]
	v_pk_fma_f32 v[142:143], v[120:121], v[120:121], v[142:143]
	v_pk_fma_f32 v[140:141], v[100:101], v[136:137], v[98:99] op_sel_hi:[1,0,1]
	v_pk_fma_f32 v[142:143], v[134:135], v[134:135], v[142:143]
	v_pk_mul_f32 v[98:99], v[28:29], v[116:117]
	v_pk_fma_f32 v[142:143], v[114:115], v[114:115], v[142:143]
	v_pk_fma_f32 v[116:117], v[98:99], v[136:137], v[138:139] op_sel_hi:[1,0,1]
	v_pk_fma_f32 v[142:143], v[140:141], v[140:141], v[142:143]
	v_lshl_add_u64 v[136:137], s[12:13], 0, v[130:131]
	v_pk_fma_f32 v[142:143], v[116:117], v[116:117], v[142:143]
	v_add_co_u32_e32 v138, vcc, s9, v136
	v_add_f32_e32 v133, v142, v143
	v_mov_b32_e32 v142, 0
	v_cvt_pk_f16_f32 v98, v110, v111
	v_add_f32_dpp v133, v133, v133 quad_perm:[1,0,3,2] row_mask:0xf bank_mask:0xf bound_ctrl:1
	v_cvt_pk_f16_f32 v99, v126, v127
	v_cvt_pk_f16_f32 v100, v112, v113
	v_add_f32_dpp v133, v133, v133 quad_perm:[2,3,0,1] row_mask:0xf bank_mask:0xf bound_ctrl:1
	v_cvt_pk_f16_f32 v101, v128, v129
	v_addc_co_u32_e32 v139, vcc, 0, v137, vcc
	v_add_f32_dpp v133, v133, v133 row_half_mirror row_mask:0xf bank_mask:0xf bound_ctrl:1
	global_store_dwordx4 v[138:139], v[98:101], off offset:1024 sc1
	s_add_u32 s12, s12, s14
	v_add_f32_dpp v133, v133, v133 row_mirror row_mask:0xf bank_mask:0xf bound_ctrl:1
	v_cvt_pk_f16_f32 v98, v106, v107
	v_cvt_pk_f16_f32 v99, v122, v123
	v_mov_b32_dpp v142, v133 row_bcast:15 row_mask:0xa bank_mask:0xf
	v_add_f32_e32 v133, v133, v142
	v_mov_b32_e32 v142, 0
	v_cvt_pk_f16_f32 v100, v108, v109
	v_cvt_pk_f16_f32 v101, v124, v125
	v_mov_b32_dpp v142, v133 row_bcast:31 row_mask:0xc bank_mask:0xf
	v_add_f32_e32 v133, v133, v142
	global_store_dwordx4 v[138:139], v[98:101], off offset:2048 sc1
	v_readlane_b32 s11, v133, 63
	s_addc_u32 s13, s13, s15
	v_cvt_pk_f16_f32 v98, v102, v103
	v_fma_f32 v133, s11, v132, v1
	v_cvt_pk_f16_f32 v99, v118, v119
	v_cvt_pk_f16_f32 v100, v104, v105
	v_cvt_pk_f16_f32 v101, v120, v121
	v_rsq_f32_e32 v142, v133
	global_store_dwordx4 v[138:139], v[98:101], off offset:3072 sc1
	v_add_co_u32_e32 v138, vcc, s22, v136
	s_nop 0
	v_cvt_pk_f16_f32 v98, v134, v135
	v_cvt_pk_f16_f32 v99, v114, v115
	v_cvt_pk_f16_f32 v100, v140, v141
	v_cvt_pk_f16_f32 v101, v116, v117
	v_addc_co_u32_e32 v139, vcc, 0, v137, vcc
	global_store_dwordx4 v[138:139], v[98:101], off sc1
	s_add_u32 s16, s16, s14
	s_addc_u32 s17, s17, s15
	v_pk_mul_f32 v[98:99], v[40:41], v[126:127]
	s_nop 0
	v_pk_mul_f32 v[100:101], v[98:99], v[142:143] op_sel_hi:[1,0]
	v_pk_mul_f32 v[98:99], v[38:39], v[110:111]
	v_pk_mul_f32 v[110:111], v[36:37], v[128:129]
	v_pk_mul_f32 v[98:99], v[98:99], v[142:143] op_sel_hi:[1,0]
	v_pk_mul_f32 v[110:111], v[110:111], v[142:143] op_sel_hi:[1,0]
	v_cvt_pk_bf16_f32 v98, v98, v99
	v_cvt_pk_bf16_f32 v99, v100, v101
	v_pk_mul_f32 v[100:101], v[34:35], v[112:113]
	s_waitcnt vmcnt(9)
	v_mov_b64_e32 v[128:129], v[76:77]
	v_pk_mul_f32 v[100:101], v[100:101], v[142:143] op_sel_hi:[1,0]
	v_mov_b64_e32 v[126:127], v[74:75]
	v_cvt_pk_bf16_f32 v100, v100, v101
	v_cvt_pk_bf16_f32 v101, v110, v111
	v_add_co_u32_e32 v110, vcc, s23, v136
	s_nop 1
	v_addc_co_u32_e32 v111, vcc, 0, v137, vcc
	global_store_dwordx4 v[110:111], v[98:101], off
	s_andn2_b64 vcc, exec, s[20:21]
	s_nop 0
	v_pk_mul_f32 v[98:99], v[46:47], v[106:107]
	v_pk_mul_f32 v[100:101], v[48:49], v[122:123]
	v_pk_mul_f32 v[98:99], v[98:99], v[142:143] op_sel_hi:[1,0]
	v_pk_mul_f32 v[100:101], v[100:101], v[142:143] op_sel_hi:[1,0]
	v_cvt_pk_bf16_f32 v98, v98, v99
	v_pk_mul_f32 v[106:107], v[44:45], v[124:125]
	v_cvt_pk_bf16_f32 v99, v100, v101
	v_pk_mul_f32 v[100:101], v[42:43], v[108:109]
	v_pk_mul_f32 v[106:107], v[106:107], v[142:143] op_sel_hi:[1,0]
	v_pk_mul_f32 v[100:101], v[100:101], v[142:143] op_sel_hi:[1,0]
	s_waitcnt vmcnt(8)
	v_mov_b64_e32 v[124:125], v[84:85]
	v_cvt_pk_bf16_f32 v100, v100, v101
	v_cvt_pk_bf16_f32 v101, v106, v107
	global_store_dwordx4 v[110:111], v[98:101], off offset:1024
	v_mov_b64_e32 v[108:109], v[72:73]
	v_mov_b64_e32 v[122:123], v[82:83]
	v_pk_mul_f32 v[98:99], v[54:55], v[102:103]
	v_pk_mul_f32 v[100:101], v[56:57], v[118:119]
	v_pk_mul_f32 v[98:99], v[98:99], v[142:143] op_sel_hi:[1,0]
	v_pk_mul_f32 v[100:101], v[100:101], v[142:143] op_sel_hi:[1,0]
	v_cvt_pk_bf16_f32 v98, v98, v99
	v_pk_mul_f32 v[102:103], v[52:53], v[120:121]
	v_cvt_pk_bf16_f32 v99, v100, v101
	v_pk_mul_f32 v[100:101], v[50:51], v[104:105]
	v_pk_mul_f32 v[102:103], v[102:103], v[142:143] op_sel_hi:[1,0]
	v_pk_mul_f32 v[100:101], v[100:101], v[142:143] op_sel_hi:[1,0]
	s_waitcnt vmcnt(8)
	v_mov_b64_e32 v[120:121], v[88:89]
	v_cvt_pk_bf16_f32 v100, v100, v101
	v_cvt_pk_bf16_f32 v101, v102, v103
	global_store_dwordx4 v[110:111], v[98:101], off offset:2048
	s_waitcnt vmcnt(8)
	v_pk_mul_f32 v[102:103], v[60:61], v[116:117]
	v_mov_b64_e32 v[118:119], v[86:87]
	s_waitcnt vmcnt(7)
	v_pk_mul_f32 v[98:99], v[62:63], v[134:135]
	v_pk_mul_f32 v[100:101], v[64:65], v[114:115]
	v_pk_mul_f32 v[98:99], v[98:99], v[142:143] op_sel_hi:[1,0]
	v_pk_mul_f32 v[100:101], v[100:101], v[142:143] op_sel_hi:[1,0]
	v_cvt_pk_bf16_f32 v98, v98, v99
	v_pk_mul_f32 v[102:103], v[102:103], v[142:143] op_sel_hi:[1,0]
	v_cvt_pk_bf16_f32 v99, v100, v101
	v_pk_mul_f32 v[100:101], v[58:59], v[140:141]
	v_mov_b64_e32 v[116:117], v[92:93]
	v_pk_mul_f32 v[100:101], v[100:101], v[142:143] op_sel_hi:[1,0]
	v_mov_b64_e32 v[114:115], v[90:91]
	v_cvt_pk_bf16_f32 v100, v100, v101
	v_cvt_pk_bf16_f32 v101, v102, v103
	global_store_dwordx4 v[110:111], v[98:101], off offset:3072
	v_mov_b64_e32 v[112:113], v[68:69]
	v_mov_b64_e32 v[104:105], v[80:81]
	v_mov_b64_e32 v[100:101], v[96:97]
	v_mov_b64_e32 v[110:111], v[66:67]
	v_mov_b64_e32 v[106:107], v[70:71]
	v_mov_b64_e32 v[102:103], v[78:79]
	v_mov_b64_e32 v[98:99], v[94:95]
	s_cbranch_vccz .LBB0_2916

.LBB0_3291:
	v_lshlrev_b32_e32 v140, 16, v126
	v_and_b32_e32 v141, 0xffff0000, v126
	v_lshlrev_b32_e32 v126, 16, v127
	v_and_b32_e32 v127, 0xffff0000, v127
	v_pk_mul_f32 v[142:143], v[126:127], v[126:127]
	v_lshlrev_b32_e32 v144, 16, v128
	v_pk_fma_f32 v[142:143], v[140:141], v[140:141], v[142:143]
	v_and_b32_e32 v145, 0xffff0000, v128
	v_pk_fma_f32 v[142:143], v[144:145], v[144:145], v[142:143]
	v_lshlrev_b32_e32 v128, 16, v129
	v_and_b32_e32 v129, 0xffff0000, v129
	v_pk_fma_f32 v[142:143], v[128:129], v[128:129], v[142:143]
	v_lshlrev_b32_e32 v146, 16, v122
	v_and_b32_e32 v147, 0xffff0000, v122
	v_pk_fma_f32 v[142:143], v[146:147], v[146:147], v[142:143]
	v_lshlrev_b32_e32 v122, 16, v123
	v_and_b32_e32 v123, 0xffff0000, v123
	v_pk_fma_f32 v[142:143], v[122:123], v[122:123], v[142:143]
	v_lshlrev_b32_e32 v148, 16, v124
	v_and_b32_e32 v149, 0xffff0000, v124
	v_pk_fma_f32 v[142:143], v[148:149], v[148:149], v[142:143]
	v_lshlrev_b32_e32 v124, 16, v125
	v_and_b32_e32 v125, 0xffff0000, v125
	v_pk_fma_f32 v[142:143], v[124:125], v[124:125], v[142:143]
	v_lshlrev_b32_e32 v150, 16, v118
	v_and_b32_e32 v151, 0xffff0000, v118
	v_pk_fma_f32 v[142:143], v[150:151], v[150:151], v[142:143]
	v_lshlrev_b32_e32 v118, 16, v119
	v_and_b32_e32 v119, 0xffff0000, v119
	v_pk_fma_f32 v[142:143], v[118:119], v[118:119], v[142:143]
	v_lshlrev_b32_e32 v152, 16, v120
	v_and_b32_e32 v153, 0xffff0000, v120
	v_pk_fma_f32 v[142:143], v[152:153], v[152:153], v[142:143]
	v_lshlrev_b32_e32 v120, 16, v121
	v_and_b32_e32 v121, 0xffff0000, v121
	v_pk_fma_f32 v[142:143], v[120:121], v[120:121], v[142:143]
	v_lshlrev_b32_e32 v154, 16, v114
	v_and_b32_e32 v155, 0xffff0000, v114
	v_pk_fma_f32 v[142:143], v[154:155], v[154:155], v[142:143]
	v_lshlrev_b32_e32 v114, 16, v115
	v_and_b32_e32 v115, 0xffff0000, v115
	v_pk_fma_f32 v[142:143], v[114:115], v[114:115], v[142:143]
	v_lshlrev_b32_e32 v156, 16, v116
	v_and_b32_e32 v157, 0xffff0000, v116
	v_pk_fma_f32 v[142:143], v[156:157], v[156:157], v[142:143]
	v_lshlrev_b32_e32 v116, 16, v117
	v_and_b32_e32 v117, 0xffff0000, v117
	v_pk_fma_f32 v[142:143], v[116:117], v[116:117], v[142:143]
	v_cvt_f32_f16_sdwa v159, v110 dst_sel:DWORD dst_unused:UNUSED_PAD src0_sel:WORD_1
	v_add_f32_e32 v142, v142, v143
	v_mov_b32_e32 v143, 0
	v_cvt_f32_f16_e32 v158, v110
	v_add_f32_dpp v142, v142, v142 quad_perm:[1,0,3,2] row_mask:0xf bank_mask:0xf bound_ctrl:1
	v_cvt_f32_f16_sdwa v161, v111 dst_sel:DWORD dst_unused:UNUSED_PAD src0_sel:WORD_1
	v_cvt_f32_f16_e32 v160, v111
	v_add_f32_dpp v142, v142, v142 quad_perm:[2,3,0,1] row_mask:0xf bank_mask:0xf bound_ctrl:1
	v_pk_mul_f32 v[110:111], v[6:7], v[140:141]
	v_cvt_f32_f16_sdwa v141, v112 dst_sel:DWORD dst_unused:UNUSED_PAD src0_sel:WORD_1
	v_add_f32_dpp v142, v142, v142 row_half_mirror row_mask:0xf bank_mask:0xf bound_ctrl:1
	v_cvt_f32_f16_e32 v140, v112
	v_pk_mul_f32 v[128:129], v[4:5], v[128:129]
	v_add_f32_dpp v142, v142, v142 row_mirror row_mask:0xf bank_mask:0xf bound_ctrl:1
	v_pk_mul_f32 v[122:123], v[16:17], v[122:123]
	v_pk_mul_f32 v[118:119], v[24:25], v[118:119]
	v_mov_b32_dpp v143, v142 row_bcast:15 row_mask:0xa bank_mask:0xf
	v_add_f32_e32 v142, v142, v143
	v_mov_b32_e32 v143, 0
	v_pk_mul_f32 v[126:127], v[8:9], v[126:127]
	s_nop 0
	v_mov_b32_dpp v143, v142 row_bcast:31 row_mask:0xc bank_mask:0xf
	v_add_f32_e32 v142, v142, v143
	s_nop 0
	v_readlane_b32 s4, v142, 63
	s_nop 1
	v_fma_f32 v142, s4, v137, v136
	v_rsq_f32_e32 v142, v142
	s_nop 0
	v_pk_fma_f32 v[110:111], v[110:111], v[142:143], v[158:159] op_sel_hi:[1,0,1]
	v_cvt_f32_f16_sdwa v159, v113 dst_sel:DWORD dst_unused:UNUSED_PAD src0_sel:WORD_1
	v_cvt_f32_f16_e32 v158, v113
	v_pk_mul_f32 v[112:113], v[2:3], v[144:145]
	v_cvt_f32_f16_sdwa v145, v107 dst_sel:DWORD dst_unused:UNUSED_PAD src0_sel:WORD_1
	v_cvt_f32_f16_e32 v144, v107
	v_pk_fma_f32 v[112:113], v[112:113], v[142:143], v[140:141] op_sel_hi:[1,0,1]
	v_pk_fma_f32 v[140:141], v[128:129], v[142:143], v[158:159] op_sel_hi:[1,0,1]
	v_cvt_f32_f16_sdwa v129, v106 dst_sel:DWORD dst_unused:UNUSED_PAD src0_sel:WORD_1
	v_cvt_f32_f16_e32 v128, v106
	v_pk_mul_f32 v[106:107], v[14:15], v[146:147]
	v_pk_fma_f32 v[144:145], v[122:123], v[142:143], v[144:145] op_sel_hi:[1,0,1]
	v_cvt_f32_f16_sdwa v123, v108 dst_sel:DWORD dst_unused:UNUSED_PAD src0_sel:WORD_1
	v_cvt_f32_f16_e32 v122, v108
	v_pk_fma_f32 v[106:107], v[106:107], v[142:143], v[128:129] op_sel_hi:[1,0,1]
	v_cvt_f32_f16_sdwa v129, v109 dst_sel:DWORD dst_unused:UNUSED_PAD src0_sel:WORD_1
	v_cvt_f32_f16_e32 v128, v109
	v_pk_mul_f32 v[108:109], v[10:11], v[148:149]
	v_pk_fma_f32 v[126:127], v[126:127], v[142:143], v[160:161] op_sel_hi:[1,0,1]
	v_pk_fma_f32 v[108:109], v[108:109], v[142:143], v[122:123] op_sel_hi:[1,0,1]
	v_pk_mul_f32 v[122:123], v[12:13], v[124:125]
	v_cvt_f32_f16_sdwa v125, v103 dst_sel:DWORD dst_unused:UNUSED_PAD src0_sel:WORD_1
	v_cvt_f32_f16_e32 v124, v103
	v_pk_fma_f32 v[146:147], v[122:123], v[142:143], v[128:129] op_sel_hi:[1,0,1]
	v_cvt_f32_f16_sdwa v123, v102 dst_sel:DWORD dst_unused:UNUSED_PAD src0_sel:WORD_1
	v_cvt_f32_f16_e32 v122, v102
	v_pk_mul_f32 v[102:103], v[22:23], v[150:151]
	v_pk_fma_f32 v[148:149], v[118:119], v[142:143], v[124:125] op_sel_hi:[1,0,1]
	v_cvt_f32_f16_sdwa v119, v104 dst_sel:DWORD dst_unused:UNUSED_PAD src0_sel:WORD_1
	v_cvt_f32_f16_e32 v118, v104
	v_pk_fma_f32 v[102:103], v[102:103], v[142:143], v[122:123] op_sel_hi:[1,0,1]
	v_cvt_f32_f16_sdwa v123, v105 dst_sel:DWORD dst_unused:UNUSED_PAD src0_sel:WORD_1
	v_cvt_f32_f16_e32 v122, v105
	v_pk_mul_f32 v[104:105], v[18:19], v[152:153]
	s_nop 0
	v_pk_fma_f32 v[104:105], v[104:105], v[142:143], v[118:119] op_sel_hi:[1,0,1]
	v_pk_mul_f32 v[118:119], v[20:21], v[120:121]
	v_cvt_f32_f16_sdwa v121, v99 dst_sel:DWORD dst_unused:UNUSED_PAD src0_sel:WORD_1
	v_pk_fma_f32 v[150:151], v[118:119], v[142:143], v[122:123] op_sel_hi:[1,0,1]
	v_cvt_f32_f16_sdwa v119, v98 dst_sel:DWORD dst_unused:UNUSED_PAD src0_sel:WORD_1
	v_cvt_f32_f16_e32 v118, v98
	v_cvt_f32_f16_e32 v120, v99
	v_pk_mul_f32 v[98:99], v[30:31], v[154:155]
	s_nop 0
	v_pk_fma_f32 v[152:153], v[98:99], v[142:143], v[118:119] op_sel_hi:[1,0,1]
	v_pk_mul_f32 v[98:99], v[32:33], v[114:115]
	v_cvt_f32_f16_sdwa v115, v101 dst_sel:DWORD dst_unused:UNUSED_PAD src0_sel:WORD_1
	v_pk_fma_f32 v[154:155], v[98:99], v[142:143], v[120:121] op_sel_hi:[1,0,1]
	v_cvt_f32_f16_sdwa v99, v100 dst_sel:DWORD dst_unused:UNUSED_PAD src0_sel:WORD_1
	v_cvt_f32_f16_e32 v98, v100
	v_cvt_f32_f16_e32 v114, v101
	v_pk_mul_f32 v[100:101], v[26:27], v[156:157]
	s_nop 0
	v_pk_fma_f32 v[156:157], v[100:101], v[142:143], v[98:99] op_sel_hi:[1,0,1]
	v_pk_mul_f32 v[98:99], v[28:29], v[116:117]
	v_cvt_pk_f16_f32 v100, v112, v113
	v_pk_fma_f32 v[142:143], v[98:99], v[142:143], v[114:115] op_sel_hi:[1,0,1]
	v_lshl_add_u64 v[114:115], s[94:95], 0, v[132:133]
	v_add_co_u32_e32 v116, vcc, s26, v114
	v_cvt_pk_f16_f32 v98, v110, v111
	v_cvt_pk_f16_f32 v99, v126, v127
	v_cvt_pk_f16_f32 v101, v140, v141
	v_addc_co_u32_e32 v117, vcc, 0, v115, vcc
	global_store_dwordx4 v[116:117], v[98:101], off offset:1024 sc1
	v_add_co_u32_e32 v114, vcc, s27, v114
	s_nop 0
	v_cvt_pk_f16_f32 v98, v106, v107
	v_cvt_pk_f16_f32 v99, v144, v145
	v_cvt_pk_f16_f32 v100, v108, v109
	v_cvt_pk_f16_f32 v101, v146, v147
	global_store_dwordx4 v[116:117], v[98:101], off offset:2048 sc1
	v_addc_co_u32_e32 v115, vcc, 0, v115, vcc
	s_nop 0
	v_cvt_pk_f16_f32 v98, v102, v103
	v_cvt_pk_f16_f32 v99, v148, v149
	v_cvt_pk_f16_f32 v100, v104, v105
	v_cvt_pk_f16_f32 v101, v150, v151
	global_store_dwordx4 v[116:117], v[98:101], off offset:3072 sc1
	v_pk_mul_f32 v[116:117], v[126:127], v[126:127]
	s_nop 0
	v_pk_fma_f32 v[116:117], v[110:111], v[110:111], v[116:117]
	v_cvt_pk_f16_f32 v98, v152, v153
	v_pk_fma_f32 v[116:117], v[112:113], v[112:113], v[116:117]
	v_cvt_pk_f16_f32 v99, v154, v155
	v_pk_fma_f32 v[116:117], v[140:141], v[140:141], v[116:117]
	v_cvt_pk_f16_f32 v100, v156, v157
	v_pk_fma_f32 v[116:117], v[106:107], v[106:107], v[116:117]
	v_cvt_pk_f16_f32 v101, v142, v143
	v_pk_fma_f32 v[116:117], v[144:145], v[144:145], v[116:117]
	global_store_dwordx4 v[114:115], v[98:101], off sc1
	v_pk_fma_f32 v[116:117], v[108:109], v[108:109], v[116:117]
	s_nop 0
	v_pk_fma_f32 v[116:117], v[146:147], v[146:147], v[116:117]
	v_pk_mul_f32 v[98:99], v[40:41], v[126:127]
	v_pk_fma_f32 v[116:117], v[102:103], v[102:103], v[116:117]
	s_nop 0
	v_pk_fma_f32 v[116:117], v[148:149], v[148:149], v[116:117]
	s_nop 0
	v_pk_fma_f32 v[116:117], v[104:105], v[104:105], v[116:117]
	s_nop 0
	v_pk_fma_f32 v[116:117], v[150:151], v[150:151], v[116:117]
	s_nop 0
	v_pk_fma_f32 v[116:117], v[152:153], v[152:153], v[116:117]
	s_nop 0
	v_pk_fma_f32 v[116:117], v[154:155], v[154:155], v[116:117]
	s_nop 0
	v_pk_fma_f32 v[116:117], v[156:157], v[156:157], v[116:117]
	s_nop 0
	v_pk_fma_f32 v[116:117], v[142:143], v[142:143], v[116:117]
	s_nop 0
	v_add_f32_e32 v116, v116, v117
	v_mov_b32_e32 v117, 0
	s_nop 0
	v_add_f32_dpp v116, v116, v116 quad_perm:[1,0,3,2] row_mask:0xf bank_mask:0xf bound_ctrl:1
	s_nop 1
	v_add_f32_dpp v116, v116, v116 quad_perm:[2,3,0,1] row_mask:0xf bank_mask:0xf bound_ctrl:1
	s_nop 1
	v_add_f32_dpp v116, v116, v116 row_half_mirror row_mask:0xf bank_mask:0xf bound_ctrl:1
	s_nop 1
	v_add_f32_dpp v116, v116, v116 row_mirror row_mask:0xf bank_mask:0xf bound_ctrl:1
	s_nop 1
	v_mov_b32_dpp v117, v116 row_bcast:15 row_mask:0xa bank_mask:0xf
	v_add_f32_e32 v116, v116, v117
	v_mov_b32_e32 v117, 0
	s_nop 1
	v_mov_b32_dpp v117, v116 row_bcast:31 row_mask:0xc bank_mask:0xf
	v_add_f32_e32 v116, v116, v117
	s_nop 0
	v_readlane_b32 s4, v116, 63
	s_nop 1
	v_fma_f32 v116, s4, v137, v136
	v_rsq_f32_e32 v158, v116
	s_nop 0
	v_pk_mul_f32 v[122:123], v[98:99], v[158:159] op_sel_hi:[1,0]
	v_pk_mul_f32 v[98:99], v[38:39], v[110:111]
	s_nop 0
	v_pk_mul_f32 v[128:129], v[98:99], v[158:159] op_sel_hi:[1,0]
	v_max_f32_e64 v99, |v122|, |v123|
	v_max_f32_e64 v98, |v128|, |v129|
	v_max3_f32 v100, v98, 0, v99
	v_pk_mul_f32 v[98:99], v[34:35], v[112:113]
	s_nop 0
	v_pk_mul_f32 v[124:125], v[98:99], v[158:159] op_sel_hi:[1,0]
	v_pk_mul_f32 v[98:99], v[36:37], v[140:141]
	v_max_f32_e64 v101, |v124|, |v125|
	v_pk_mul_f32 v[126:127], v[98:99], v[158:159] op_sel_hi:[1,0]
	s_nop 0
	v_max_f32_e64 v98, |v126|, |v127|
	v_max3_f32 v100, v100, v101, v98
	v_pk_mul_f32 v[98:99], v[46:47], v[106:107]
	s_nop 0
	v_pk_mul_f32 v[114:115], v[98:99], v[158:159] op_sel_hi:[1,0]
	v_pk_mul_f32 v[98:99], v[48:49], v[144:145]
	v_max_f32_e64 v101, |v114|, |v115|
	v_pk_mul_f32 v[118:119], v[98:99], v[158:159] op_sel_hi:[1,0]
	s_nop 0
	v_max_f32_e64 v98, |v118|, |v119|
	v_max3_f32 v100, v100, v101, v98
	v_pk_mul_f32 v[98:99], v[42:43], v[108:109]
	s_nop 0
	v_pk_mul_f32 v[116:117], v[98:99], v[158:159] op_sel_hi:[1,0]
	v_pk_mul_f32 v[98:99], v[44:45], v[146:147]
	v_max_f32_e64 v101, |v116|, |v117|
	v_pk_mul_f32 v[120:121], v[98:99], v[158:159] op_sel_hi:[1,0]
	s_nop 0
	v_max_f32_e64 v98, |v120|, |v121|
	v_max3_f32 v100, v100, v101, v98
	v_pk_mul_f32 v[98:99], v[54:55], v[102:103]
	s_nop 0
	v_pk_mul_f32 v[106:107], v[98:99], v[158:159] op_sel_hi:[1,0]
	v_pk_mul_f32 v[98:99], v[56:57], v[148:149]
	v_max_f32_e64 v101, |v106|, |v107|
	v_pk_mul_f32 v[110:111], v[98:99], v[158:159] op_sel_hi:[1,0]
	s_nop 0
	v_max_f32_e64 v98, |v110|, |v111|
	v_max3_f32 v100, v100, v101, v98
	v_pk_mul_f32 v[98:99], v[50:51], v[104:105]
	s_nop 0
	v_pk_mul_f32 v[108:109], v[98:99], v[158:159] op_sel_hi:[1,0]
	v_pk_mul_f32 v[98:99], v[52:53], v[150:151]
	v_max_f32_e64 v101, |v108|, |v109|
	v_pk_mul_f32 v[112:113], v[98:99], v[158:159] op_sel_hi:[1,0]
	s_nop 0
	v_max_f32_e64 v98, |v112|, |v113|
	v_max3_f32 v104, v100, v101, v98
	s_waitcnt vmcnt(4)
	v_pk_mul_f32 v[98:99], v[62:63], v[152:153]
	v_pk_mul_f32 v[100:101], v[64:65], v[154:155]
	v_pk_mul_f32 v[98:99], v[98:99], v[158:159] op_sel_hi:[1,0]
	v_pk_mul_f32 v[102:103], v[100:101], v[158:159] op_sel_hi:[1,0]
	v_max_f32_e64 v105, |v98|, |v99|
	v_max_f32_e64 v100, |v102|, |v103|
	v_max3_f32 v140, v104, v105, v100
	v_pk_mul_f32 v[100:101], v[58:59], v[156:157]
	v_pk_mul_f32 v[104:105], v[60:61], v[142:143]
	v_pk_mul_f32 v[100:101], v[100:101], v[158:159] op_sel_hi:[1,0]
	v_pk_mul_f32 v[104:105], v[104:105], v[158:159] op_sel_hi:[1,0]
	v_max_f32_e64 v141, |v100|, |v101|
	v_max_f32_e64 v142, |v104|, |v105|
	v_max3_f32 v140, v140, v141, v142
	v_mov_b32_e32 v141, 0
	s_nop 1
	v_mov_b32_dpp v141, v140 quad_perm:[1,0,3,2] row_mask:0xf bank_mask:0xf
	v_max_f32_e32 v141, v141, v141
	v_max_f32_e32 v140, v140, v141
	v_mov_b32_e32 v141, 0
	s_nop 1
	v_mov_b32_dpp v141, v140 quad_perm:[2,3,0,1] row_mask:0xf bank_mask:0xf
	v_max_f32_e32 v141, v141, v141
	v_max_f32_e32 v140, v140, v141
	v_mov_b32_e32 v141, 0
	s_nop 1
	v_mov_b32_dpp v141, v140 row_half_mirror row_mask:0xf bank_mask:0xf
	v_max_f32_e32 v141, v141, v141
	v_max_f32_e32 v140, v140, v141
	v_mov_b32_e32 v141, 0
	s_nop 1
	v_mov_b32_dpp v141, v140 row_mirror row_mask:0xf bank_mask:0xf
	v_max_f32_e32 v141, v141, v141
	v_max_f32_e32 v140, v140, v141
	v_mov_b32_e32 v141, 0
	s_nop 1
	v_mov_b32_dpp v141, v140 row_bcast:15 row_mask:0xa bank_mask:0xf
	v_max_f32_e32 v141, v141, v141
	v_max_f32_e32 v140, v140, v141
	v_mov_b32_e32 v141, 0
	s_nop 1
	v_mov_b32_dpp v141, v140 row_bcast:31 row_mask:0xc bank_mask:0xf
	v_max_f32_e32 v141, v141, v141
	v_max_f32_e32 v140, v140, v141
	s_nop 0
	v_readlane_b32 s15, v140, 63
	s_nop 1
	v_cmp_gt_f32_e64 s[4:5], s15, 0
	s_and_saveexec_b64 s[24:25], s[0:1]
	s_cbranch_execz .LBB0_3288
	v_mul_f32_e32 v140, s15, v138
	s_add_u32 s36, s94, s13
	v_cndmask_b32_e64 v140, 1.0, v140, s[4:5]
	s_addc_u32 s37, s95, s35
	global_store_dword v1, v140, s[36:37]
	s_branch .LBB0_3288
